# GEMM MFMA blocks: instruction order within each 8-MFMA k-step changed so consecutive MFMAs share an operand (plus earlier wait cleanup edits)
# baseline (speedup 1.0000x reference)
; #define PG8_STAGE(bufoff, gbase, voff) do { _Pragma("unroll") for (int _i = 0; _i < 2; ++_i) { unsigned keep_; \
;         asm volatile("s_mov_b32 %0, m0\n\ts_mov_b32 m0, %3\n\ts_nop 0\n\tglobal_load_lds_dwordx4 %1, %2\n\ts_mov_b32 m0, %0" \
;             : "=&s"(keep_) : "v"((voff)[_i]), "s"((const void*)(gbase)), "s"(ldsb0 + (unsigned)(bufoff) + (unsigned)(_i * 8192)) : "memory"); } } while (0)
; #define PG8_LDA(dst, b, h) do { _Pragma("unroll") for (int m = 0; m < 4; ++m) _Pragma("unroll") for (int k = 0; k < 2; ++k) dst[m][k] = *(const LAS bf16x8*)(lds + PG8_SA(b, h) + aoff + m * 2048 + k * 1024); } while (0)
; #define PG8_LDB(dst, b, h) do { _Pragma("unroll") for (int n = 0; n < 2; ++n) _Pragma("unroll") for (int k = 0; k < 2; ++k) dst[n][k] = *(const LAS bf16x8*)(lds + PG8_SB(b, h) + boff + n * 2048 + k * 1024); } while (0)
; #define PG8_MMA(ai, bj, At, Bt) do { __builtin_amdgcn_s_setprio(1); _Pragma("unroll") for (int m = 0; m < 4; ++m) _Pragma("unroll") for (int n = 0; n < 2; ++n) _Pragma("unroll") for (int k = 0; k < 2; ++k) \
;         acc[ai][bj][m][n] = __builtin_amdgcn_mfma_f32_16x16x32_bf16(Bt[n][k], At[m][k], acc[ai][bj][m][n], 0, 0, 0); __builtin_amdgcn_s_setprio(0); } while (0)
; #define PG8_WAIT_V(n) asm volatile("s_waitcnt vmcnt(" #n ")" ::: "memory")
; #define PG8_WAIT_L(n) asm volatile("s_waitcnt lgkmcnt(" #n ")" ::: "memory")
; template <class Epi, class Sched, bool ALIGN_EPI>
; __device__ __forceinline__ void gemm_phase(LAS unsigned char* lds, const Gemm g, const Sched& S, const Epi& E) {
;     ...
;             const bool last = (t == nt - 2);
;             const char* a1 = cA + (size_t)(t + 1) * kstep;
;             const char* a2 = last ? nA : cA + (size_t)(t + 2) * kstep; const char* b2 = last ? nB : cB + (size_t)(t + 2) * kstep;
;             const char* a3 = a2 + kstep; const char* b3 = b2 + kstep;
;             PG8_LDB(B0, 0, 0); PG8_LDB(B1, 0, 1); PG8_SCHED; PG8_LDA(At, 0, 0); PG8_STAGE(PG8_SA(1, 1), a1 + hstepA, voffA);
;             PG8_WAIT_V(8); PG8_WAIT_L(0); PG8_BAR; PG8_MMA(0, 0, At, B0); PG8_MMA(0, 1, At, B1); PG8_BAR; PG8_SCHED;
;             PG8_LDA(At, 0, 1); PG8_STAGE(PG8_SB(0, 0), b2, voffB); PG8_STAGE(PG8_SB(0, 1), b2 + hstepB, voffB); PG8_STAGE(PG8_SA(0, 0), a2, voffA);
;             PG8_WAIT_V(8); PG8_WAIT_L(0); PG8_BAR; PG8_MMA(1, 0, At, B0); PG8_MMA(1, 1, At, B1); PG8_BAR; PG8_SCHED;
.LBB0_113:
	ds_read_b128 v[136:139], v157
	ds_read_b128 v[140:143], v157 offset:1024
	ds_read_b128 v[144:147], v157 offset:2048
	ds_read_b128 v[172:175], v157 offset:3072
	ds_read_b128 v[180:183], v158
	ds_read_b128 v[184:187], v158 offset:1024
	ds_read_b128 v[188:191], v158 offset:2048
	ds_read_b128 v[192:195], v158 offset:3072
	s_add_u32 s6, s4, 0x100
	s_addc_u32 s7, s5, 0
	s_cmp_eq_u32 s81, 28
	s_cselect_b32 s50, s39, s6
	s_cselect_b32 s51, s24, s7
	s_cselect_b32 s48, s58, s59
	s_cselect_b32 s49, s41, s80
	s_add_u32 s8, s50, 0x80
	s_addc_u32 s9, s51, 0
	ds_read_b128 v[196:199], v159
	ds_read_b128 v[206:209], v159 offset:1024
	ds_read_b128 v[210:213], v159 offset:2048
	ds_read_b128 v[214:217], v159 offset:3072
	ds_read_b128 v[218:221], v159 offset:4096
	ds_read_b128 v[222:225], v159 offset:5120
	ds_read_b128 v[226:229], v159 offset:6144
	ds_read_b128 v[230:233], v159 offset:7168
	s_add_u32 s4, s4, 0x80080
	s_addc_u32 s5, s5, 0
	s_mov_b32 m0, s75
	s_nop 0
	global_load_lds_dwordx4 v151, s[4:5]
	s_nop 0
	s_mov_b32 m0, s77
	s_nop 0
	global_load_lds_dwordx4 v153, s[4:5]
	s_waitcnt vmcnt(8)
	s_waitcnt lgkmcnt(0)
	s_barrier
	s_setprio 1
	v_mfma_f32_16x16x32_bf16 v[126:129], v[136:139], v[196:199], v[126:129]
	v_mfma_f32_16x16x32_bf16 v[110:113], v[136:139], v[210:213], v[110:113]
	v_mfma_f32_16x16x32_bf16 v[94:97], v[136:139], v[218:221], v[94:97]
	v_mfma_f32_16x16x32_bf16 v[78:81], v[136:139], v[226:229], v[78:81]
	v_mfma_f32_16x16x32_bf16 v[74:77], v[144:147], v[226:229], v[74:77]
	v_mfma_f32_16x16x32_bf16 v[90:93], v[144:147], v[218:221], v[90:93]
	v_mfma_f32_16x16x32_bf16 v[106:109], v[144:147], v[210:213], v[106:109]
	v_mfma_f32_16x16x32_bf16 v[122:125], v[144:147], v[196:199], v[122:125]
	v_mfma_f32_16x16x32_bf16 v[122:125], v[172:175], v[206:209], v[122:125]
	v_mfma_f32_16x16x32_bf16 v[106:109], v[172:175], v[214:217], v[106:109]
	v_mfma_f32_16x16x32_bf16 v[90:93], v[172:175], v[222:225], v[90:93]
	v_mfma_f32_16x16x32_bf16 v[74:77], v[172:175], v[230:233], v[74:77]
	v_mfma_f32_16x16x32_bf16 v[78:81], v[140:143], v[230:233], v[78:81]
	v_mfma_f32_16x16x32_bf16 v[94:97], v[140:143], v[222:225], v[94:97]
	v_mfma_f32_16x16x32_bf16 v[110:113], v[140:143], v[214:217], v[110:113]
	v_mfma_f32_16x16x32_bf16 v[126:129], v[140:143], v[206:209], v[126:129]
	v_mfma_f32_16x16x32_bf16 v[118:121], v[180:183], v[196:199], v[118:121]
	v_mfma_f32_16x16x32_bf16 v[102:105], v[180:183], v[210:213], v[102:105]
	v_mfma_f32_16x16x32_bf16 v[86:89], v[180:183], v[218:221], v[86:89]
	v_mfma_f32_16x16x32_bf16 v[70:73], v[180:183], v[226:229], v[70:73]
	v_mfma_f32_16x16x32_bf16 v[66:69], v[188:191], v[226:229], v[66:69]
	v_mfma_f32_16x16x32_bf16 v[82:85], v[188:191], v[218:221], v[82:85]
	v_mfma_f32_16x16x32_bf16 v[98:101], v[188:191], v[210:213], v[98:101]
	v_mfma_f32_16x16x32_bf16 v[114:117], v[188:191], v[196:199], v[114:117]
	v_mfma_f32_16x16x32_bf16 v[114:117], v[192:195], v[206:209], v[114:117]
	v_mfma_f32_16x16x32_bf16 v[98:101], v[192:195], v[214:217], v[98:101]
	v_mfma_f32_16x16x32_bf16 v[82:85], v[192:195], v[222:225], v[82:85]
	v_mfma_f32_16x16x32_bf16 v[66:69], v[192:195], v[230:233], v[66:69]
	v_mfma_f32_16x16x32_bf16 v[70:73], v[184:187], v[230:233], v[70:73]
	v_mfma_f32_16x16x32_bf16 v[86:89], v[184:187], v[222:225], v[86:89]
	v_mfma_f32_16x16x32_bf16 v[102:105], v[184:187], v[214:217], v[102:105]
	v_mfma_f32_16x16x32_bf16 v[118:121], v[184:187], v[206:209], v[118:121]
	s_setprio 0
	s_barrier
	ds_read_b128 v[196:199], v159 offset:16384
	ds_read_b128 v[206:209], v159 offset:17408
	ds_read_b128 v[210:213], v159 offset:18432
	ds_read_b128 v[214:217], v159 offset:19456
	ds_read_b128 v[218:221], v159 offset:20480
	ds_read_b128 v[222:225], v159 offset:21504
	ds_read_b128 v[226:229], v159 offset:22528
	ds_read_b128 v[230:233], v159 offset:23552
	s_mov_b32 m0, s23
	s_nop 0
	global_load_lds_dwordx4 v152, s[48:49]
	s_nop 0
	s_mov_b32 m0, s62
	s_nop 0
	global_load_lds_dwordx4 v154, s[48:49]
	s_add_u32 s4, s48, 0x80000
	s_addc_u32 s5, s49, 0
	s_mov_b32 m0, s63
	s_nop 0
	global_load_lds_dwordx4 v152, s[4:5]
	s_nop 0
	s_mov_b32 m0, s64
	s_nop 0
	global_load_lds_dwordx4 v154, s[4:5]
	s_mov_b32 m0, s61
	s_nop 0
	global_load_lds_dwordx4 v151, s[50:51]
	s_nop 0
	s_mov_b32 m0, s65
	s_nop 0
	global_load_lds_dwordx4 v153, s[50:51]
	s_waitcnt vmcnt(8)
	s_waitcnt lgkmcnt(0)
	s_barrier
	s_setprio 1
	v_mfma_f32_16x16x32_bf16 v[62:65], v[136:139], v[196:199], v[62:65]
	v_mfma_f32_16x16x32_bf16 v[46:49], v[136:139], v[210:213], v[46:49]
	v_mfma_f32_16x16x32_bf16 v[30:33], v[136:139], v[218:221], v[30:33]
	v_mfma_f32_16x16x32_bf16 v[14:17], v[136:139], v[226:229], v[14:17]
	v_mfma_f32_16x16x32_bf16 v[10:13], v[144:147], v[226:229], v[10:13]
	v_mfma_f32_16x16x32_bf16 v[26:29], v[144:147], v[218:221], v[26:29]
	v_mfma_f32_16x16x32_bf16 v[42:45], v[144:147], v[210:213], v[42:45]
	v_mfma_f32_16x16x32_bf16 v[58:61], v[144:147], v[196:199], v[58:61]
	v_mfma_f32_16x16x32_bf16 v[58:61], v[172:175], v[206:209], v[58:61]
	v_mfma_f32_16x16x32_bf16 v[42:45], v[172:175], v[214:217], v[42:45]
	v_mfma_f32_16x16x32_bf16 v[26:29], v[172:175], v[222:225], v[26:29]
	v_mfma_f32_16x16x32_bf16 v[10:13], v[172:175], v[230:233], v[10:13]
	v_mfma_f32_16x16x32_bf16 v[14:17], v[140:143], v[230:233], v[14:17]
	v_mfma_f32_16x16x32_bf16 v[30:33], v[140:143], v[222:225], v[30:33]
	v_mfma_f32_16x16x32_bf16 v[46:49], v[140:143], v[214:217], v[46:49]
	v_mfma_f32_16x16x32_bf16 v[62:65], v[140:143], v[206:209], v[62:65]
	v_mfma_f32_16x16x32_bf16 v[54:57], v[180:183], v[196:199], v[54:57]
	v_mfma_f32_16x16x32_bf16 v[38:41], v[180:183], v[210:213], v[38:41]
	v_mfma_f32_16x16x32_bf16 v[22:25], v[180:183], v[218:221], v[22:25]
	v_mfma_f32_16x16x32_bf16 v[6:9], v[180:183], v[226:229], v[6:9]
	v_mfma_f32_16x16x32_bf16 v[2:5], v[188:191], v[226:229], v[2:5]
	v_mfma_f32_16x16x32_bf16 v[18:21], v[188:191], v[218:221], v[18:21]
	v_mfma_f32_16x16x32_bf16 v[34:37], v[188:191], v[210:213], v[34:37]
	v_mfma_f32_16x16x32_bf16 v[50:53], v[188:191], v[196:199], v[50:53]
	v_mfma_f32_16x16x32_bf16 v[50:53], v[192:195], v[206:209], v[50:53]
	v_mfma_f32_16x16x32_bf16 v[34:37], v[192:195], v[214:217], v[34:37]
	v_mfma_f32_16x16x32_bf16 v[18:21], v[192:195], v[222:225], v[18:21]
	v_mfma_f32_16x16x32_bf16 v[2:5], v[192:195], v[230:233], v[2:5]
	v_mfma_f32_16x16x32_bf16 v[6:9], v[184:187], v[230:233], v[6:9]
	v_mfma_f32_16x16x32_bf16 v[22:25], v[184:187], v[222:225], v[22:25]
	v_mfma_f32_16x16x32_bf16 v[38:41], v[184:187], v[214:217], v[38:41]
	v_mfma_f32_16x16x32_bf16 v[54:57], v[184:187], v[206:209], v[54:57]
	s_setprio 0
	s_barrier
; #define PG8_STAGE(bufoff, gbase, voff) do { _Pragma("unroll") for (int _i = 0; _i < 2; ++_i) { unsigned keep_; \
;         asm volatile("s_mov_b32 %0, m0\n\ts_mov_b32 m0, %3\n\ts_nop 0\n\tglobal_load_lds_dwordx4 %1, %2\n\ts_mov_b32 m0, %0" \
;             : "=&s"(keep_) : "v"((voff)[_i]), "s"((const void*)(gbase)), "s"(ldsb0 + (unsigned)(bufoff) + (unsigned)(_i * 8192)) : "memory"); } } while (0)
; #define PG8_LDA(dst, b, h) do { _Pragma("unroll") for (int m = 0; m < 4; ++m) _Pragma("unroll") for (int k = 0; k < 2; ++k) dst[m][k] = *(const LAS bf16x8*)(lds + PG8_SA(b, h) + aoff + m * 2048 + k * 1024); } while (0)
; #define PG8_LDB(dst, b, h) do { _Pragma("unroll") for (int n = 0; n < 2; ++n) _Pragma("unroll") for (int k = 0; k < 2; ++k) dst[n][k] = *(const LAS bf16x8*)(lds + PG8_SB(b, h) + boff + n * 2048 + k * 1024); } while (0)
; #define PG8_MMA(ai, bj, At, Bt) do { __builtin_amdgcn_s_setprio(1); _Pragma("unroll") for (int m = 0; m < 4; ++m) _Pragma("unroll") for (int n = 0; n < 2; ++n) _Pragma("unroll") for (int k = 0; k < 2; ++k) \
;         acc[ai][bj][m][n] = __builtin_amdgcn_mfma_f32_16x16x32_bf16(Bt[n][k], At[m][k], acc[ai][bj][m][n], 0, 0, 0); __builtin_amdgcn_s_setprio(0); } while (0)
; #define PG8_WAIT_V(n) asm volatile("s_waitcnt vmcnt(" #n ")" ::: "memory")
; #define PG8_WAIT_L(n) asm volatile("s_waitcnt lgkmcnt(" #n ")" ::: "memory")
; #define PG8_BAR __builtin_amdgcn_s_barrier()
; #define PG8_SCHED __builtin_amdgcn_sched_barrier(0)
; template <class Epi, class Sched, bool ALIGN_EPI>
; __device__ __forceinline__ void gemm_phase(LAS unsigned char* lds, const Gemm g, const Sched& S, const Epi& E) {
;     ...
;             PG8_LDB(B0, 1, 0); PG8_LDB(B1, 1, 1); PG8_SCHED; PG8_LDA(At, 1, 0); PG8_STAGE(PG8_SA(0, 1), a2 + hstepA, voffA);
;             PG8_WAIT_V(8); PG8_WAIT_L(0); PG8_BAR; PG8_MMA(0, 0, At, B0); PG8_MMA(0, 1, At, B1); PG8_BAR; PG8_SCHED;
;             PG8_LDA(At, 1, 1); PG8_STAGE(PG8_SB(1, 0), b3, voffB); PG8_STAGE(PG8_SB(1, 1), b3 + hstepB, voffB); PG8_STAGE(PG8_SA(1, 0), a3, voffA);
;             PG8_WAIT_V(8); PG8_WAIT_L(0); PG8_BAR; PG8_MMA(1, 0, At, B0); PG8_MMA(1, 1, At, B1); PG8_BAR; PG8_SCHED;
;         }
	ds_read_b128 v[136:139], v160
	ds_read_b128 v[140:143], v160 offset:1024
	ds_read_b128 v[144:147], v160 offset:2048
	ds_read_b128 v[172:175], v160 offset:3072
	ds_read_b128 v[180:183], v161
	ds_read_b128 v[184:187], v161 offset:1024
	ds_read_b128 v[188:191], v161 offset:2048
	ds_read_b128 v[192:195], v161 offset:3072
	ds_read_b128 v[196:199], v159 offset:32768
	ds_read_b128 v[206:209], v159 offset:33792
	ds_read_b128 v[210:213], v159 offset:34816
	ds_read_b128 v[214:217], v159 offset:35840
	ds_read_b128 v[218:221], v159 offset:36864
	ds_read_b128 v[222:225], v159 offset:37888
	ds_read_b128 v[226:229], v159 offset:38912
	ds_read_b128 v[230:233], v159 offset:39936
	s_add_u32 s4, s50, 0x80000
	s_addc_u32 s5, s51, 0
	s_mov_b32 m0, s66
	s_nop 0
	global_load_lds_dwordx4 v151, s[4:5]
	s_nop 0
	s_mov_b32 m0, s67
	s_nop 0
	global_load_lds_dwordx4 v153, s[4:5]
	s_waitcnt vmcnt(8)
	s_waitcnt lgkmcnt(0)
	s_barrier
	s_setprio 1
	v_mfma_f32_16x16x32_bf16 v[126:129], v[136:139], v[196:199], v[126:129]
	v_mfma_f32_16x16x32_bf16 v[110:113], v[136:139], v[210:213], v[110:113]
	v_mfma_f32_16x16x32_bf16 v[94:97], v[136:139], v[218:221], v[94:97]
	v_mfma_f32_16x16x32_bf16 v[78:81], v[136:139], v[226:229], v[78:81]
	v_mfma_f32_16x16x32_bf16 v[74:77], v[144:147], v[226:229], v[74:77]
	v_mfma_f32_16x16x32_bf16 v[90:93], v[144:147], v[218:221], v[90:93]
	v_mfma_f32_16x16x32_bf16 v[106:109], v[144:147], v[210:213], v[106:109]
	v_mfma_f32_16x16x32_bf16 v[122:125], v[144:147], v[196:199], v[122:125]
	v_mfma_f32_16x16x32_bf16 v[122:125], v[172:175], v[206:209], v[122:125]
	v_mfma_f32_16x16x32_bf16 v[106:109], v[172:175], v[214:217], v[106:109]
	v_mfma_f32_16x16x32_bf16 v[90:93], v[172:175], v[222:225], v[90:93]
	v_mfma_f32_16x16x32_bf16 v[74:77], v[172:175], v[230:233], v[74:77]
	v_mfma_f32_16x16x32_bf16 v[78:81], v[140:143], v[230:233], v[78:81]
	v_mfma_f32_16x16x32_bf16 v[94:97], v[140:143], v[222:225], v[94:97]
	v_mfma_f32_16x16x32_bf16 v[110:113], v[140:143], v[214:217], v[110:113]
	v_mfma_f32_16x16x32_bf16 v[126:129], v[140:143], v[206:209], v[126:129]
	v_mfma_f32_16x16x32_bf16 v[118:121], v[180:183], v[196:199], v[118:121]
	v_mfma_f32_16x16x32_bf16 v[102:105], v[180:183], v[210:213], v[102:105]
	v_mfma_f32_16x16x32_bf16 v[86:89], v[180:183], v[218:221], v[86:89]
	v_mfma_f32_16x16x32_bf16 v[70:73], v[180:183], v[226:229], v[70:73]
	v_mfma_f32_16x16x32_bf16 v[66:69], v[188:191], v[226:229], v[66:69]
	v_mfma_f32_16x16x32_bf16 v[82:85], v[188:191], v[218:221], v[82:85]
	v_mfma_f32_16x16x32_bf16 v[98:101], v[188:191], v[210:213], v[98:101]
	v_mfma_f32_16x16x32_bf16 v[114:117], v[188:191], v[196:199], v[114:117]
	v_mfma_f32_16x16x32_bf16 v[114:117], v[192:195], v[206:209], v[114:117]
	v_mfma_f32_16x16x32_bf16 v[98:101], v[192:195], v[214:217], v[98:101]
	v_mfma_f32_16x16x32_bf16 v[82:85], v[192:195], v[222:225], v[82:85]
	v_mfma_f32_16x16x32_bf16 v[66:69], v[192:195], v[230:233], v[66:69]
	v_mfma_f32_16x16x32_bf16 v[70:73], v[184:187], v[230:233], v[70:73]
	v_mfma_f32_16x16x32_bf16 v[86:89], v[184:187], v[222:225], v[86:89]
	v_mfma_f32_16x16x32_bf16 v[102:105], v[184:187], v[214:217], v[102:105]
	v_mfma_f32_16x16x32_bf16 v[118:121], v[184:187], v[206:209], v[118:121]
	s_setprio 0
	s_barrier
	ds_read_b128 v[196:199], v159 offset:49152
	ds_read_b128 v[206:209], v159 offset:50176
	ds_read_b128 v[210:213], v159 offset:51200
	ds_read_b128 v[214:217], v159 offset:52224
	ds_read_b128 v[218:221], v159 offset:53248
	ds_read_b128 v[222:225], v159 offset:54272
	ds_read_b128 v[226:229], v159 offset:55296
	ds_read_b128 v[230:233], v159 offset:56320
	s_add_u32 s4, s48, 0x80
	s_addc_u32 s5, s49, 0
	s_mov_b32 m0, s69
	s_nop 0
	global_load_lds_dwordx4 v152, s[4:5]
	s_nop 0
	s_mov_b32 m0, s70
	s_nop 0
	global_load_lds_dwordx4 v154, s[4:5]
	s_add_u32 s4, s48, 0x80080
	s_addc_u32 s5, s49, 0
	s_mov_b32 m0, s73
	s_nop 0
	global_load_lds_dwordx4 v152, s[4:5]
	s_nop 0
	s_mov_b32 m0, s74
	s_nop 0
	global_load_lds_dwordx4 v154, s[4:5]
	s_mov_b32 m0, s71
	s_nop 0
	global_load_lds_dwordx4 v151, s[8:9]
	s_nop 0
	s_mov_b32 m0, s72
	s_nop 0
	global_load_lds_dwordx4 v153, s[8:9]
	s_waitcnt vmcnt(8)
	s_waitcnt lgkmcnt(0)
	s_barrier
	s_setprio 1
	v_mfma_f32_16x16x32_bf16 v[62:65], v[136:139], v[196:199], v[62:65]
	v_mfma_f32_16x16x32_bf16 v[46:49], v[136:139], v[210:213], v[46:49]
	v_mfma_f32_16x16x32_bf16 v[30:33], v[136:139], v[218:221], v[30:33]
	v_mfma_f32_16x16x32_bf16 v[14:17], v[136:139], v[226:229], v[14:17]
	v_mfma_f32_16x16x32_bf16 v[10:13], v[144:147], v[226:229], v[10:13]
	v_mfma_f32_16x16x32_bf16 v[26:29], v[144:147], v[218:221], v[26:29]
	v_mfma_f32_16x16x32_bf16 v[42:45], v[144:147], v[210:213], v[42:45]
	v_mfma_f32_16x16x32_bf16 v[58:61], v[144:147], v[196:199], v[58:61]
	v_mfma_f32_16x16x32_bf16 v[58:61], v[172:175], v[206:209], v[58:61]
	v_mfma_f32_16x16x32_bf16 v[42:45], v[172:175], v[214:217], v[42:45]
	v_mfma_f32_16x16x32_bf16 v[26:29], v[172:175], v[222:225], v[26:29]
	v_mfma_f32_16x16x32_bf16 v[10:13], v[172:175], v[230:233], v[10:13]
	v_mfma_f32_16x16x32_bf16 v[14:17], v[140:143], v[230:233], v[14:17]
	v_mfma_f32_16x16x32_bf16 v[30:33], v[140:143], v[222:225], v[30:33]
	v_mfma_f32_16x16x32_bf16 v[46:49], v[140:143], v[214:217], v[46:49]
	v_mfma_f32_16x16x32_bf16 v[62:65], v[140:143], v[206:209], v[62:65]
	v_mfma_f32_16x16x32_bf16 v[54:57], v[180:183], v[196:199], v[54:57]
	v_mfma_f32_16x16x32_bf16 v[38:41], v[180:183], v[210:213], v[38:41]
	v_mfma_f32_16x16x32_bf16 v[22:25], v[180:183], v[218:221], v[22:25]
	v_mfma_f32_16x16x32_bf16 v[6:9], v[180:183], v[226:229], v[6:9]
	v_mfma_f32_16x16x32_bf16 v[2:5], v[188:191], v[226:229], v[2:5]
	v_mfma_f32_16x16x32_bf16 v[18:21], v[188:191], v[218:221], v[18:21]
	v_mfma_f32_16x16x32_bf16 v[34:37], v[188:191], v[210:213], v[34:37]
	v_mfma_f32_16x16x32_bf16 v[50:53], v[188:191], v[196:199], v[50:53]
	v_mfma_f32_16x16x32_bf16 v[50:53], v[192:195], v[206:209], v[50:53]
	v_mfma_f32_16x16x32_bf16 v[34:37], v[192:195], v[214:217], v[34:37]
	v_mfma_f32_16x16x32_bf16 v[18:21], v[192:195], v[222:225], v[18:21]
	v_mfma_f32_16x16x32_bf16 v[2:5], v[192:195], v[230:233], v[2:5]
	v_mfma_f32_16x16x32_bf16 v[6:9], v[184:187], v[230:233], v[6:9]
	v_mfma_f32_16x16x32_bf16 v[22:25], v[184:187], v[222:225], v[22:25]
	v_mfma_f32_16x16x32_bf16 v[38:41], v[184:187], v[214:217], v[38:41]
	v_mfma_f32_16x16x32_bf16 v[54:57], v[184:187], v[206:209], v[54:57]
	s_setprio 0
	s_barrier
	s_add_i32 s81, s81, 2
	s_add_u32 s59, s59, 0x100
	s_addc_u32 s80, s80, 0
	s_cmp_gt_u32 s81, 29
	s_mov_b64 s[4:5], s[6:7]
	s_cbranch_scc0 .LBB0_113
	s_and_b64 vcc, exec, s[36:37]
	s_cbranch_vccz .LBB0_116
	s_barrier

; #define PG8_STAGE(bufoff, gbase, voff) do { _Pragma("unroll") for (int _i = 0; _i < 2; ++_i) { unsigned keep_; \
;         asm volatile("s_mov_b32 %0, m0\n\ts_mov_b32 m0, %3\n\ts_nop 0\n\tglobal_load_lds_dwordx4 %1, %2\n\ts_mov_b32 m0, %0" \
;             : "=&s"(keep_) : "v"((voff)[_i]), "s"((const void*)(gbase)), "s"(ldsb0 + (unsigned)(bufoff) + (unsigned)(_i * 8192)) : "memory"); } } while (0)
; #define PG8_LDA(dst, b, h) do { _Pragma("unroll") for (int m = 0; m < 4; ++m) _Pragma("unroll") for (int k = 0; k < 2; ++k) dst[m][k] = *(const LAS bf16x8*)(lds + PG8_SA(b, h) + aoff + m * 2048 + k * 1024); } while (0)
; #define PG8_LDB(dst, b, h) do { _Pragma("unroll") for (int n = 0; n < 2; ++n) _Pragma("unroll") for (int k = 0; k < 2; ++k) dst[n][k] = *(const LAS bf16x8*)(lds + PG8_SB(b, h) + boff + n * 2048 + k * 1024); } while (0)
; #define PG8_WAIT_V(n) asm volatile("s_waitcnt vmcnt(" #n ")" ::: "memory")
; #define PG8_WAIT_L(n) asm volatile("s_waitcnt lgkmcnt(" #n ")" ::: "memory")
; #define PG8_BAR __builtin_amdgcn_s_barrier()
; template <class Epi, class Sched, bool ALIGN_EPI>
; __device__ __forceinline__ void gemm_phase(LAS unsigned char* lds, const Gemm g, const Sched& S, const Epi& E) {
;     ...
;         const bool has_next = S.next(ui + 1, nxt);
;         const char* nA = has_next ? (const char*)g.A + (size_t)nxt.pm * tstepA + (size_t)nxt.pn * g.a_koff * 2 : cA; const char* nB = has_next ? (const char*)g.Bt + (size_t)nxt.pn * tstepB : cB;
; #pragma unroll 1
;         for (int t = 0; t < nt; t += 2) {
;             const bool last = (t == nt - 2);
;             const char* a1 = cA + (size_t)(t + 1) * kstep;
;             const char* a2 = last ? nA : cA + (size_t)(t + 2) * kstep; const char* b2 = last ? nB : cB + (size_t)(t + 2) * kstep;
;             const char* a3 = a2 + kstep; const char* b3 = b2 + kstep;
;             PG8_LDB(B0, 0, 0); PG8_LDB(B1, 0, 1); PG8_SCHED; PG8_LDA(At, 0, 0); PG8_STAGE(PG8_SA(1, 1), a1 + hstepA, voffA);
;             PG8_WAIT_V(8); PG8_WAIT_L(0); PG8_BAR; PG8_MMA(0, 0, At, B0); PG8_MMA(0, 1, At, B1); PG8_BAR; PG8_SCHED;
;             PG8_LDA(At, 0, 1); PG8_STAGE(PG8_SB(0, 0), b2, voffB); PG8_STAGE(PG8_SB(0, 1), b2 + hstepB, voffB); PG8_STAGE(PG8_SA(0, 0), a2, voffA);
;             PG8_WAIT_V(8); PG8_WAIT_L(0); PG8_BAR; PG8_MMA(1, 0, At, B0); PG8_MMA(1, 1, At, B1); PG8_BAR; PG8_SCHED;
.LBB0_805:
	s_add_u32 s48, s34, s40
	s_addc_u32 s49, s35, s41
	s_add_u32 s44, s48, 0x100
	s_addc_u32 s45, s49, 0
	s_and_b64 s[42:43], s[38:39], exec
	s_cselect_b32 s45, s3, s45
	s_cselect_b32 s44, s17, s44
	s_add_u32 s40, s30, s40
	s_addc_u32 s41, s31, s41
	s_add_u32 s42, s40, 0x100
	s_addc_u32 s43, s41, 0
	s_add_u32 s40, s44, 0x80
	s_addc_u32 s41, s45, 0
	ds_read_b128 v[130:133], v151
	s_waitcnt vmcnt(7)
	ds_read_b128 v[134:137], v151 offset:1024
	ds_read_b128 v[156:159], v151 offset:2048
	s_waitcnt vmcnt(0)
	ds_read_b128 v[160:163], v151 offset:3072
	ds_read_b128 v[164:167], v152
	ds_read_b128 v[168:171], v152 offset:1024
	ds_read_b128 v[172:175], v152 offset:2048
	ds_read_b128 v[180:183], v152 offset:3072
	s_and_b64 s[38:39], s[38:39], exec
	s_cselect_b32 s47, s15, s43
	s_cselect_b32 s46, s72, s42
	s_add_u32 s52, s48, 0x40080
	s_addc_u32 s53, s49, 0
	s_add_u32 s48, s46, 0x10000
	s_addc_u32 s49, s47, 0
	s_add_u32 s42, s44, 0x40000
	s_addc_u32 s43, s45, 0
	s_add_u32 s38, s46, 0x80
	s_addc_u32 s39, s47, 0
	s_add_u32 s50, s46, 0x10080
	s_addc_u32 s51, s47, 0
	ds_read_b128 v[184:187], v153
	ds_read_b128 v[188:191], v153 offset:1024
	ds_read_b128 v[192:195], v153 offset:2048
	ds_read_b128 v[196:199], v153 offset:3072
	ds_read_b128 v[200:203], v153 offset:4096
	ds_read_b128 v[204:207], v153 offset:5120
	ds_read_b128 v[208:211], v153 offset:6144
	ds_read_b128 v[212:215], v153 offset:7168
	s_mov_b32 m0, s70
	s_nop 0
	global_load_lds_dwordx4 v144, s[52:53]
	s_nop 0
	s_mov_b32 m0, s71
	s_nop 0
	global_load_lds_dwordx4 v146, s[52:53]
	s_waitcnt vmcnt(8)
	s_waitcnt lgkmcnt(0)
	s_barrier
	s_setprio 1
	v_mfma_f32_16x16x32_bf16 v[126:129], v[130:133], v[184:187], v[126:129]
	v_mfma_f32_16x16x32_bf16 v[118:121], v[130:133], v[192:195], v[118:121]
	v_mfma_f32_16x16x32_bf16 v[110:113], v[130:133], v[200:203], v[110:113]
	v_mfma_f32_16x16x32_bf16 v[102:105], v[130:133], v[208:211], v[102:105]
	v_mfma_f32_16x16x32_bf16 v[98:101], v[156:159], v[208:211], v[98:101]
	v_mfma_f32_16x16x32_bf16 v[106:109], v[156:159], v[200:203], v[106:109]
	v_mfma_f32_16x16x32_bf16 v[114:117], v[156:159], v[192:195], v[114:117]
	v_mfma_f32_16x16x32_bf16 v[122:125], v[156:159], v[184:187], v[122:125]
	v_mfma_f32_16x16x32_bf16 v[122:125], v[160:163], v[188:191], v[122:125]
	v_mfma_f32_16x16x32_bf16 v[114:117], v[160:163], v[196:199], v[114:117]
	v_mfma_f32_16x16x32_bf16 v[106:109], v[160:163], v[204:207], v[106:109]
	v_mfma_f32_16x16x32_bf16 v[98:101], v[160:163], v[212:215], v[98:101]
	v_mfma_f32_16x16x32_bf16 v[102:105], v[134:137], v[212:215], v[102:105]
	v_mfma_f32_16x16x32_bf16 v[110:113], v[134:137], v[204:207], v[110:113]
	v_mfma_f32_16x16x32_bf16 v[118:121], v[134:137], v[196:199], v[118:121]
	v_mfma_f32_16x16x32_bf16 v[126:129], v[134:137], v[188:191], v[126:129]
	v_mfma_f32_16x16x32_bf16 v[70:73], v[164:167], v[184:187], v[70:73]
	v_mfma_f32_16x16x32_bf16 v[58:61], v[164:167], v[192:195], v[58:61]
	v_mfma_f32_16x16x32_bf16 v[46:49], v[164:167], v[200:203], v[46:49]
	v_mfma_f32_16x16x32_bf16 v[38:41], v[164:167], v[208:211], v[38:41]
	v_mfma_f32_16x16x32_bf16 v[34:37], v[172:175], v[208:211], v[34:37]
	v_mfma_f32_16x16x32_bf16 v[42:45], v[172:175], v[200:203], v[42:45]
	v_mfma_f32_16x16x32_bf16 v[50:53], v[172:175], v[192:195], v[50:53]
	v_mfma_f32_16x16x32_bf16 v[66:69], v[172:175], v[184:187], v[66:69]
	v_mfma_f32_16x16x32_bf16 v[66:69], v[180:183], v[188:191], v[66:69]
	v_mfma_f32_16x16x32_bf16 v[50:53], v[180:183], v[196:199], v[50:53]
	v_mfma_f32_16x16x32_bf16 v[42:45], v[180:183], v[204:207], v[42:45]
	v_mfma_f32_16x16x32_bf16 v[34:37], v[180:183], v[212:215], v[34:37]
	v_mfma_f32_16x16x32_bf16 v[38:41], v[168:171], v[212:215], v[38:41]
	v_mfma_f32_16x16x32_bf16 v[46:49], v[168:171], v[204:207], v[46:49]
	v_mfma_f32_16x16x32_bf16 v[58:61], v[168:171], v[196:199], v[58:61]
	v_mfma_f32_16x16x32_bf16 v[70:73], v[168:171], v[188:191], v[70:73]
	s_setprio 0
	s_barrier
	ds_read_b128 v[184:187], v153 offset:16384
	ds_read_b128 v[188:191], v153 offset:17408
	ds_read_b128 v[192:195], v153 offset:18432
	ds_read_b128 v[196:199], v153 offset:19456
	ds_read_b128 v[200:203], v153 offset:20480
	ds_read_b128 v[204:207], v153 offset:21504
	ds_read_b128 v[208:211], v153 offset:22528
	ds_read_b128 v[212:215], v153 offset:23552
	s_mov_b32 m0, s29
	s_nop 0
	global_load_lds_dwordx4 v145, s[46:47]
	s_nop 0
	s_mov_b32 m0, s57
	s_nop 0
	global_load_lds_dwordx4 v147, s[46:47]
	s_mov_b32 m0, s58
	s_nop 0
	global_load_lds_dwordx4 v145, s[48:49]
	s_nop 0
	s_mov_b32 m0, s59
	s_nop 0
	global_load_lds_dwordx4 v147, s[48:49]
	s_nop 0
	s_mov_b32 m0, s56
	s_nop 0
	global_load_lds_dwordx4 v144, s[44:45]
	s_nop 0
	s_mov_b32 m0, s61
	s_nop 0
	global_load_lds_dwordx4 v146, s[44:45]
	s_waitcnt vmcnt(8)
	s_waitcnt lgkmcnt(0)
	s_barrier
; #define PG8_STAGE(bufoff, gbase, voff) do { _Pragma("unroll") for (int _i = 0; _i < 2; ++_i) { unsigned keep_; \
;         asm volatile("s_mov_b32 %0, m0\n\ts_mov_b32 m0, %3\n\ts_nop 0\n\tglobal_load_lds_dwordx4 %1, %2\n\ts_mov_b32 m0, %0" \
;             : "=&s"(keep_) : "v"((voff)[_i]), "s"((const void*)(gbase)), "s"(ldsb0 + (unsigned)(bufoff) + (unsigned)(_i * 8192)) : "memory"); } } while (0)
; #define PG8_LDA(dst, b, h) do { _Pragma("unroll") for (int m = 0; m < 4; ++m) _Pragma("unroll") for (int k = 0; k < 2; ++k) dst[m][k] = *(const LAS bf16x8*)(lds + PG8_SA(b, h) + aoff + m * 2048 + k * 1024); } while (0)
; #define PG8_LDB(dst, b, h) do { _Pragma("unroll") for (int n = 0; n < 2; ++n) _Pragma("unroll") for (int k = 0; k < 2; ++k) dst[n][k] = *(const LAS bf16x8*)(lds + PG8_SB(b, h) + boff + n * 2048 + k * 1024); } while (0)
; #define PG8_MMA(ai, bj, At, Bt) do { __builtin_amdgcn_s_setprio(1); _Pragma("unroll") for (int m = 0; m < 4; ++m) _Pragma("unroll") for (int n = 0; n < 2; ++n) _Pragma("unroll") for (int k = 0; k < 2; ++k) \
;         acc[ai][bj][m][n] = __builtin_amdgcn_mfma_f32_16x16x32_bf16(Bt[n][k], At[m][k], acc[ai][bj][m][n], 0, 0, 0); __builtin_amdgcn_s_setprio(0); } while (0)
; #define PG8_WAIT_V(n) asm volatile("s_waitcnt vmcnt(" #n ")" ::: "memory")
; #define PG8_WAIT_L(n) asm volatile("s_waitcnt lgkmcnt(" #n ")" ::: "memory")
; #define PG8_BAR __builtin_amdgcn_s_barrier()
; #define PG8_SCHED __builtin_amdgcn_sched_barrier(0)
; template <class Epi, class Sched, bool ALIGN_EPI>
; __device__ __forceinline__ void gemm_phase(LAS unsigned char* lds, const Gemm g, const Sched& S, const Epi& E) {
;     ...
;             PG8_WAIT_V(8); PG8_WAIT_L(0); PG8_BAR; PG8_MMA(1, 0, At, B0); PG8_MMA(1, 1, At, B1); PG8_BAR; PG8_SCHED;
;             PG8_LDB(B0, 1, 0); PG8_LDB(B1, 1, 1); PG8_SCHED; PG8_LDA(At, 1, 0); PG8_STAGE(PG8_SA(0, 1), a2 + hstepA, voffA);
;             PG8_WAIT_V(8); PG8_WAIT_L(0); PG8_BAR; PG8_MMA(0, 0, At, B0); PG8_MMA(0, 1, At, B1); PG8_BAR; PG8_SCHED;
;             PG8_LDA(At, 1, 1); PG8_STAGE(PG8_SB(1, 0), b3, voffB); PG8_STAGE(PG8_SB(1, 1), b3 + hstepB, voffB); PG8_STAGE(PG8_SA(1, 0), a3, voffA);
;             PG8_WAIT_V(8); PG8_WAIT_L(0); PG8_BAR; PG8_MMA(1, 0, At, B0); PG8_MMA(1, 1, At, B1); PG8_BAR; PG8_SCHED;
	s_setprio 1
	v_mfma_f32_16x16x32_bf16 v[94:97], v[130:133], v[184:187], v[94:97]
	v_mfma_f32_16x16x32_bf16 v[86:89], v[130:133], v[192:195], v[86:89]
	v_mfma_f32_16x16x32_bf16 v[78:81], v[130:133], v[200:203], v[78:81]
	v_mfma_f32_16x16x32_bf16 v[62:65], v[130:133], v[208:211], v[62:65]
	v_mfma_f32_16x16x32_bf16 v[54:57], v[156:159], v[208:211], v[54:57]
	v_mfma_f32_16x16x32_bf16 v[74:77], v[156:159], v[200:203], v[74:77]
	v_mfma_f32_16x16x32_bf16 v[82:85], v[156:159], v[192:195], v[82:85]
	v_mfma_f32_16x16x32_bf16 v[90:93], v[156:159], v[184:187], v[90:93]
	v_mfma_f32_16x16x32_bf16 v[90:93], v[160:163], v[188:191], v[90:93]
	v_mfma_f32_16x16x32_bf16 v[82:85], v[160:163], v[196:199], v[82:85]
	v_mfma_f32_16x16x32_bf16 v[74:77], v[160:163], v[204:207], v[74:77]
	v_mfma_f32_16x16x32_bf16 v[54:57], v[160:163], v[212:215], v[54:57]
	v_mfma_f32_16x16x32_bf16 v[62:65], v[134:137], v[212:215], v[62:65]
	v_mfma_f32_16x16x32_bf16 v[78:81], v[134:137], v[204:207], v[78:81]
	v_mfma_f32_16x16x32_bf16 v[86:89], v[134:137], v[196:199], v[86:89]
	v_mfma_f32_16x16x32_bf16 v[94:97], v[134:137], v[188:191], v[94:97]
	v_mfma_f32_16x16x32_bf16 v[30:33], v[164:167], v[184:187], v[30:33]
	v_mfma_f32_16x16x32_bf16 v[22:25], v[164:167], v[192:195], v[22:25]
	v_mfma_f32_16x16x32_bf16 v[14:17], v[164:167], v[200:203], v[14:17]
	v_mfma_f32_16x16x32_bf16 v[6:9], v[164:167], v[208:211], v[6:9]
	v_mfma_f32_16x16x32_bf16 v[2:5], v[172:175], v[208:211], v[2:5]
	v_mfma_f32_16x16x32_bf16 v[10:13], v[172:175], v[200:203], v[10:13]
	v_mfma_f32_16x16x32_bf16 v[18:21], v[172:175], v[192:195], v[18:21]
	v_mfma_f32_16x16x32_bf16 v[26:29], v[172:175], v[184:187], v[26:29]
	v_mfma_f32_16x16x32_bf16 v[26:29], v[180:183], v[188:191], v[26:29]
	v_mfma_f32_16x16x32_bf16 v[18:21], v[180:183], v[196:199], v[18:21]
	v_mfma_f32_16x16x32_bf16 v[10:13], v[180:183], v[204:207], v[10:13]
	v_mfma_f32_16x16x32_bf16 v[2:5], v[180:183], v[212:215], v[2:5]
	v_mfma_f32_16x16x32_bf16 v[6:9], v[168:171], v[212:215], v[6:9]
	v_mfma_f32_16x16x32_bf16 v[14:17], v[168:171], v[204:207], v[14:17]
	v_mfma_f32_16x16x32_bf16 v[22:25], v[168:171], v[196:199], v[22:25]
	v_mfma_f32_16x16x32_bf16 v[30:33], v[168:171], v[188:191], v[30:33]
	s_setprio 0
	s_barrier
	ds_read_b128 v[130:133], v154
	ds_read_b128 v[134:137], v154 offset:1024
	ds_read_b128 v[156:159], v154 offset:2048
	ds_read_b128 v[160:163], v154 offset:3072
	ds_read_b128 v[164:167], v155
	ds_read_b128 v[168:171], v155 offset:1024
	ds_read_b128 v[172:175], v155 offset:2048
	ds_read_b128 v[180:183], v155 offset:3072
	ds_read_b128 v[184:187], v153 offset:32768
	ds_read_b128 v[188:191], v153 offset:33792
	ds_read_b128 v[192:195], v153 offset:34816
	ds_read_b128 v[196:199], v153 offset:35840
	ds_read_b128 v[200:203], v153 offset:36864
	ds_read_b128 v[204:207], v153 offset:37888
	ds_read_b128 v[208:211], v153 offset:38912
	ds_read_b128 v[212:215], v153 offset:39936
	s_mov_b32 m0, s62
	s_nop 0
	global_load_lds_dwordx4 v144, s[42:43]
	s_nop 0
	s_mov_b32 m0, s63
	s_nop 0
	global_load_lds_dwordx4 v146, s[42:43]
	s_waitcnt vmcnt(8)
	s_waitcnt lgkmcnt(0)
	s_barrier
	s_setprio 1
	v_mfma_f32_16x16x32_bf16 v[126:129], v[130:133], v[184:187], v[126:129]
	v_mfma_f32_16x16x32_bf16 v[118:121], v[130:133], v[192:195], v[118:121]
	v_mfma_f32_16x16x32_bf16 v[110:113], v[130:133], v[200:203], v[110:113]
	v_mfma_f32_16x16x32_bf16 v[102:105], v[130:133], v[208:211], v[102:105]
	v_mfma_f32_16x16x32_bf16 v[98:101], v[156:159], v[208:211], v[98:101]
	v_mfma_f32_16x16x32_bf16 v[106:109], v[156:159], v[200:203], v[106:109]
	v_mfma_f32_16x16x32_bf16 v[114:117], v[156:159], v[192:195], v[114:117]
	v_mfma_f32_16x16x32_bf16 v[122:125], v[156:159], v[184:187], v[122:125]
	v_mfma_f32_16x16x32_bf16 v[122:125], v[160:163], v[188:191], v[122:125]
	v_mfma_f32_16x16x32_bf16 v[114:117], v[160:163], v[196:199], v[114:117]
	v_mfma_f32_16x16x32_bf16 v[106:109], v[160:163], v[204:207], v[106:109]
	v_mfma_f32_16x16x32_bf16 v[98:101], v[160:163], v[212:215], v[98:101]
	v_mfma_f32_16x16x32_bf16 v[102:105], v[134:137], v[212:215], v[102:105]
	v_mfma_f32_16x16x32_bf16 v[110:113], v[134:137], v[204:207], v[110:113]
	v_mfma_f32_16x16x32_bf16 v[118:121], v[134:137], v[196:199], v[118:121]
	v_mfma_f32_16x16x32_bf16 v[126:129], v[134:137], v[188:191], v[126:129]
	v_mfma_f32_16x16x32_bf16 v[70:73], v[164:167], v[184:187], v[70:73]
	v_mfma_f32_16x16x32_bf16 v[58:61], v[164:167], v[192:195], v[58:61]
	v_mfma_f32_16x16x32_bf16 v[46:49], v[164:167], v[200:203], v[46:49]
	v_mfma_f32_16x16x32_bf16 v[38:41], v[164:167], v[208:211], v[38:41]
	v_mfma_f32_16x16x32_bf16 v[34:37], v[172:175], v[208:211], v[34:37]
	v_mfma_f32_16x16x32_bf16 v[42:45], v[172:175], v[200:203], v[42:45]
	v_mfma_f32_16x16x32_bf16 v[50:53], v[172:175], v[192:195], v[50:53]
	v_mfma_f32_16x16x32_bf16 v[66:69], v[172:175], v[184:187], v[66:69]
	v_mfma_f32_16x16x32_bf16 v[66:69], v[180:183], v[188:191], v[66:69]
	v_mfma_f32_16x16x32_bf16 v[50:53], v[180:183], v[196:199], v[50:53]
	v_mfma_f32_16x16x32_bf16 v[42:45], v[180:183], v[204:207], v[42:45]
	v_mfma_f32_16x16x32_bf16 v[34:37], v[180:183], v[212:215], v[34:37]
	v_mfma_f32_16x16x32_bf16 v[38:41], v[168:171], v[212:215], v[38:41]
	v_mfma_f32_16x16x32_bf16 v[46:49], v[168:171], v[204:207], v[46:49]
	v_mfma_f32_16x16x32_bf16 v[58:61], v[168:171], v[196:199], v[58:61]
	v_mfma_f32_16x16x32_bf16 v[70:73], v[168:171], v[188:191], v[70:73]
	s_setprio 0
	s_barrier
; #define PG8_STAGE(bufoff, gbase, voff) do { _Pragma("unroll") for (int _i = 0; _i < 2; ++_i) { unsigned keep_; \
;         asm volatile("s_mov_b32 %0, m0\n\ts_mov_b32 m0, %3\n\ts_nop 0\n\tglobal_load_lds_dwordx4 %1, %2\n\ts_mov_b32 m0, %0" \
;             : "=&s"(keep_) : "v"((voff)[_i]), "s"((const void*)(gbase)), "s"(ldsb0 + (unsigned)(bufoff) + (unsigned)(_i * 8192)) : "memory"); } } while (0)
; #define PG8_LDA(dst, b, h) do { _Pragma("unroll") for (int m = 0; m < 4; ++m) _Pragma("unroll") for (int k = 0; k < 2; ++k) dst[m][k] = *(const LAS bf16x8*)(lds + PG8_SA(b, h) + aoff + m * 2048 + k * 1024); } while (0)
; #define PG8_MMA(ai, bj, At, Bt) do { __builtin_amdgcn_s_setprio(1); _Pragma("unroll") for (int m = 0; m < 4; ++m) _Pragma("unroll") for (int n = 0; n < 2; ++n) _Pragma("unroll") for (int k = 0; k < 2; ++k) \
;         acc[ai][bj][m][n] = __builtin_amdgcn_mfma_f32_16x16x32_bf16(Bt[n][k], At[m][k], acc[ai][bj][m][n], 0, 0, 0); __builtin_amdgcn_s_setprio(0); } while (0)
; #define PG8_WAIT_V(n) asm volatile("s_waitcnt vmcnt(" #n ")" ::: "memory")
; #define PG8_WAIT_L(n) asm volatile("s_waitcnt lgkmcnt(" #n ")" ::: "memory")
; #define PG8_BAR __builtin_amdgcn_s_barrier()
; #define PG8_SCHED __builtin_amdgcn_sched_barrier(0)
; template <class Epi, class Sched, bool ALIGN_EPI>
; __device__ __forceinline__ void gemm_phase(LAS unsigned char* lds, const Gemm g, const Sched& S, const Epi& E) {
;     ...
;             PG8_LDA(At, 1, 1); PG8_STAGE(PG8_SB(1, 0), b3, voffB); PG8_STAGE(PG8_SB(1, 1), b3 + hstepB, voffB); PG8_STAGE(PG8_SA(1, 0), a3, voffA);
;             PG8_WAIT_V(8); PG8_WAIT_L(0); PG8_BAR; PG8_MMA(1, 0, At, B0); PG8_MMA(1, 1, At, B1); PG8_BAR; PG8_SCHED;
;         }
;         if constexpr (ALIGN_EPI) { if (wr == 0) PG8_BAR; }
	ds_read_b128 v[184:187], v153 offset:49152
	ds_read_b128 v[188:191], v153 offset:50176
	ds_read_b128 v[192:195], v153 offset:51200
	ds_read_b128 v[196:199], v153 offset:52224
	ds_read_b128 v[200:203], v153 offset:53248
	ds_read_b128 v[204:207], v153 offset:54272
	ds_read_b128 v[208:211], v153 offset:55296
	ds_read_b128 v[212:215], v153 offset:56320
	s_mov_b32 m0, s64
	s_nop 0
	global_load_lds_dwordx4 v145, s[38:39]
	s_nop 0
	s_mov_b32 m0, s65
	s_nop 0
	global_load_lds_dwordx4 v147, s[38:39]
	s_mov_b32 m0, s68
	s_nop 0
	global_load_lds_dwordx4 v145, s[50:51]
	s_nop 0
	s_mov_b32 m0, s69
	s_nop 0
	global_load_lds_dwordx4 v147, s[50:51]
	s_nop 0
	s_mov_b32 m0, s66
	s_nop 0
	global_load_lds_dwordx4 v144, s[40:41]
	s_nop 0
	s_mov_b32 m0, s67
	s_nop 0
	global_load_lds_dwordx4 v146, s[40:41]
	s_waitcnt vmcnt(8)
	s_waitcnt lgkmcnt(0)
	s_barrier
	s_setprio 1
	v_mfma_f32_16x16x32_bf16 v[94:97], v[130:133], v[184:187], v[94:97]
	v_mfma_f32_16x16x32_bf16 v[86:89], v[130:133], v[192:195], v[86:89]
	v_mfma_f32_16x16x32_bf16 v[78:81], v[130:133], v[200:203], v[78:81]
	v_mfma_f32_16x16x32_bf16 v[62:65], v[130:133], v[208:211], v[62:65]
	v_mfma_f32_16x16x32_bf16 v[54:57], v[156:159], v[208:211], v[54:57]
	v_mfma_f32_16x16x32_bf16 v[74:77], v[156:159], v[200:203], v[74:77]
	v_mfma_f32_16x16x32_bf16 v[82:85], v[156:159], v[192:195], v[82:85]
	v_mfma_f32_16x16x32_bf16 v[90:93], v[156:159], v[184:187], v[90:93]
	v_mfma_f32_16x16x32_bf16 v[90:93], v[160:163], v[188:191], v[90:93]
	v_mfma_f32_16x16x32_bf16 v[82:85], v[160:163], v[196:199], v[82:85]
	v_mfma_f32_16x16x32_bf16 v[74:77], v[160:163], v[204:207], v[74:77]
	v_mfma_f32_16x16x32_bf16 v[54:57], v[160:163], v[212:215], v[54:57]
	v_mfma_f32_16x16x32_bf16 v[62:65], v[134:137], v[212:215], v[62:65]
	v_mfma_f32_16x16x32_bf16 v[78:81], v[134:137], v[204:207], v[78:81]
	v_mfma_f32_16x16x32_bf16 v[86:89], v[134:137], v[196:199], v[86:89]
	v_mfma_f32_16x16x32_bf16 v[94:97], v[134:137], v[188:191], v[94:97]
	v_mfma_f32_16x16x32_bf16 v[30:33], v[164:167], v[184:187], v[30:33]
	v_mfma_f32_16x16x32_bf16 v[22:25], v[164:167], v[192:195], v[22:25]
	v_mfma_f32_16x16x32_bf16 v[14:17], v[164:167], v[200:203], v[14:17]
	v_mfma_f32_16x16x32_bf16 v[6:9], v[164:167], v[208:211], v[6:9]
	v_mfma_f32_16x16x32_bf16 v[2:5], v[172:175], v[208:211], v[2:5]
	v_mfma_f32_16x16x32_bf16 v[10:13], v[172:175], v[200:203], v[10:13]
	v_mfma_f32_16x16x32_bf16 v[18:21], v[172:175], v[192:195], v[18:21]
	v_mfma_f32_16x16x32_bf16 v[26:29], v[172:175], v[184:187], v[26:29]
	v_mfma_f32_16x16x32_bf16 v[26:29], v[180:183], v[188:191], v[26:29]
	v_mfma_f32_16x16x32_bf16 v[18:21], v[180:183], v[196:199], v[18:21]
	v_mfma_f32_16x16x32_bf16 v[10:13], v[180:183], v[204:207], v[10:13]
	v_mfma_f32_16x16x32_bf16 v[2:5], v[180:183], v[212:215], v[2:5]
	v_mfma_f32_16x16x32_bf16 v[6:9], v[168:171], v[212:215], v[6:9]
	v_mfma_f32_16x16x32_bf16 v[14:17], v[168:171], v[204:207], v[14:17]
	v_mfma_f32_16x16x32_bf16 v[22:25], v[168:171], v[196:199], v[22:25]
	v_mfma_f32_16x16x32_bf16 v[30:33], v[168:171], v[188:191], v[30:33]
	s_setprio 0
	s_barrier
	s_andn2_b64 vcc, exec, s[36:37]
	s_mov_b64 s[38:39], -1
	s_mov_b64 s[36:37], 0
	s_mov_b64 s[40:41], 0x100
	s_cbranch_vccz .LBB0_805
	s_and_b64 vcc, exec, s[12:13]
	s_cbranch_vccz .LBB0_808
	s_barrier

; #define PG8_STAGE(bufoff, gbase, voff) do { _Pragma("unroll") for (int _i = 0; _i < 2; ++_i) { unsigned keep_; \
;         asm volatile("s_mov_b32 %0, m0\n\ts_mov_b32 m0, %3\n\ts_nop 0\n\tglobal_load_lds_dwordx4 %1, %2\n\ts_mov_b32 m0, %0" \
;             : "=&s"(keep_) : "v"((voff)[_i]), "s"((const void*)(gbase)), "s"(ldsb0 + (unsigned)(bufoff) + (unsigned)(_i * 8192)) : "memory"); } } while (0)
; #define PG8_LDA(dst, b, h) do { _Pragma("unroll") for (int m = 0; m < 4; ++m) _Pragma("unroll") for (int k = 0; k < 2; ++k) dst[m][k] = *(const LAS bf16x8*)(lds + PG8_SA(b, h) + aoff + m * 2048 + k * 1024); } while (0)
; #define PG8_LDB(dst, b, h) do { _Pragma("unroll") for (int n = 0; n < 2; ++n) _Pragma("unroll") for (int k = 0; k < 2; ++k) dst[n][k] = *(const LAS bf16x8*)(lds + PG8_SB(b, h) + boff + n * 2048 + k * 1024); } while (0)
; #define PG8_MMA(ai, bj, At, Bt) do { __builtin_amdgcn_s_setprio(1); _Pragma("unroll") for (int m = 0; m < 4; ++m) _Pragma("unroll") for (int n = 0; n < 2; ++n) _Pragma("unroll") for (int k = 0; k < 2; ++k) \
;         acc[ai][bj][m][n] = __builtin_amdgcn_mfma_f32_16x16x32_bf16(Bt[n][k], At[m][k], acc[ai][bj][m][n], 0, 0, 0); __builtin_amdgcn_s_setprio(0); } while (0)
; #define PG8_WAIT_V(n) asm volatile("s_waitcnt vmcnt(" #n ")" ::: "memory")
; #define PG8_BAR __builtin_amdgcn_s_barrier()
; template <class Epi, class Sched, bool ALIGN_EPI>
; __device__ __forceinline__ void gemm_phase(LAS unsigned char* lds, const Gemm g, const Sched& S, const Epi& E) {
;     ...
;         for (int t = 0; t < nt; t += 2) {
;             const bool last = (t == nt - 2);
;             const char* a1 = cA + (size_t)(t + 1) * kstep;
;             const char* a2 = last ? nA : cA + (size_t)(t + 2) * kstep; const char* b2 = last ? nB : cB + (size_t)(t + 2) * kstep;
;             const char* a3 = a2 + kstep; const char* b3 = b2 + kstep;
;             PG8_LDB(B0, 0, 0); PG8_LDB(B1, 0, 1); PG8_SCHED; PG8_LDA(At, 0, 0); PG8_STAGE(PG8_SA(1, 1), a1 + hstepA, voffA);
;             PG8_WAIT_V(8); PG8_WAIT_L(0); PG8_BAR; PG8_MMA(0, 0, At, B0); PG8_MMA(0, 1, At, B1); PG8_BAR; PG8_SCHED;
;             PG8_LDA(At, 0, 1); PG8_STAGE(PG8_SB(0, 0), b2, voffB); PG8_STAGE(PG8_SB(0, 1), b2 + hstepB, voffB); PG8_STAGE(PG8_SA(0, 0), a2, voffA);
;             PG8_WAIT_V(8); PG8_WAIT_L(0); PG8_BAR; PG8_MMA(1, 0, At, B0); PG8_MMA(1, 1, At, B1); PG8_BAR; PG8_SCHED;
.LBB0_1137:
	ds_read_b128 v[110:113], v206
	ds_read_b128 v[126:129], v206 offset:1024
	ds_read_b128 v[130:133], v206 offset:2048
	ds_read_b128 v[142:145], v206 offset:3072
	ds_read_b128 v[146:149], v207
	ds_read_b128 v[150:153], v207 offset:1024
	ds_read_b128 v[154:157], v207 offset:2048
	ds_read_b128 v[158:161], v207 offset:3072
	s_cmp_eq_u32 s63, 28
	s_cselect_b32 s40, s5, s19
	s_cselect_b32 s41, s3, s27
	s_cselect_b32 s38, s7, s61
	s_cselect_b32 s39, s6, s62
	s_add_u32 s36, s40, 0x80
	s_addc_u32 s37, s41, 0
	ds_read_b128 v[162:165], v208
	ds_read_b128 v[166:169], v208 offset:1024
	ds_read_b128 v[170:173], v208 offset:2048
	ds_read_b128 v[174:177], v208 offset:3072
	ds_read_b128 v[188:191], v208 offset:4096
	ds_read_b128 v[192:195], v208 offset:5120
	ds_read_b128 v[196:199], v208 offset:6144
	ds_read_b128 v[212:215], v208 offset:7168
	s_mov_b32 m0, s58
	s_nop 0
	global_load_lds_dwordx4 v179, s[34:35]
	s_nop 0
	s_mov_b32 m0, s59
	s_nop 0
	global_load_lds_dwordx4 v201, s[34:35]
	s_waitcnt vmcnt(8)
	s_waitcnt lgkmcnt(0)
	s_barrier
	s_setprio 1
	v_mfma_f32_16x16x32_bf16 v[138:141], v[110:113], v[162:165], v[138:141]
	v_mfma_f32_16x16x32_bf16 v[114:117], v[110:113], v[170:173], v[114:117]
	v_mfma_f32_16x16x32_bf16 v[94:97], v[110:113], v[188:191], v[94:97]
	v_mfma_f32_16x16x32_bf16 v[78:81], v[110:113], v[196:199], v[78:81]
	v_mfma_f32_16x16x32_bf16 v[74:77], v[130:133], v[196:199], v[74:77]
	v_mfma_f32_16x16x32_bf16 v[90:93], v[130:133], v[188:191], v[90:93]
	v_mfma_f32_16x16x32_bf16 v[106:109], v[130:133], v[170:173], v[106:109]
	v_mfma_f32_16x16x32_bf16 v[134:137], v[130:133], v[162:165], v[134:137]
	v_mfma_f32_16x16x32_bf16 v[134:137], v[142:145], v[166:169], v[134:137]
	v_mfma_f32_16x16x32_bf16 v[106:109], v[142:145], v[174:177], v[106:109]
	v_mfma_f32_16x16x32_bf16 v[90:93], v[142:145], v[192:195], v[90:93]
	v_mfma_f32_16x16x32_bf16 v[74:77], v[142:145], v[212:215], v[74:77]
	v_mfma_f32_16x16x32_bf16 v[78:81], v[126:129], v[212:215], v[78:81]
	v_mfma_f32_16x16x32_bf16 v[94:97], v[126:129], v[192:195], v[94:97]
	v_mfma_f32_16x16x32_bf16 v[114:117], v[126:129], v[174:177], v[114:117]
	v_mfma_f32_16x16x32_bf16 v[138:141], v[126:129], v[166:169], v[138:141]
	v_mfma_f32_16x16x32_bf16 v[122:125], v[146:149], v[162:165], v[122:125]
	v_mfma_f32_16x16x32_bf16 v[102:105], v[146:149], v[170:173], v[102:105]
	v_mfma_f32_16x16x32_bf16 v[86:89], v[146:149], v[188:191], v[86:89]
	v_mfma_f32_16x16x32_bf16 v[70:73], v[146:149], v[196:199], v[70:73]
	v_mfma_f32_16x16x32_bf16 v[66:69], v[154:157], v[196:199], v[66:69]
	v_mfma_f32_16x16x32_bf16 v[82:85], v[154:157], v[188:191], v[82:85]
	v_mfma_f32_16x16x32_bf16 v[98:101], v[154:157], v[170:173], v[98:101]
	v_mfma_f32_16x16x32_bf16 v[118:121], v[154:157], v[162:165], v[118:121]
	v_mfma_f32_16x16x32_bf16 v[118:121], v[158:161], v[166:169], v[118:121]
	v_mfma_f32_16x16x32_bf16 v[98:101], v[158:161], v[174:177], v[98:101]
	v_mfma_f32_16x16x32_bf16 v[82:85], v[158:161], v[192:195], v[82:85]
	v_mfma_f32_16x16x32_bf16 v[66:69], v[158:161], v[212:215], v[66:69]
	v_mfma_f32_16x16x32_bf16 v[70:73], v[150:153], v[212:215], v[70:73]
	v_mfma_f32_16x16x32_bf16 v[86:89], v[150:153], v[192:195], v[86:89]
	v_mfma_f32_16x16x32_bf16 v[102:105], v[150:153], v[174:177], v[102:105]
	v_mfma_f32_16x16x32_bf16 v[122:125], v[150:153], v[166:169], v[122:125]
	s_setprio 0
	s_barrier
	ds_read_b128 v[162:165], v208 offset:16384
	ds_read_b128 v[166:169], v208 offset:17408
	ds_read_b128 v[170:173], v208 offset:18432
	ds_read_b128 v[174:177], v208 offset:19456
	ds_read_b128 v[188:191], v208 offset:20480
	ds_read_b128 v[192:195], v208 offset:21504
	ds_read_b128 v[196:199], v208 offset:22528
	ds_read_b128 v[212:215], v208 offset:23552
	s_mov_b32 m0, s45
	s_nop 0
	global_load_lds_dwordx4 v200, s[38:39]
	s_nop 0
	s_mov_b32 m0, s46
	s_nop 0
	global_load_lds_dwordx4 v203, s[38:39]
	s_add_u32 s64, s38, 0x80000
	s_addc_u32 s65, s39, 0
	s_mov_b32 m0, s47
	s_nop 0
	global_load_lds_dwordx4 v200, s[64:65]
	s_nop 0
	s_mov_b32 m0, s48
	s_nop 0
	global_load_lds_dwordx4 v203, s[64:65]
	s_mov_b32 m0, s44
	s_nop 0
	global_load_lds_dwordx4 v179, s[40:41]
	s_nop 0
	s_mov_b32 m0, s49
	s_nop 0
	global_load_lds_dwordx4 v201, s[40:41]
	s_waitcnt vmcnt(8)
	s_waitcnt lgkmcnt(0)
	s_barrier
	s_setprio 1
	v_mfma_f32_16x16x32_bf16 v[62:65], v[110:113], v[162:165], v[62:65]
	v_mfma_f32_16x16x32_bf16 v[46:49], v[110:113], v[170:173], v[46:49]
	v_mfma_f32_16x16x32_bf16 v[30:33], v[110:113], v[188:191], v[30:33]
	v_mfma_f32_16x16x32_bf16 v[14:17], v[110:113], v[196:199], v[14:17]
	v_mfma_f32_16x16x32_bf16 v[10:13], v[130:133], v[196:199], v[10:13]
	v_mfma_f32_16x16x32_bf16 v[26:29], v[130:133], v[188:191], v[26:29]
	v_mfma_f32_16x16x32_bf16 v[42:45], v[130:133], v[170:173], v[42:45]
	v_mfma_f32_16x16x32_bf16 v[58:61], v[130:133], v[162:165], v[58:61]
	v_mfma_f32_16x16x32_bf16 v[58:61], v[142:145], v[166:169], v[58:61]
	v_mfma_f32_16x16x32_bf16 v[42:45], v[142:145], v[174:177], v[42:45]
	v_mfma_f32_16x16x32_bf16 v[26:29], v[142:145], v[192:195], v[26:29]
	v_mfma_f32_16x16x32_bf16 v[10:13], v[142:145], v[212:215], v[10:13]
	v_mfma_f32_16x16x32_bf16 v[14:17], v[126:129], v[212:215], v[14:17]
	v_mfma_f32_16x16x32_bf16 v[30:33], v[126:129], v[192:195], v[30:33]
	v_mfma_f32_16x16x32_bf16 v[46:49], v[126:129], v[174:177], v[46:49]
	v_mfma_f32_16x16x32_bf16 v[62:65], v[126:129], v[166:169], v[62:65]
	v_mfma_f32_16x16x32_bf16 v[54:57], v[146:149], v[162:165], v[54:57]
	v_mfma_f32_16x16x32_bf16 v[38:41], v[146:149], v[170:173], v[38:41]
	v_mfma_f32_16x16x32_bf16 v[22:25], v[146:149], v[188:191], v[22:25]
	v_mfma_f32_16x16x32_bf16 v[6:9], v[146:149], v[196:199], v[6:9]
	v_mfma_f32_16x16x32_bf16 v[2:5], v[154:157], v[196:199], v[2:5]
	v_mfma_f32_16x16x32_bf16 v[18:21], v[154:157], v[188:191], v[18:21]
	v_mfma_f32_16x16x32_bf16 v[34:37], v[154:157], v[170:173], v[34:37]
	v_mfma_f32_16x16x32_bf16 v[50:53], v[154:157], v[162:165], v[50:53]
	v_mfma_f32_16x16x32_bf16 v[50:53], v[158:161], v[166:169], v[50:53]
	v_mfma_f32_16x16x32_bf16 v[34:37], v[158:161], v[174:177], v[34:37]
	v_mfma_f32_16x16x32_bf16 v[18:21], v[158:161], v[192:195], v[18:21]
	v_mfma_f32_16x16x32_bf16 v[2:5], v[158:161], v[212:215], v[2:5]
	v_mfma_f32_16x16x32_bf16 v[6:9], v[150:153], v[212:215], v[6:9]
	v_mfma_f32_16x16x32_bf16 v[22:25], v[150:153], v[192:195], v[22:25]
	v_mfma_f32_16x16x32_bf16 v[38:41], v[150:153], v[174:177], v[38:41]
	v_mfma_f32_16x16x32_bf16 v[54:57], v[150:153], v[166:169], v[54:57]
	s_setprio 0
	s_barrier
; #define PG8_STAGE(bufoff, gbase, voff) do { _Pragma("unroll") for (int _i = 0; _i < 2; ++_i) { unsigned keep_; \
;         asm volatile("s_mov_b32 %0, m0\n\ts_mov_b32 m0, %3\n\ts_nop 0\n\tglobal_load_lds_dwordx4 %1, %2\n\ts_mov_b32 m0, %0" \
;             : "=&s"(keep_) : "v"((voff)[_i]), "s"((const void*)(gbase)), "s"(ldsb0 + (unsigned)(bufoff) + (unsigned)(_i * 8192)) : "memory"); } } while (0)
; #define PG8_LDA(dst, b, h) do { _Pragma("unroll") for (int m = 0; m < 4; ++m) _Pragma("unroll") for (int k = 0; k < 2; ++k) dst[m][k] = *(const LAS bf16x8*)(lds + PG8_SA(b, h) + aoff + m * 2048 + k * 1024); } while (0)
; #define PG8_LDB(dst, b, h) do { _Pragma("unroll") for (int n = 0; n < 2; ++n) _Pragma("unroll") for (int k = 0; k < 2; ++k) dst[n][k] = *(const LAS bf16x8*)(lds + PG8_SB(b, h) + boff + n * 2048 + k * 1024); } while (0)
; #define PG8_MMA(ai, bj, At, Bt) do { __builtin_amdgcn_s_setprio(1); _Pragma("unroll") for (int m = 0; m < 4; ++m) _Pragma("unroll") for (int n = 0; n < 2; ++n) _Pragma("unroll") for (int k = 0; k < 2; ++k) \
;         acc[ai][bj][m][n] = __builtin_amdgcn_mfma_f32_16x16x32_bf16(Bt[n][k], At[m][k], acc[ai][bj][m][n], 0, 0, 0); __builtin_amdgcn_s_setprio(0); } while (0)
; #define PG8_WAIT_V(n) asm volatile("s_waitcnt vmcnt(" #n ")" ::: "memory")
; #define PG8_WAIT_L(n) asm volatile("s_waitcnt lgkmcnt(" #n ")" ::: "memory")
; #define PG8_BAR __builtin_amdgcn_s_barrier()
; #define PG8_SCHED __builtin_amdgcn_sched_barrier(0)
; template <class Epi, class Sched, bool ALIGN_EPI>
; __device__ __forceinline__ void gemm_phase(LAS unsigned char* lds, const Gemm g, const Sched& S, const Epi& E) {
;     ...
;             PG8_LDB(B0, 1, 0); PG8_LDB(B1, 1, 1); PG8_SCHED; PG8_LDA(At, 1, 0); PG8_STAGE(PG8_SA(0, 1), a2 + hstepA, voffA);
;             PG8_WAIT_V(8); PG8_WAIT_L(0); PG8_BAR; PG8_MMA(0, 0, At, B0); PG8_MMA(0, 1, At, B1); PG8_BAR; PG8_SCHED;
;             PG8_LDA(At, 1, 1); PG8_STAGE(PG8_SB(1, 0), b3, voffB); PG8_STAGE(PG8_SB(1, 1), b3 + hstepB, voffB); PG8_STAGE(PG8_SA(1, 0), a3, voffA);
;             PG8_WAIT_V(8); PG8_WAIT_L(0); PG8_BAR; PG8_MMA(1, 0, At, B0); PG8_MMA(1, 1, At, B1); PG8_BAR; PG8_SCHED;
;         }
;         if constexpr (ALIGN_EPI) { if (wr == 0) PG8_BAR; }
	ds_read_b128 v[110:113], v209
	ds_read_b128 v[126:129], v209 offset:1024
	ds_read_b128 v[130:133], v209 offset:2048
	ds_read_b128 v[142:145], v209 offset:3072
	ds_read_b128 v[146:149], v210
	ds_read_b128 v[150:153], v210 offset:1024
	ds_read_b128 v[154:157], v210 offset:2048
	ds_read_b128 v[158:161], v210 offset:3072
	ds_read_b128 v[162:165], v208 offset:32768
	ds_read_b128 v[166:169], v208 offset:33792
	ds_read_b128 v[170:173], v208 offset:34816
	ds_read_b128 v[174:177], v208 offset:35840
	ds_read_b128 v[188:191], v208 offset:36864
	ds_read_b128 v[192:195], v208 offset:37888
	ds_read_b128 v[196:199], v208 offset:38912
	ds_read_b128 v[212:215], v208 offset:39936
	s_add_u32 s40, s40, 0x80000
	s_addc_u32 s41, s41, 0
	s_mov_b32 m0, s50
	s_nop 0
	global_load_lds_dwordx4 v179, s[40:41]
	s_nop 0
	s_mov_b32 m0, s51
	s_nop 0
	global_load_lds_dwordx4 v201, s[40:41]
	s_waitcnt vmcnt(8)
	s_waitcnt lgkmcnt(0)
	s_barrier
	s_setprio 1
	v_mfma_f32_16x16x32_bf16 v[138:141], v[110:113], v[162:165], v[138:141]
	v_mfma_f32_16x16x32_bf16 v[114:117], v[110:113], v[170:173], v[114:117]
	v_mfma_f32_16x16x32_bf16 v[94:97], v[110:113], v[188:191], v[94:97]
	v_mfma_f32_16x16x32_bf16 v[78:81], v[110:113], v[196:199], v[78:81]
	v_mfma_f32_16x16x32_bf16 v[74:77], v[130:133], v[196:199], v[74:77]
	v_mfma_f32_16x16x32_bf16 v[90:93], v[130:133], v[188:191], v[90:93]
	v_mfma_f32_16x16x32_bf16 v[106:109], v[130:133], v[170:173], v[106:109]
	v_mfma_f32_16x16x32_bf16 v[134:137], v[130:133], v[162:165], v[134:137]
	v_mfma_f32_16x16x32_bf16 v[134:137], v[142:145], v[166:169], v[134:137]
	v_mfma_f32_16x16x32_bf16 v[106:109], v[142:145], v[174:177], v[106:109]
	v_mfma_f32_16x16x32_bf16 v[90:93], v[142:145], v[192:195], v[90:93]
	v_mfma_f32_16x16x32_bf16 v[74:77], v[142:145], v[212:215], v[74:77]
	v_mfma_f32_16x16x32_bf16 v[78:81], v[126:129], v[212:215], v[78:81]
	v_mfma_f32_16x16x32_bf16 v[94:97], v[126:129], v[192:195], v[94:97]
	v_mfma_f32_16x16x32_bf16 v[114:117], v[126:129], v[174:177], v[114:117]
	v_mfma_f32_16x16x32_bf16 v[138:141], v[126:129], v[166:169], v[138:141]
	v_mfma_f32_16x16x32_bf16 v[122:125], v[146:149], v[162:165], v[122:125]
	v_mfma_f32_16x16x32_bf16 v[102:105], v[146:149], v[170:173], v[102:105]
	v_mfma_f32_16x16x32_bf16 v[86:89], v[146:149], v[188:191], v[86:89]
	v_mfma_f32_16x16x32_bf16 v[70:73], v[146:149], v[196:199], v[70:73]
	v_mfma_f32_16x16x32_bf16 v[66:69], v[154:157], v[196:199], v[66:69]
	v_mfma_f32_16x16x32_bf16 v[82:85], v[154:157], v[188:191], v[82:85]
	v_mfma_f32_16x16x32_bf16 v[98:101], v[154:157], v[170:173], v[98:101]
	v_mfma_f32_16x16x32_bf16 v[118:121], v[154:157], v[162:165], v[118:121]
	v_mfma_f32_16x16x32_bf16 v[118:121], v[158:161], v[166:169], v[118:121]
	v_mfma_f32_16x16x32_bf16 v[98:101], v[158:161], v[174:177], v[98:101]
	v_mfma_f32_16x16x32_bf16 v[82:85], v[158:161], v[192:195], v[82:85]
	v_mfma_f32_16x16x32_bf16 v[66:69], v[158:161], v[212:215], v[66:69]
	v_mfma_f32_16x16x32_bf16 v[70:73], v[150:153], v[212:215], v[70:73]
	v_mfma_f32_16x16x32_bf16 v[86:89], v[150:153], v[192:195], v[86:89]
	v_mfma_f32_16x16x32_bf16 v[102:105], v[150:153], v[174:177], v[102:105]
	v_mfma_f32_16x16x32_bf16 v[122:125], v[150:153], v[166:169], v[122:125]
	s_setprio 0
	s_barrier
	ds_read_b128 v[162:165], v208 offset:49152
	ds_read_b128 v[166:169], v208 offset:50176
	ds_read_b128 v[170:173], v208 offset:51200
	ds_read_b128 v[174:177], v208 offset:52224
	ds_read_b128 v[188:191], v208 offset:53248
	ds_read_b128 v[192:195], v208 offset:54272
	ds_read_b128 v[196:199], v208 offset:55296
	ds_read_b128 v[212:215], v208 offset:56320
	s_add_u32 s40, s38, 0x80
	s_addc_u32 s41, s39, 0
	s_mov_b32 m0, s52
	s_nop 0
	global_load_lds_dwordx4 v200, s[40:41]
	s_add_u32 s38, s38, 0x80080
	s_mov_b32 m0, s53
	s_nop 0
	global_load_lds_dwordx4 v203, s[40:41]
	s_addc_u32 s39, s39, 0
	s_mov_b32 m0, s56
	s_nop 0
	global_load_lds_dwordx4 v200, s[38:39]
	s_nop 0
	s_mov_b32 m0, s57
	s_nop 0
	global_load_lds_dwordx4 v203, s[38:39]
	s_mov_b32 m0, s54
	s_nop 0
	global_load_lds_dwordx4 v179, s[36:37]
	s_nop 0
	s_mov_b32 m0, s55
	s_nop 0
	global_load_lds_dwordx4 v201, s[36:37]
	s_waitcnt vmcnt(8)
	s_waitcnt lgkmcnt(0)
	s_barrier
	s_setprio 1
	v_mfma_f32_16x16x32_bf16 v[62:65], v[110:113], v[162:165], v[62:65]
	v_mfma_f32_16x16x32_bf16 v[46:49], v[110:113], v[170:173], v[46:49]
	v_mfma_f32_16x16x32_bf16 v[30:33], v[110:113], v[188:191], v[30:33]
	v_mfma_f32_16x16x32_bf16 v[14:17], v[110:113], v[196:199], v[14:17]
	v_mfma_f32_16x16x32_bf16 v[10:13], v[130:133], v[196:199], v[10:13]
	v_mfma_f32_16x16x32_bf16 v[26:29], v[130:133], v[188:191], v[26:29]
	v_mfma_f32_16x16x32_bf16 v[42:45], v[130:133], v[170:173], v[42:45]
	v_mfma_f32_16x16x32_bf16 v[58:61], v[130:133], v[162:165], v[58:61]
	v_mfma_f32_16x16x32_bf16 v[58:61], v[142:145], v[166:169], v[58:61]
	v_mfma_f32_16x16x32_bf16 v[42:45], v[142:145], v[174:177], v[42:45]
	v_mfma_f32_16x16x32_bf16 v[26:29], v[142:145], v[192:195], v[26:29]
	v_mfma_f32_16x16x32_bf16 v[10:13], v[142:145], v[212:215], v[10:13]
	v_mfma_f32_16x16x32_bf16 v[14:17], v[126:129], v[212:215], v[14:17]
	v_mfma_f32_16x16x32_bf16 v[30:33], v[126:129], v[192:195], v[30:33]
	v_mfma_f32_16x16x32_bf16 v[46:49], v[126:129], v[174:177], v[46:49]
	v_mfma_f32_16x16x32_bf16 v[62:65], v[126:129], v[166:169], v[62:65]
	v_mfma_f32_16x16x32_bf16 v[54:57], v[146:149], v[162:165], v[54:57]
	v_mfma_f32_16x16x32_bf16 v[38:41], v[146:149], v[170:173], v[38:41]
	v_mfma_f32_16x16x32_bf16 v[22:25], v[146:149], v[188:191], v[22:25]
	v_mfma_f32_16x16x32_bf16 v[6:9], v[146:149], v[196:199], v[6:9]
	v_mfma_f32_16x16x32_bf16 v[2:5], v[154:157], v[196:199], v[2:5]
	v_mfma_f32_16x16x32_bf16 v[18:21], v[154:157], v[188:191], v[18:21]
	v_mfma_f32_16x16x32_bf16 v[34:37], v[154:157], v[170:173], v[34:37]
	v_mfma_f32_16x16x32_bf16 v[50:53], v[154:157], v[162:165], v[50:53]
	v_mfma_f32_16x16x32_bf16 v[50:53], v[158:161], v[166:169], v[50:53]
	v_mfma_f32_16x16x32_bf16 v[34:37], v[158:161], v[174:177], v[34:37]
	v_mfma_f32_16x16x32_bf16 v[18:21], v[158:161], v[192:195], v[18:21]
	v_mfma_f32_16x16x32_bf16 v[2:5], v[158:161], v[212:215], v[2:5]
	v_mfma_f32_16x16x32_bf16 v[6:9], v[150:153], v[212:215], v[6:9]
	v_mfma_f32_16x16x32_bf16 v[22:25], v[150:153], v[192:195], v[22:25]
	v_mfma_f32_16x16x32_bf16 v[38:41], v[150:153], v[174:177], v[38:41]
	v_mfma_f32_16x16x32_bf16 v[54:57], v[150:153], v[166:169], v[54:57]
	s_setprio 0
	s_barrier
	s_add_i32 s63, s63, 2
	s_add_u32 s19, s19, 0x100
	s_addc_u32 s27, s27, 0
	s_add_u32 s61, s61, 0x100
	s_addc_u32 s62, s62, 0
	s_add_u32 s34, s34, 0x100
	s_addc_u32 s35, s35, 0
	s_cmp_gt_u32 s63, 29
	s_cbranch_scc0 .LBB0_1137
	s_and_b64 vcc, exec, s[16:17]
	s_cbranch_vccz .LBB0_1140
	s_barrier

; #define PG8_STAGE(bufoff, gbase, voff) do { _Pragma("unroll") for (int _i = 0; _i < 2; ++_i) { unsigned keep_; \
;         asm volatile("s_mov_b32 %0, m0\n\ts_mov_b32 m0, %3\n\ts_nop 0\n\tglobal_load_lds_dwordx4 %1, %2\n\ts_mov_b32 m0, %0" \
;             : "=&s"(keep_) : "v"((voff)[_i]), "s"((const void*)(gbase)), "s"(ldsb0 + (unsigned)(bufoff) + (unsigned)(_i * 8192)) : "memory"); } } while (0)
; #define PG8_LDA(dst, b, h) do { _Pragma("unroll") for (int m = 0; m < 4; ++m) _Pragma("unroll") for (int k = 0; k < 2; ++k) dst[m][k] = *(const LAS bf16x8*)(lds + PG8_SA(b, h) + aoff + m * 2048 + k * 1024); } while (0)
; #define PG8_LDB(dst, b, h) do { _Pragma("unroll") for (int n = 0; n < 2; ++n) _Pragma("unroll") for (int k = 0; k < 2; ++k) dst[n][k] = *(const LAS bf16x8*)(lds + PG8_SB(b, h) + boff + n * 2048 + k * 1024); } while (0)
; #define PG8_MMA(ai, bj, At, Bt) do { __builtin_amdgcn_s_setprio(1); _Pragma("unroll") for (int m = 0; m < 4; ++m) _Pragma("unroll") for (int n = 0; n < 2; ++n) _Pragma("unroll") for (int k = 0; k < 2; ++k) \
;         acc[ai][bj][m][n] = __builtin_amdgcn_mfma_f32_16x16x32_bf16(Bt[n][k], At[m][k], acc[ai][bj][m][n], 0, 0, 0); __builtin_amdgcn_s_setprio(0); } while (0)
; #define PG8_WAIT_V(n) asm volatile("s_waitcnt vmcnt(" #n ")" ::: "memory")
; #define PG8_BAR __builtin_amdgcn_s_barrier()
; template <class Epi, class Sched, bool ALIGN_EPI>
; __device__ __forceinline__ void gemm_phase(LAS unsigned char* lds, const Gemm g, const Sched& S, const Epi& E) {
;     ...
;         for (int t = 0; t < nt; t += 2) {
;             const bool last = (t == nt - 2);
;             const char* a1 = cA + (size_t)(t + 1) * kstep;
;             const char* a2 = last ? nA : cA + (size_t)(t + 2) * kstep; const char* b2 = last ? nB : cB + (size_t)(t + 2) * kstep;
;             const char* a3 = a2 + kstep; const char* b3 = b2 + kstep;
;             PG8_LDB(B0, 0, 0); PG8_LDB(B1, 0, 1); PG8_SCHED; PG8_LDA(At, 0, 0); PG8_STAGE(PG8_SA(1, 1), a1 + hstepA, voffA);
;             PG8_WAIT_V(8); PG8_WAIT_L(0); PG8_BAR; PG8_MMA(0, 0, At, B0); PG8_MMA(0, 1, At, B1); PG8_BAR; PG8_SCHED;
;             PG8_LDA(At, 0, 1); PG8_STAGE(PG8_SB(0, 0), b2, voffB); PG8_STAGE(PG8_SB(0, 1), b2 + hstepB, voffB); PG8_STAGE(PG8_SA(0, 0), a2, voffA);
;             PG8_WAIT_V(8); PG8_WAIT_L(0); PG8_BAR; PG8_MMA(1, 0, At, B0); PG8_MMA(1, 1, At, B1); PG8_BAR; PG8_SCHED;
.LBB0_1218:
	ds_read_b128 v[154:157], v141
	ds_read_b128 v[158:161], v141 offset:1024
	ds_read_b128 v[162:165], v141 offset:2048
	ds_read_b128 v[166:169], v141 offset:3072
	ds_read_b128 v[170:173], v142
	ds_read_b128 v[174:177], v142 offset:1024
	ds_read_b128 v[180:183], v142 offset:2048
	ds_read_b128 v[184:187], v142 offset:3072
	s_add_u32 s36, s34, 0x100
	s_addc_u32 s37, s35, 0
	s_cmp_eq_u32 s64, 28
	s_cselect_b32 s42, s5, s36
	s_cselect_b32 s43, s3, s37
	s_cselect_b32 s40, s7, s19
	s_cselect_b32 s41, s6, s27
	s_add_u32 s38, s42, 0x80
	s_addc_u32 s39, s43, 0
	ds_read_b128 v[188:191], v143
	ds_read_b128 v[192:195], v143 offset:1024
	ds_read_b128 v[196:199], v143 offset:2048
	ds_read_b128 v[204:207], v143 offset:3072
	ds_read_b128 v[208:211], v143 offset:4096
	ds_read_b128 v[212:215], v143 offset:5120
	ds_read_b128 v[216:219], v143 offset:6144
	ds_read_b128 v[220:223], v143 offset:7168
	s_add_u32 s34, s34, 0x80080
	s_addc_u32 s35, s35, 0
	s_mov_b32 m0, s61
	s_nop 0
	global_load_lds_dwordx4 v134, s[34:35]
	s_nop 0
	s_mov_b32 m0, s62
	s_nop 0
	global_load_lds_dwordx4 v136, s[34:35]
	s_waitcnt vmcnt(8)
	s_waitcnt lgkmcnt(0)
	s_barrier
	s_setprio 1
	v_mfma_f32_16x16x32_bf16 v[126:129], v[154:157], v[188:191], v[126:129]
	v_mfma_f32_16x16x32_bf16 v[110:113], v[154:157], v[196:199], v[110:113]
	v_mfma_f32_16x16x32_bf16 v[94:97], v[154:157], v[208:211], v[94:97]
	v_mfma_f32_16x16x32_bf16 v[78:81], v[154:157], v[216:219], v[78:81]
	v_mfma_f32_16x16x32_bf16 v[74:77], v[162:165], v[216:219], v[74:77]
	v_mfma_f32_16x16x32_bf16 v[90:93], v[162:165], v[208:211], v[90:93]
	v_mfma_f32_16x16x32_bf16 v[106:109], v[162:165], v[196:199], v[106:109]
	v_mfma_f32_16x16x32_bf16 v[122:125], v[162:165], v[188:191], v[122:125]
	v_mfma_f32_16x16x32_bf16 v[122:125], v[166:169], v[192:195], v[122:125]
	v_mfma_f32_16x16x32_bf16 v[106:109], v[166:169], v[204:207], v[106:109]
	v_mfma_f32_16x16x32_bf16 v[90:93], v[166:169], v[212:215], v[90:93]
	v_mfma_f32_16x16x32_bf16 v[74:77], v[166:169], v[220:223], v[74:77]
	v_mfma_f32_16x16x32_bf16 v[78:81], v[158:161], v[220:223], v[78:81]
	v_mfma_f32_16x16x32_bf16 v[94:97], v[158:161], v[212:215], v[94:97]
	v_mfma_f32_16x16x32_bf16 v[110:113], v[158:161], v[204:207], v[110:113]
	v_mfma_f32_16x16x32_bf16 v[126:129], v[158:161], v[192:195], v[126:129]
	v_mfma_f32_16x16x32_bf16 v[118:121], v[170:173], v[188:191], v[118:121]
	v_mfma_f32_16x16x32_bf16 v[102:105], v[170:173], v[196:199], v[102:105]
	v_mfma_f32_16x16x32_bf16 v[86:89], v[170:173], v[208:211], v[86:89]
	v_mfma_f32_16x16x32_bf16 v[70:73], v[170:173], v[216:219], v[70:73]
	v_mfma_f32_16x16x32_bf16 v[66:69], v[180:183], v[216:219], v[66:69]
	v_mfma_f32_16x16x32_bf16 v[82:85], v[180:183], v[208:211], v[82:85]
	v_mfma_f32_16x16x32_bf16 v[98:101], v[180:183], v[196:199], v[98:101]
	v_mfma_f32_16x16x32_bf16 v[114:117], v[180:183], v[188:191], v[114:117]
	v_mfma_f32_16x16x32_bf16 v[114:117], v[184:187], v[192:195], v[114:117]
	v_mfma_f32_16x16x32_bf16 v[98:101], v[184:187], v[204:207], v[98:101]
	v_mfma_f32_16x16x32_bf16 v[82:85], v[184:187], v[212:215], v[82:85]
	v_mfma_f32_16x16x32_bf16 v[66:69], v[184:187], v[220:223], v[66:69]
	v_mfma_f32_16x16x32_bf16 v[70:73], v[174:177], v[220:223], v[70:73]
	v_mfma_f32_16x16x32_bf16 v[86:89], v[174:177], v[212:215], v[86:89]
	v_mfma_f32_16x16x32_bf16 v[102:105], v[174:177], v[204:207], v[102:105]
	v_mfma_f32_16x16x32_bf16 v[118:121], v[174:177], v[192:195], v[118:121]
	s_setprio 0
	s_barrier
	ds_read_b128 v[188:191], v143 offset:16384
	ds_read_b128 v[192:195], v143 offset:17408
	ds_read_b128 v[196:199], v143 offset:18432
	ds_read_b128 v[204:207], v143 offset:19456
	ds_read_b128 v[208:211], v143 offset:20480
	ds_read_b128 v[212:215], v143 offset:21504
	ds_read_b128 v[216:219], v143 offset:22528
	ds_read_b128 v[220:223], v143 offset:23552
	s_mov_b32 m0, s47
	s_nop 0
	global_load_lds_dwordx4 v135, s[40:41]
	s_nop 0
	s_mov_b32 m0, s48
	s_nop 0
	global_load_lds_dwordx4 v137, s[40:41]
	s_add_u32 s34, s40, 0x80000
	s_addc_u32 s35, s41, 0
	s_mov_b32 m0, s49
	s_nop 0
	global_load_lds_dwordx4 v135, s[34:35]
	s_nop 0
	s_mov_b32 m0, s50
	s_nop 0
	global_load_lds_dwordx4 v137, s[34:35]
	s_mov_b32 m0, s45
	s_nop 0
	global_load_lds_dwordx4 v134, s[42:43]
	s_nop 0
	s_mov_b32 m0, s51
	s_nop 0
	global_load_lds_dwordx4 v136, s[42:43]
	s_waitcnt vmcnt(8)
	s_waitcnt lgkmcnt(0)
	s_barrier
	s_setprio 1
	v_mfma_f32_16x16x32_bf16 v[62:65], v[154:157], v[188:191], v[62:65]
	v_mfma_f32_16x16x32_bf16 v[46:49], v[154:157], v[196:199], v[46:49]
	v_mfma_f32_16x16x32_bf16 v[30:33], v[154:157], v[208:211], v[30:33]
	v_mfma_f32_16x16x32_bf16 v[14:17], v[154:157], v[216:219], v[14:17]
	v_mfma_f32_16x16x32_bf16 v[10:13], v[162:165], v[216:219], v[10:13]
	v_mfma_f32_16x16x32_bf16 v[26:29], v[162:165], v[208:211], v[26:29]
	v_mfma_f32_16x16x32_bf16 v[42:45], v[162:165], v[196:199], v[42:45]
	v_mfma_f32_16x16x32_bf16 v[58:61], v[162:165], v[188:191], v[58:61]
	v_mfma_f32_16x16x32_bf16 v[58:61], v[166:169], v[192:195], v[58:61]
	v_mfma_f32_16x16x32_bf16 v[42:45], v[166:169], v[204:207], v[42:45]
	v_mfma_f32_16x16x32_bf16 v[26:29], v[166:169], v[212:215], v[26:29]
	v_mfma_f32_16x16x32_bf16 v[10:13], v[166:169], v[220:223], v[10:13]
	v_mfma_f32_16x16x32_bf16 v[14:17], v[158:161], v[220:223], v[14:17]
	v_mfma_f32_16x16x32_bf16 v[30:33], v[158:161], v[212:215], v[30:33]
	v_mfma_f32_16x16x32_bf16 v[46:49], v[158:161], v[204:207], v[46:49]
	v_mfma_f32_16x16x32_bf16 v[62:65], v[158:161], v[192:195], v[62:65]
	v_mfma_f32_16x16x32_bf16 v[54:57], v[170:173], v[188:191], v[54:57]
	v_mfma_f32_16x16x32_bf16 v[38:41], v[170:173], v[196:199], v[38:41]
	v_mfma_f32_16x16x32_bf16 v[22:25], v[170:173], v[208:211], v[22:25]
	v_mfma_f32_16x16x32_bf16 v[6:9], v[170:173], v[216:219], v[6:9]
	v_mfma_f32_16x16x32_bf16 v[2:5], v[180:183], v[216:219], v[2:5]
	v_mfma_f32_16x16x32_bf16 v[18:21], v[180:183], v[208:211], v[18:21]
	v_mfma_f32_16x16x32_bf16 v[34:37], v[180:183], v[196:199], v[34:37]
	v_mfma_f32_16x16x32_bf16 v[50:53], v[180:183], v[188:191], v[50:53]
	v_mfma_f32_16x16x32_bf16 v[50:53], v[184:187], v[192:195], v[50:53]
	v_mfma_f32_16x16x32_bf16 v[34:37], v[184:187], v[204:207], v[34:37]
	v_mfma_f32_16x16x32_bf16 v[18:21], v[184:187], v[212:215], v[18:21]
	v_mfma_f32_16x16x32_bf16 v[2:5], v[184:187], v[220:223], v[2:5]
	v_mfma_f32_16x16x32_bf16 v[6:9], v[174:177], v[220:223], v[6:9]
	v_mfma_f32_16x16x32_bf16 v[22:25], v[174:177], v[212:215], v[22:25]
	v_mfma_f32_16x16x32_bf16 v[38:41], v[174:177], v[204:207], v[38:41]
	v_mfma_f32_16x16x32_bf16 v[54:57], v[174:177], v[192:195], v[54:57]
	s_setprio 0
	s_barrier
; #define PG8_STAGE(bufoff, gbase, voff) do { _Pragma("unroll") for (int _i = 0; _i < 2; ++_i) { unsigned keep_; \
;         asm volatile("s_mov_b32 %0, m0\n\ts_mov_b32 m0, %3\n\ts_nop 0\n\tglobal_load_lds_dwordx4 %1, %2\n\ts_mov_b32 m0, %0" \
;             : "=&s"(keep_) : "v"((voff)[_i]), "s"((const void*)(gbase)), "s"(ldsb0 + (unsigned)(bufoff) + (unsigned)(_i * 8192)) : "memory"); } } while (0)
; #define PG8_LDA(dst, b, h) do { _Pragma("unroll") for (int m = 0; m < 4; ++m) _Pragma("unroll") for (int k = 0; k < 2; ++k) dst[m][k] = *(const LAS bf16x8*)(lds + PG8_SA(b, h) + aoff + m * 2048 + k * 1024); } while (0)
; #define PG8_LDB(dst, b, h) do { _Pragma("unroll") for (int n = 0; n < 2; ++n) _Pragma("unroll") for (int k = 0; k < 2; ++k) dst[n][k] = *(const LAS bf16x8*)(lds + PG8_SB(b, h) + boff + n * 2048 + k * 1024); } while (0)
; #define PG8_MMA(ai, bj, At, Bt) do { __builtin_amdgcn_s_setprio(1); _Pragma("unroll") for (int m = 0; m < 4; ++m) _Pragma("unroll") for (int n = 0; n < 2; ++n) _Pragma("unroll") for (int k = 0; k < 2; ++k) \
;         acc[ai][bj][m][n] = __builtin_amdgcn_mfma_f32_16x16x32_bf16(Bt[n][k], At[m][k], acc[ai][bj][m][n], 0, 0, 0); __builtin_amdgcn_s_setprio(0); } while (0)
; #define PG8_WAIT_V(n) asm volatile("s_waitcnt vmcnt(" #n ")" ::: "memory")
; #define PG8_WAIT_L(n) asm volatile("s_waitcnt lgkmcnt(" #n ")" ::: "memory")
; #define PG8_BAR __builtin_amdgcn_s_barrier()
; #define PG8_SCHED __builtin_amdgcn_sched_barrier(0)
; template <class Epi, class Sched, bool ALIGN_EPI>
; __device__ __forceinline__ void gemm_phase(LAS unsigned char* lds, const Gemm g, const Sched& S, const Epi& E) {
;     ...
;             PG8_LDB(B0, 1, 0); PG8_LDB(B1, 1, 1); PG8_SCHED; PG8_LDA(At, 1, 0); PG8_STAGE(PG8_SA(0, 1), a2 + hstepA, voffA);
;             PG8_WAIT_V(8); PG8_WAIT_L(0); PG8_BAR; PG8_MMA(0, 0, At, B0); PG8_MMA(0, 1, At, B1); PG8_BAR; PG8_SCHED;
;             PG8_LDA(At, 1, 1); PG8_STAGE(PG8_SB(1, 0), b3, voffB); PG8_STAGE(PG8_SB(1, 1), b3 + hstepB, voffB); PG8_STAGE(PG8_SA(1, 0), a3, voffA);
;             PG8_WAIT_V(8); PG8_WAIT_L(0); PG8_BAR; PG8_MMA(1, 0, At, B0); PG8_MMA(1, 1, At, B1); PG8_BAR; PG8_SCHED;
;         }
;         if constexpr (ALIGN_EPI) { if (wr == 0) PG8_BAR; }
	ds_read_b128 v[154:157], v144
	ds_read_b128 v[158:161], v144 offset:1024
	ds_read_b128 v[162:165], v144 offset:2048
	ds_read_b128 v[166:169], v144 offset:3072
	ds_read_b128 v[170:173], v145
	ds_read_b128 v[174:177], v145 offset:1024
	ds_read_b128 v[180:183], v145 offset:2048
	ds_read_b128 v[184:187], v145 offset:3072
	ds_read_b128 v[188:191], v143 offset:32768
	ds_read_b128 v[192:195], v143 offset:33792
	ds_read_b128 v[196:199], v143 offset:34816
	ds_read_b128 v[204:207], v143 offset:35840
	ds_read_b128 v[208:211], v143 offset:36864
	ds_read_b128 v[212:215], v143 offset:37888
	ds_read_b128 v[216:219], v143 offset:38912
	ds_read_b128 v[220:223], v143 offset:39936
	s_add_u32 s34, s42, 0x80000
	s_addc_u32 s35, s43, 0
	s_mov_b32 m0, s52
	s_nop 0
	global_load_lds_dwordx4 v134, s[34:35]
	s_nop 0
	s_mov_b32 m0, s53
	s_nop 0
	global_load_lds_dwordx4 v136, s[34:35]
	s_waitcnt vmcnt(8)
	s_waitcnt lgkmcnt(0)
	s_barrier
	s_setprio 1
	v_mfma_f32_16x16x32_bf16 v[126:129], v[154:157], v[188:191], v[126:129]
	v_mfma_f32_16x16x32_bf16 v[110:113], v[154:157], v[196:199], v[110:113]
	v_mfma_f32_16x16x32_bf16 v[94:97], v[154:157], v[208:211], v[94:97]
	v_mfma_f32_16x16x32_bf16 v[78:81], v[154:157], v[216:219], v[78:81]
	v_mfma_f32_16x16x32_bf16 v[74:77], v[162:165], v[216:219], v[74:77]
	v_mfma_f32_16x16x32_bf16 v[90:93], v[162:165], v[208:211], v[90:93]
	v_mfma_f32_16x16x32_bf16 v[106:109], v[162:165], v[196:199], v[106:109]
	v_mfma_f32_16x16x32_bf16 v[122:125], v[162:165], v[188:191], v[122:125]
	v_mfma_f32_16x16x32_bf16 v[122:125], v[166:169], v[192:195], v[122:125]
	v_mfma_f32_16x16x32_bf16 v[106:109], v[166:169], v[204:207], v[106:109]
	v_mfma_f32_16x16x32_bf16 v[90:93], v[166:169], v[212:215], v[90:93]
	v_mfma_f32_16x16x32_bf16 v[74:77], v[166:169], v[220:223], v[74:77]
	v_mfma_f32_16x16x32_bf16 v[78:81], v[158:161], v[220:223], v[78:81]
	v_mfma_f32_16x16x32_bf16 v[94:97], v[158:161], v[212:215], v[94:97]
	v_mfma_f32_16x16x32_bf16 v[110:113], v[158:161], v[204:207], v[110:113]
	v_mfma_f32_16x16x32_bf16 v[126:129], v[158:161], v[192:195], v[126:129]
	v_mfma_f32_16x16x32_bf16 v[118:121], v[170:173], v[188:191], v[118:121]
	v_mfma_f32_16x16x32_bf16 v[102:105], v[170:173], v[196:199], v[102:105]
	v_mfma_f32_16x16x32_bf16 v[86:89], v[170:173], v[208:211], v[86:89]
	v_mfma_f32_16x16x32_bf16 v[70:73], v[170:173], v[216:219], v[70:73]
	v_mfma_f32_16x16x32_bf16 v[66:69], v[180:183], v[216:219], v[66:69]
	v_mfma_f32_16x16x32_bf16 v[82:85], v[180:183], v[208:211], v[82:85]
	v_mfma_f32_16x16x32_bf16 v[98:101], v[180:183], v[196:199], v[98:101]
	v_mfma_f32_16x16x32_bf16 v[114:117], v[180:183], v[188:191], v[114:117]
	v_mfma_f32_16x16x32_bf16 v[114:117], v[184:187], v[192:195], v[114:117]
	v_mfma_f32_16x16x32_bf16 v[98:101], v[184:187], v[204:207], v[98:101]
	v_mfma_f32_16x16x32_bf16 v[82:85], v[184:187], v[212:215], v[82:85]
	v_mfma_f32_16x16x32_bf16 v[66:69], v[184:187], v[220:223], v[66:69]
	v_mfma_f32_16x16x32_bf16 v[70:73], v[174:177], v[220:223], v[70:73]
	v_mfma_f32_16x16x32_bf16 v[86:89], v[174:177], v[212:215], v[86:89]
	v_mfma_f32_16x16x32_bf16 v[102:105], v[174:177], v[204:207], v[102:105]
	v_mfma_f32_16x16x32_bf16 v[118:121], v[174:177], v[192:195], v[118:121]
	s_setprio 0
	s_barrier
	ds_read_b128 v[188:191], v143 offset:49152
	ds_read_b128 v[192:195], v143 offset:50176
	ds_read_b128 v[196:199], v143 offset:51200
	ds_read_b128 v[204:207], v143 offset:52224
	ds_read_b128 v[208:211], v143 offset:53248
	ds_read_b128 v[212:215], v143 offset:54272
	ds_read_b128 v[216:219], v143 offset:55296
	ds_read_b128 v[220:223], v143 offset:56320
	s_add_u32 s34, s40, 0x80
	s_addc_u32 s35, s41, 0
	s_mov_b32 m0, s54
	s_nop 0
	global_load_lds_dwordx4 v135, s[34:35]
	s_nop 0
	s_mov_b32 m0, s55
	s_nop 0
	global_load_lds_dwordx4 v137, s[34:35]
	s_add_u32 s34, s40, 0x80080
	s_addc_u32 s35, s41, 0
	s_mov_b32 m0, s58
	s_nop 0
	global_load_lds_dwordx4 v135, s[34:35]
	s_nop 0
	s_mov_b32 m0, s59
	s_nop 0
	global_load_lds_dwordx4 v137, s[34:35]
	s_mov_b32 m0, s56
	s_nop 0
	global_load_lds_dwordx4 v134, s[38:39]
	s_nop 0
	s_mov_b32 m0, s57
	s_nop 0
	global_load_lds_dwordx4 v136, s[38:39]
	s_waitcnt vmcnt(8)
	s_waitcnt lgkmcnt(0)
	s_barrier
	s_setprio 1
	v_mfma_f32_16x16x32_bf16 v[62:65], v[154:157], v[188:191], v[62:65]
	v_mfma_f32_16x16x32_bf16 v[46:49], v[154:157], v[196:199], v[46:49]
	v_mfma_f32_16x16x32_bf16 v[30:33], v[154:157], v[208:211], v[30:33]
	v_mfma_f32_16x16x32_bf16 v[14:17], v[154:157], v[216:219], v[14:17]
	v_mfma_f32_16x16x32_bf16 v[10:13], v[162:165], v[216:219], v[10:13]
	v_mfma_f32_16x16x32_bf16 v[26:29], v[162:165], v[208:211], v[26:29]
	v_mfma_f32_16x16x32_bf16 v[42:45], v[162:165], v[196:199], v[42:45]
	v_mfma_f32_16x16x32_bf16 v[58:61], v[162:165], v[188:191], v[58:61]
	v_mfma_f32_16x16x32_bf16 v[58:61], v[166:169], v[192:195], v[58:61]
	v_mfma_f32_16x16x32_bf16 v[42:45], v[166:169], v[204:207], v[42:45]
	v_mfma_f32_16x16x32_bf16 v[26:29], v[166:169], v[212:215], v[26:29]
	v_mfma_f32_16x16x32_bf16 v[10:13], v[166:169], v[220:223], v[10:13]
	v_mfma_f32_16x16x32_bf16 v[14:17], v[158:161], v[220:223], v[14:17]
	v_mfma_f32_16x16x32_bf16 v[30:33], v[158:161], v[212:215], v[30:33]
	v_mfma_f32_16x16x32_bf16 v[46:49], v[158:161], v[204:207], v[46:49]
	v_mfma_f32_16x16x32_bf16 v[62:65], v[158:161], v[192:195], v[62:65]
	v_mfma_f32_16x16x32_bf16 v[54:57], v[170:173], v[188:191], v[54:57]
	v_mfma_f32_16x16x32_bf16 v[38:41], v[170:173], v[196:199], v[38:41]
	v_mfma_f32_16x16x32_bf16 v[22:25], v[170:173], v[208:211], v[22:25]
	v_mfma_f32_16x16x32_bf16 v[6:9], v[170:173], v[216:219], v[6:9]
	v_mfma_f32_16x16x32_bf16 v[2:5], v[180:183], v[216:219], v[2:5]
	v_mfma_f32_16x16x32_bf16 v[18:21], v[180:183], v[208:211], v[18:21]
	v_mfma_f32_16x16x32_bf16 v[34:37], v[180:183], v[196:199], v[34:37]
	v_mfma_f32_16x16x32_bf16 v[50:53], v[180:183], v[188:191], v[50:53]
	v_mfma_f32_16x16x32_bf16 v[50:53], v[184:187], v[192:195], v[50:53]
	v_mfma_f32_16x16x32_bf16 v[34:37], v[184:187], v[204:207], v[34:37]
	v_mfma_f32_16x16x32_bf16 v[18:21], v[184:187], v[212:215], v[18:21]
	v_mfma_f32_16x16x32_bf16 v[2:5], v[184:187], v[220:223], v[2:5]
	v_mfma_f32_16x16x32_bf16 v[6:9], v[174:177], v[220:223], v[6:9]
	v_mfma_f32_16x16x32_bf16 v[22:25], v[174:177], v[212:215], v[22:25]
	v_mfma_f32_16x16x32_bf16 v[38:41], v[174:177], v[204:207], v[38:41]
	v_mfma_f32_16x16x32_bf16 v[54:57], v[174:177], v[192:195], v[54:57]
	s_setprio 0
	s_barrier
	s_add_i32 s64, s64, 2
	s_add_u32 s19, s19, 0x100
	s_addc_u32 s27, s27, 0
	s_cmp_gt_u32 s64, 29
	s_mov_b64 s[34:35], s[36:37]
	s_cbranch_scc0 .LBB0_1218
	s_and_b64 vcc, exec, s[16:17]
	s_cbranch_vccz .LBB0_1221
	s_barrier

; #define PG8_STAGE(bufoff, gbase, voff) do { _Pragma("unroll") for (int _i = 0; _i < 2; ++_i) { unsigned keep_; \
;         asm volatile("s_mov_b32 %0, m0\n\ts_mov_b32 m0, %3\n\ts_nop 0\n\tglobal_load_lds_dwordx4 %1, %2\n\ts_mov_b32 m0, %0" \
;             : "=&s"(keep_) : "v"((voff)[_i]), "s"((const void*)(gbase)), "s"(ldsb0 + (unsigned)(bufoff) + (unsigned)(_i * 8192)) : "memory"); } } while (0)
; #define PG8_LDA(dst, b, h) do { _Pragma("unroll") for (int m = 0; m < 4; ++m) _Pragma("unroll") for (int k = 0; k < 2; ++k) dst[m][k] = *(const LAS bf16x8*)(lds + PG8_SA(b, h) + aoff + m * 2048 + k * 1024); } while (0)
; #define PG8_LDB(dst, b, h) do { _Pragma("unroll") for (int n = 0; n < 2; ++n) _Pragma("unroll") for (int k = 0; k < 2; ++k) dst[n][k] = *(const LAS bf16x8*)(lds + PG8_SB(b, h) + boff + n * 2048 + k * 1024); } while (0)
; #define PG8_MMA(ai, bj, At, Bt) do { __builtin_amdgcn_s_setprio(1); _Pragma("unroll") for (int m = 0; m < 4; ++m) _Pragma("unroll") for (int n = 0; n < 2; ++n) _Pragma("unroll") for (int k = 0; k < 2; ++k) \
;         acc[ai][bj][m][n] = __builtin_amdgcn_mfma_f32_16x16x32_bf16(Bt[n][k], At[m][k], acc[ai][bj][m][n], 0, 0, 0); __builtin_amdgcn_s_setprio(0); } while (0)
; #define PG8_WAIT_V(n) asm volatile("s_waitcnt vmcnt(" #n ")" ::: "memory")
; #define PG8_BAR __builtin_amdgcn_s_barrier()
; template <class Epi, class Sched, bool ALIGN_EPI>
; __device__ __forceinline__ void gemm_phase(LAS unsigned char* lds, const Gemm g, const Sched& S, const Epi& E) {
;     ...
;         for (int t = 0; t < nt; t += 2) {
;             const bool last = (t == nt - 2);
;             const char* a1 = cA + (size_t)(t + 1) * kstep;
;             const char* a2 = last ? nA : cA + (size_t)(t + 2) * kstep; const char* b2 = last ? nB : cB + (size_t)(t + 2) * kstep;
;             const char* a3 = a2 + kstep; const char* b3 = b2 + kstep;
;             PG8_LDB(B0, 0, 0); PG8_LDB(B1, 0, 1); PG8_SCHED; PG8_LDA(At, 0, 0); PG8_STAGE(PG8_SA(1, 1), a1 + hstepA, voffA);
;             PG8_WAIT_V(8); PG8_WAIT_L(0); PG8_BAR; PG8_MMA(0, 0, At, B0); PG8_MMA(0, 1, At, B1); PG8_BAR; PG8_SCHED;
;             PG8_LDA(At, 0, 1); PG8_STAGE(PG8_SB(0, 0), b2, voffB); PG8_STAGE(PG8_SB(0, 1), b2 + hstepB, voffB); PG8_STAGE(PG8_SA(0, 0), a2, voffA);
;             PG8_WAIT_V(8); PG8_WAIT_L(0); PG8_BAR; PG8_MMA(1, 0, At, B0); PG8_MMA(1, 1, At, B1); PG8_BAR; PG8_SCHED;
.LBB0_1317:
	ds_read_b128 v[110:113], v206
	ds_read_b128 v[126:129], v206 offset:1024
	ds_read_b128 v[130:133], v206 offset:2048
	ds_read_b128 v[142:145], v206 offset:3072
	ds_read_b128 v[146:149], v207
	ds_read_b128 v[150:153], v207 offset:1024
	ds_read_b128 v[154:157], v207 offset:2048
	ds_read_b128 v[158:161], v207 offset:3072
	s_cmpk_eq_i32 s58, 0x54
	s_cselect_b32 s34, s14, s6
	s_cselect_b32 s35, s15, s7
	s_cselect_b32 s30, s26, s56
	s_cselect_b32 s31, s27, s57
	s_add_u32 s28, s34, 0x80
	s_addc_u32 s29, s35, 0
	ds_read_b128 v[162:165], v208
	ds_read_b128 v[166:169], v208 offset:1024
	ds_read_b128 v[170:173], v208 offset:2048
	ds_read_b128 v[174:177], v208 offset:3072
	ds_read_b128 v[188:191], v208 offset:4096
	ds_read_b128 v[192:195], v208 offset:5120
	ds_read_b128 v[196:199], v208 offset:6144
	ds_read_b128 v[212:215], v208 offset:7168
	s_mov_b32 m0, s52
	s_nop 0
	global_load_lds_dwordx4 v179, s[4:5]
	s_nop 0
	s_mov_b32 m0, s53
	s_nop 0
	global_load_lds_dwordx4 v201, s[4:5]
	s_waitcnt vmcnt(8)
	s_waitcnt lgkmcnt(0)
	s_barrier
	s_setprio 1
	v_mfma_f32_16x16x32_bf16 v[138:141], v[110:113], v[162:165], v[138:141]
	v_mfma_f32_16x16x32_bf16 v[114:117], v[110:113], v[170:173], v[114:117]
	v_mfma_f32_16x16x32_bf16 v[94:97], v[110:113], v[188:191], v[94:97]
	v_mfma_f32_16x16x32_bf16 v[78:81], v[110:113], v[196:199], v[78:81]
	v_mfma_f32_16x16x32_bf16 v[74:77], v[130:133], v[196:199], v[74:77]
	v_mfma_f32_16x16x32_bf16 v[90:93], v[130:133], v[188:191], v[90:93]
	v_mfma_f32_16x16x32_bf16 v[106:109], v[130:133], v[170:173], v[106:109]
	v_mfma_f32_16x16x32_bf16 v[134:137], v[130:133], v[162:165], v[134:137]
	v_mfma_f32_16x16x32_bf16 v[134:137], v[142:145], v[166:169], v[134:137]
	v_mfma_f32_16x16x32_bf16 v[106:109], v[142:145], v[174:177], v[106:109]
	v_mfma_f32_16x16x32_bf16 v[90:93], v[142:145], v[192:195], v[90:93]
	v_mfma_f32_16x16x32_bf16 v[74:77], v[142:145], v[212:215], v[74:77]
	v_mfma_f32_16x16x32_bf16 v[78:81], v[126:129], v[212:215], v[78:81]
	v_mfma_f32_16x16x32_bf16 v[94:97], v[126:129], v[192:195], v[94:97]
	v_mfma_f32_16x16x32_bf16 v[114:117], v[126:129], v[174:177], v[114:117]
	v_mfma_f32_16x16x32_bf16 v[138:141], v[126:129], v[166:169], v[138:141]
	v_mfma_f32_16x16x32_bf16 v[122:125], v[146:149], v[162:165], v[122:125]
	v_mfma_f32_16x16x32_bf16 v[102:105], v[146:149], v[170:173], v[102:105]
	v_mfma_f32_16x16x32_bf16 v[86:89], v[146:149], v[188:191], v[86:89]
	v_mfma_f32_16x16x32_bf16 v[70:73], v[146:149], v[196:199], v[70:73]
	v_mfma_f32_16x16x32_bf16 v[66:69], v[154:157], v[196:199], v[66:69]
	v_mfma_f32_16x16x32_bf16 v[82:85], v[154:157], v[188:191], v[82:85]
	v_mfma_f32_16x16x32_bf16 v[98:101], v[154:157], v[170:173], v[98:101]
	v_mfma_f32_16x16x32_bf16 v[118:121], v[154:157], v[162:165], v[118:121]
	v_mfma_f32_16x16x32_bf16 v[118:121], v[158:161], v[166:169], v[118:121]
	v_mfma_f32_16x16x32_bf16 v[98:101], v[158:161], v[174:177], v[98:101]
	v_mfma_f32_16x16x32_bf16 v[82:85], v[158:161], v[192:195], v[82:85]
	v_mfma_f32_16x16x32_bf16 v[66:69], v[158:161], v[212:215], v[66:69]
	v_mfma_f32_16x16x32_bf16 v[70:73], v[150:153], v[212:215], v[70:73]
	v_mfma_f32_16x16x32_bf16 v[86:89], v[150:153], v[192:195], v[86:89]
	v_mfma_f32_16x16x32_bf16 v[102:105], v[150:153], v[174:177], v[102:105]
	v_mfma_f32_16x16x32_bf16 v[122:125], v[150:153], v[166:169], v[122:125]
	s_setprio 0
	s_barrier
	ds_read_b128 v[162:165], v208 offset:16384
	ds_read_b128 v[166:169], v208 offset:17408
	ds_read_b128 v[170:173], v208 offset:18432
	ds_read_b128 v[174:177], v208 offset:19456
	ds_read_b128 v[188:191], v208 offset:20480
	ds_read_b128 v[192:195], v208 offset:21504
	ds_read_b128 v[196:199], v208 offset:22528
	ds_read_b128 v[212:215], v208 offset:23552
	s_mov_b32 m0, s39
	s_nop 0
	global_load_lds_dwordx4 v200, s[30:31]
	s_add_u32 s62, s30, 0x160000
	s_mov_b32 m0, s40
	s_nop 0
	global_load_lds_dwordx4 v203, s[30:31]
	s_addc_u32 s63, s31, 0
	s_mov_b32 m0, s41
	s_nop 0
	global_load_lds_dwordx4 v200, s[62:63]
	s_nop 0
	s_mov_b32 m0, s42
	s_nop 0
	global_load_lds_dwordx4 v203, s[62:63]
	s_nop 0
	s_mov_b32 m0, s38
	s_nop 0
	global_load_lds_dwordx4 v179, s[34:35]
	s_nop 0
	s_mov_b32 m0, s43
	s_nop 0
	global_load_lds_dwordx4 v201, s[34:35]
	s_waitcnt vmcnt(8)
	s_waitcnt lgkmcnt(0)
	s_barrier
	s_setprio 1
	v_mfma_f32_16x16x32_bf16 v[62:65], v[110:113], v[162:165], v[62:65]
	v_mfma_f32_16x16x32_bf16 v[46:49], v[110:113], v[170:173], v[46:49]
	v_mfma_f32_16x16x32_bf16 v[30:33], v[110:113], v[188:191], v[30:33]
	v_mfma_f32_16x16x32_bf16 v[14:17], v[110:113], v[196:199], v[14:17]
	v_mfma_f32_16x16x32_bf16 v[10:13], v[130:133], v[196:199], v[10:13]
	v_mfma_f32_16x16x32_bf16 v[26:29], v[130:133], v[188:191], v[26:29]
	v_mfma_f32_16x16x32_bf16 v[42:45], v[130:133], v[170:173], v[42:45]
	v_mfma_f32_16x16x32_bf16 v[58:61], v[130:133], v[162:165], v[58:61]
	v_mfma_f32_16x16x32_bf16 v[58:61], v[142:145], v[166:169], v[58:61]
	v_mfma_f32_16x16x32_bf16 v[42:45], v[142:145], v[174:177], v[42:45]
	v_mfma_f32_16x16x32_bf16 v[26:29], v[142:145], v[192:195], v[26:29]
	v_mfma_f32_16x16x32_bf16 v[10:13], v[142:145], v[212:215], v[10:13]
	v_mfma_f32_16x16x32_bf16 v[14:17], v[126:129], v[212:215], v[14:17]
	v_mfma_f32_16x16x32_bf16 v[30:33], v[126:129], v[192:195], v[30:33]
	v_mfma_f32_16x16x32_bf16 v[46:49], v[126:129], v[174:177], v[46:49]
	v_mfma_f32_16x16x32_bf16 v[62:65], v[126:129], v[166:169], v[62:65]
	v_mfma_f32_16x16x32_bf16 v[54:57], v[146:149], v[162:165], v[54:57]
	v_mfma_f32_16x16x32_bf16 v[38:41], v[146:149], v[170:173], v[38:41]
	v_mfma_f32_16x16x32_bf16 v[22:25], v[146:149], v[188:191], v[22:25]
	v_mfma_f32_16x16x32_bf16 v[6:9], v[146:149], v[196:199], v[6:9]
	v_mfma_f32_16x16x32_bf16 v[2:5], v[154:157], v[196:199], v[2:5]
	v_mfma_f32_16x16x32_bf16 v[18:21], v[154:157], v[188:191], v[18:21]
	v_mfma_f32_16x16x32_bf16 v[34:37], v[154:157], v[170:173], v[34:37]
	v_mfma_f32_16x16x32_bf16 v[50:53], v[154:157], v[162:165], v[50:53]
	v_mfma_f32_16x16x32_bf16 v[50:53], v[158:161], v[166:169], v[50:53]
	v_mfma_f32_16x16x32_bf16 v[34:37], v[158:161], v[174:177], v[34:37]
	v_mfma_f32_16x16x32_bf16 v[18:21], v[158:161], v[192:195], v[18:21]
	v_mfma_f32_16x16x32_bf16 v[2:5], v[158:161], v[212:215], v[2:5]
	v_mfma_f32_16x16x32_bf16 v[6:9], v[150:153], v[212:215], v[6:9]
	v_mfma_f32_16x16x32_bf16 v[22:25], v[150:153], v[192:195], v[22:25]
	v_mfma_f32_16x16x32_bf16 v[38:41], v[150:153], v[174:177], v[38:41]
	v_mfma_f32_16x16x32_bf16 v[54:57], v[150:153], v[166:169], v[54:57]
	s_setprio 0
	s_barrier
; #define PG8_STAGE(bufoff, gbase, voff) do { _Pragma("unroll") for (int _i = 0; _i < 2; ++_i) { unsigned keep_; \
;         asm volatile("s_mov_b32 %0, m0\n\ts_mov_b32 m0, %3\n\ts_nop 0\n\tglobal_load_lds_dwordx4 %1, %2\n\ts_mov_b32 m0, %0" \
;             : "=&s"(keep_) : "v"((voff)[_i]), "s"((const void*)(gbase)), "s"(ldsb0 + (unsigned)(bufoff) + (unsigned)(_i * 8192)) : "memory"); } } while (0)
; #define PG8_LDA(dst, b, h) do { _Pragma("unroll") for (int m = 0; m < 4; ++m) _Pragma("unroll") for (int k = 0; k < 2; ++k) dst[m][k] = *(const LAS bf16x8*)(lds + PG8_SA(b, h) + aoff + m * 2048 + k * 1024); } while (0)
; #define PG8_LDB(dst, b, h) do { _Pragma("unroll") for (int n = 0; n < 2; ++n) _Pragma("unroll") for (int k = 0; k < 2; ++k) dst[n][k] = *(const LAS bf16x8*)(lds + PG8_SB(b, h) + boff + n * 2048 + k * 1024); } while (0)
; #define PG8_MMA(ai, bj, At, Bt) do { __builtin_amdgcn_s_setprio(1); _Pragma("unroll") for (int m = 0; m < 4; ++m) _Pragma("unroll") for (int n = 0; n < 2; ++n) _Pragma("unroll") for (int k = 0; k < 2; ++k) \
;         acc[ai][bj][m][n] = __builtin_amdgcn_mfma_f32_16x16x32_bf16(Bt[n][k], At[m][k], acc[ai][bj][m][n], 0, 0, 0); __builtin_amdgcn_s_setprio(0); } while (0)
; #define PG8_WAIT_V(n) asm volatile("s_waitcnt vmcnt(" #n ")" ::: "memory")
; #define PG8_WAIT_L(n) asm volatile("s_waitcnt lgkmcnt(" #n ")" ::: "memory")
; #define PG8_BAR __builtin_amdgcn_s_barrier()
; #define PG8_SCHED __builtin_amdgcn_sched_barrier(0)
; template <class Epi, class Sched, bool ALIGN_EPI>
; __device__ __forceinline__ void gemm_phase(LAS unsigned char* lds, const Gemm g, const Sched& S, const Epi& E) {
;     ...
;             PG8_LDB(B0, 1, 0); PG8_LDB(B1, 1, 1); PG8_SCHED; PG8_LDA(At, 1, 0); PG8_STAGE(PG8_SA(0, 1), a2 + hstepA, voffA);
;             PG8_WAIT_V(8); PG8_WAIT_L(0); PG8_BAR; PG8_MMA(0, 0, At, B0); PG8_MMA(0, 1, At, B1); PG8_BAR; PG8_SCHED;
;             PG8_LDA(At, 1, 1); PG8_STAGE(PG8_SB(1, 0), b3, voffB); PG8_STAGE(PG8_SB(1, 1), b3 + hstepB, voffB); PG8_STAGE(PG8_SA(1, 0), a3, voffA);
;             PG8_WAIT_V(8); PG8_WAIT_L(0); PG8_BAR; PG8_MMA(1, 0, At, B0); PG8_MMA(1, 1, At, B1); PG8_BAR; PG8_SCHED;
;         }
;         if constexpr (ALIGN_EPI) { if (wr == 0) PG8_BAR; }
	ds_read_b128 v[110:113], v209
	ds_read_b128 v[126:129], v209 offset:1024
	ds_read_b128 v[130:133], v209 offset:2048
	ds_read_b128 v[142:145], v209 offset:3072
	ds_read_b128 v[146:149], v210
	ds_read_b128 v[150:153], v210 offset:1024
	ds_read_b128 v[154:157], v210 offset:2048
	ds_read_b128 v[158:161], v210 offset:3072
	ds_read_b128 v[162:165], v208 offset:32768
	ds_read_b128 v[166:169], v208 offset:33792
	ds_read_b128 v[170:173], v208 offset:34816
	ds_read_b128 v[174:177], v208 offset:35840
	ds_read_b128 v[188:191], v208 offset:36864
	ds_read_b128 v[192:195], v208 offset:37888
	ds_read_b128 v[196:199], v208 offset:38912
	ds_read_b128 v[212:215], v208 offset:39936
	s_add_u32 s34, s34, 0x160000
	s_addc_u32 s35, s35, 0
	s_mov_b32 m0, s44
	s_nop 0
	global_load_lds_dwordx4 v179, s[34:35]
	s_nop 0
	s_mov_b32 m0, s45
	s_nop 0
	global_load_lds_dwordx4 v201, s[34:35]
	s_waitcnt vmcnt(8)
	s_waitcnt lgkmcnt(0)
	s_barrier
	s_setprio 1
	v_mfma_f32_16x16x32_bf16 v[138:141], v[110:113], v[162:165], v[138:141]
	v_mfma_f32_16x16x32_bf16 v[114:117], v[110:113], v[170:173], v[114:117]
	v_mfma_f32_16x16x32_bf16 v[94:97], v[110:113], v[188:191], v[94:97]
	v_mfma_f32_16x16x32_bf16 v[78:81], v[110:113], v[196:199], v[78:81]
	v_mfma_f32_16x16x32_bf16 v[74:77], v[130:133], v[196:199], v[74:77]
	v_mfma_f32_16x16x32_bf16 v[90:93], v[130:133], v[188:191], v[90:93]
	v_mfma_f32_16x16x32_bf16 v[106:109], v[130:133], v[170:173], v[106:109]
	v_mfma_f32_16x16x32_bf16 v[134:137], v[130:133], v[162:165], v[134:137]
	v_mfma_f32_16x16x32_bf16 v[134:137], v[142:145], v[166:169], v[134:137]
	v_mfma_f32_16x16x32_bf16 v[106:109], v[142:145], v[174:177], v[106:109]
	v_mfma_f32_16x16x32_bf16 v[90:93], v[142:145], v[192:195], v[90:93]
	v_mfma_f32_16x16x32_bf16 v[74:77], v[142:145], v[212:215], v[74:77]
	v_mfma_f32_16x16x32_bf16 v[78:81], v[126:129], v[212:215], v[78:81]
	v_mfma_f32_16x16x32_bf16 v[94:97], v[126:129], v[192:195], v[94:97]
	v_mfma_f32_16x16x32_bf16 v[114:117], v[126:129], v[174:177], v[114:117]
	v_mfma_f32_16x16x32_bf16 v[138:141], v[126:129], v[166:169], v[138:141]
	v_mfma_f32_16x16x32_bf16 v[122:125], v[146:149], v[162:165], v[122:125]
	v_mfma_f32_16x16x32_bf16 v[102:105], v[146:149], v[170:173], v[102:105]
	v_mfma_f32_16x16x32_bf16 v[86:89], v[146:149], v[188:191], v[86:89]
	v_mfma_f32_16x16x32_bf16 v[70:73], v[146:149], v[196:199], v[70:73]
	v_mfma_f32_16x16x32_bf16 v[66:69], v[154:157], v[196:199], v[66:69]
	v_mfma_f32_16x16x32_bf16 v[82:85], v[154:157], v[188:191], v[82:85]
	v_mfma_f32_16x16x32_bf16 v[98:101], v[154:157], v[170:173], v[98:101]
	v_mfma_f32_16x16x32_bf16 v[118:121], v[154:157], v[162:165], v[118:121]
	v_mfma_f32_16x16x32_bf16 v[118:121], v[158:161], v[166:169], v[118:121]
	v_mfma_f32_16x16x32_bf16 v[98:101], v[158:161], v[174:177], v[98:101]
	v_mfma_f32_16x16x32_bf16 v[82:85], v[158:161], v[192:195], v[82:85]
	v_mfma_f32_16x16x32_bf16 v[66:69], v[158:161], v[212:215], v[66:69]
	v_mfma_f32_16x16x32_bf16 v[70:73], v[150:153], v[212:215], v[70:73]
	v_mfma_f32_16x16x32_bf16 v[86:89], v[150:153], v[192:195], v[86:89]
	v_mfma_f32_16x16x32_bf16 v[102:105], v[150:153], v[174:177], v[102:105]
	v_mfma_f32_16x16x32_bf16 v[122:125], v[150:153], v[166:169], v[122:125]
	s_setprio 0
	s_barrier
	ds_read_b128 v[162:165], v208 offset:49152
	ds_read_b128 v[166:169], v208 offset:50176
	ds_read_b128 v[170:173], v208 offset:51200
	ds_read_b128 v[174:177], v208 offset:52224
	ds_read_b128 v[188:191], v208 offset:53248
	ds_read_b128 v[192:195], v208 offset:54272
	ds_read_b128 v[196:199], v208 offset:55296
	ds_read_b128 v[212:215], v208 offset:56320
	s_add_u32 s34, s30, 0x80
	s_addc_u32 s35, s31, 0
	s_mov_b32 m0, s46
	s_nop 0
	global_load_lds_dwordx4 v200, s[34:35]
	s_add_u32 s30, s30, 0x160080
	s_mov_b32 m0, s47
	s_nop 0
	global_load_lds_dwordx4 v203, s[34:35]
	s_addc_u32 s31, s31, 0
	s_mov_b32 m0, s50
	s_nop 0
	global_load_lds_dwordx4 v200, s[30:31]
	s_nop 0
	s_mov_b32 m0, s51
	s_nop 0
	global_load_lds_dwordx4 v203, s[30:31]
	s_mov_b32 m0, s48
	s_nop 0
	global_load_lds_dwordx4 v179, s[28:29]
	s_nop 0
	s_mov_b32 m0, s49
	s_nop 0
	global_load_lds_dwordx4 v201, s[28:29]
	s_waitcnt vmcnt(8)
	s_waitcnt lgkmcnt(0)
	s_barrier
	s_setprio 1
	v_mfma_f32_16x16x32_bf16 v[62:65], v[110:113], v[162:165], v[62:65]
	v_mfma_f32_16x16x32_bf16 v[46:49], v[110:113], v[170:173], v[46:49]
	v_mfma_f32_16x16x32_bf16 v[30:33], v[110:113], v[188:191], v[30:33]
	v_mfma_f32_16x16x32_bf16 v[14:17], v[110:113], v[196:199], v[14:17]
	v_mfma_f32_16x16x32_bf16 v[10:13], v[130:133], v[196:199], v[10:13]
	v_mfma_f32_16x16x32_bf16 v[26:29], v[130:133], v[188:191], v[26:29]
	v_mfma_f32_16x16x32_bf16 v[42:45], v[130:133], v[170:173], v[42:45]
	v_mfma_f32_16x16x32_bf16 v[58:61], v[130:133], v[162:165], v[58:61]
	v_mfma_f32_16x16x32_bf16 v[58:61], v[142:145], v[166:169], v[58:61]
	v_mfma_f32_16x16x32_bf16 v[42:45], v[142:145], v[174:177], v[42:45]
	v_mfma_f32_16x16x32_bf16 v[26:29], v[142:145], v[192:195], v[26:29]
	v_mfma_f32_16x16x32_bf16 v[10:13], v[142:145], v[212:215], v[10:13]
	v_mfma_f32_16x16x32_bf16 v[14:17], v[126:129], v[212:215], v[14:17]
	v_mfma_f32_16x16x32_bf16 v[30:33], v[126:129], v[192:195], v[30:33]
	v_mfma_f32_16x16x32_bf16 v[46:49], v[126:129], v[174:177], v[46:49]
	v_mfma_f32_16x16x32_bf16 v[62:65], v[126:129], v[166:169], v[62:65]
	v_mfma_f32_16x16x32_bf16 v[54:57], v[146:149], v[162:165], v[54:57]
	v_mfma_f32_16x16x32_bf16 v[38:41], v[146:149], v[170:173], v[38:41]
	v_mfma_f32_16x16x32_bf16 v[22:25], v[146:149], v[188:191], v[22:25]
	v_mfma_f32_16x16x32_bf16 v[6:9], v[146:149], v[196:199], v[6:9]
	v_mfma_f32_16x16x32_bf16 v[2:5], v[154:157], v[196:199], v[2:5]
	v_mfma_f32_16x16x32_bf16 v[18:21], v[154:157], v[188:191], v[18:21]
	v_mfma_f32_16x16x32_bf16 v[34:37], v[154:157], v[170:173], v[34:37]
	v_mfma_f32_16x16x32_bf16 v[50:53], v[154:157], v[162:165], v[50:53]
	v_mfma_f32_16x16x32_bf16 v[50:53], v[158:161], v[166:169], v[50:53]
	v_mfma_f32_16x16x32_bf16 v[34:37], v[158:161], v[174:177], v[34:37]
	v_mfma_f32_16x16x32_bf16 v[18:21], v[158:161], v[192:195], v[18:21]
	v_mfma_f32_16x16x32_bf16 v[2:5], v[158:161], v[212:215], v[2:5]
	v_mfma_f32_16x16x32_bf16 v[6:9], v[150:153], v[212:215], v[6:9]
	v_mfma_f32_16x16x32_bf16 v[22:25], v[150:153], v[192:195], v[22:25]
	v_mfma_f32_16x16x32_bf16 v[38:41], v[150:153], v[174:177], v[38:41]
	v_mfma_f32_16x16x32_bf16 v[54:57], v[150:153], v[166:169], v[54:57]
	s_setprio 0
	s_barrier
	s_add_i32 s58, s58, 2
	s_add_u32 s6, s6, 0x100
	s_addc_u32 s7, s7, 0
	s_add_u32 s56, s56, 0x100
	s_addc_u32 s57, s57, 0
	s_add_u32 s4, s4, 0x100
	s_addc_u32 s5, s5, 0
	s_cmpk_gt_u32 s58, 0x55
	s_cbranch_scc0 .LBB0_1317
	s_and_b64 vcc, exec, s[18:19]
	s_cbranch_vccz .LBB0_1320
	s_barrier

; #define PG8_STAGE(bufoff, gbase, voff) do { _Pragma("unroll") for (int _i = 0; _i < 2; ++_i) { unsigned keep_; \
;         asm volatile("s_mov_b32 %0, m0\n\ts_mov_b32 m0, %3\n\ts_nop 0\n\tglobal_load_lds_dwordx4 %1, %2\n\ts_mov_b32 m0, %0" \
;             : "=&s"(keep_) : "v"((voff)[_i]), "s"((const void*)(gbase)), "s"(ldsb0 + (unsigned)(bufoff) + (unsigned)(_i * 8192)) : "memory"); } } while (0)
; #define PG8_LDA(dst, b, h) do { _Pragma("unroll") for (int m = 0; m < 4; ++m) _Pragma("unroll") for (int k = 0; k < 2; ++k) dst[m][k] = *(const LAS bf16x8*)(lds + PG8_SA(b, h) + aoff + m * 2048 + k * 1024); } while (0)
; #define PG8_LDB(dst, b, h) do { _Pragma("unroll") for (int n = 0; n < 2; ++n) _Pragma("unroll") for (int k = 0; k < 2; ++k) dst[n][k] = *(const LAS bf16x8*)(lds + PG8_SB(b, h) + boff + n * 2048 + k * 1024); } while (0)
; #define PG8_MMA(ai, bj, At, Bt) do { __builtin_amdgcn_s_setprio(1); _Pragma("unroll") for (int m = 0; m < 4; ++m) _Pragma("unroll") for (int n = 0; n < 2; ++n) _Pragma("unroll") for (int k = 0; k < 2; ++k) \
;         acc[ai][bj][m][n] = __builtin_amdgcn_mfma_f32_16x16x32_bf16(Bt[n][k], At[m][k], acc[ai][bj][m][n], 0, 0, 0); __builtin_amdgcn_s_setprio(0); } while (0)
; #define PG8_WAIT_V(n) asm volatile("s_waitcnt vmcnt(" #n ")" ::: "memory")
; #define PG8_BAR __builtin_amdgcn_s_barrier()
; template <class Epi, class Sched, bool ALIGN_EPI>
; __device__ __forceinline__ void gemm_phase(LAS unsigned char* lds, const Gemm g, const Sched& S, const Epi& E) {
;     ...
;         for (int t = 0; t < nt; t += 2) {
;             const bool last = (t == nt - 2);
;             const char* a1 = cA + (size_t)(t + 1) * kstep;
;             const char* a2 = last ? nA : cA + (size_t)(t + 2) * kstep; const char* b2 = last ? nB : cB + (size_t)(t + 2) * kstep;
;             const char* a3 = a2 + kstep; const char* b3 = b2 + kstep;
;             PG8_LDB(B0, 0, 0); PG8_LDB(B1, 0, 1); PG8_SCHED; PG8_LDA(At, 0, 0); PG8_STAGE(PG8_SA(1, 1), a1 + hstepA, voffA);
;             PG8_WAIT_V(8); PG8_WAIT_L(0); PG8_BAR; PG8_MMA(0, 0, At, B0); PG8_MMA(0, 1, At, B1); PG8_BAR; PG8_SCHED;
;             PG8_LDA(At, 0, 1); PG8_STAGE(PG8_SB(0, 0), b2, voffB); PG8_STAGE(PG8_SB(0, 1), b2 + hstepB, voffB); PG8_STAGE(PG8_SA(0, 0), a2, voffA);
;             PG8_WAIT_V(8); PG8_WAIT_L(0); PG8_BAR; PG8_MMA(1, 0, At, B0); PG8_MMA(1, 1, At, B1); PG8_BAR; PG8_SCHED;
.LBB0_1409:
	ds_read_b128 v[132:135], v146
	ds_read_b128 v[136:139], v146 offset:1024
	ds_read_b128 v[160:163], v146 offset:2048
	ds_read_b128 v[164:167], v146 offset:3072
	ds_read_b128 v[168:171], v147
	ds_read_b128 v[172:175], v147 offset:1024
	ds_read_b128 v[180:183], v147 offset:2048
	ds_read_b128 v[184:187], v147 offset:3072
	s_add_u32 s8, s4, 0x100
	s_addc_u32 s9, s5, 0
	s_cmp_eq_u32 s39, 28
	s_cselect_b32 s46, s3, s8
	s_cselect_b32 s47, s2, s9
	s_cselect_b32 s12, s7, s23
	s_cselect_b32 s13, s6, s37
	s_add_u32 s10, s46, 0x80
	s_addc_u32 s11, s47, 0
	ds_read_b128 v[188:191], v148
	ds_read_b128 v[192:195], v148 offset:1024
	ds_read_b128 v[196:199], v148 offset:2048
	ds_read_b128 v[204:207], v148 offset:3072
	ds_read_b128 v[208:211], v148 offset:4096
	ds_read_b128 v[212:215], v148 offset:5120
	ds_read_b128 v[216:219], v148 offset:6144
	ds_read_b128 v[220:223], v148 offset:7168
	s_add_u32 s4, s4, 0x80080
	s_addc_u32 s5, s5, 0
	s_mov_b32 m0, s68
	s_nop 0
	global_load_lds_dwordx4 v140, s[4:5]
	s_nop 0
	s_mov_b32 m0, s69
	s_nop 0
	global_load_lds_dwordx4 v142, s[4:5]
	s_waitcnt vmcnt(8)
	s_waitcnt lgkmcnt(0)
	s_barrier
	s_setprio 1
	v_mfma_f32_16x16x32_bf16 v[126:129], v[132:135], v[188:191], v[126:129]
	v_mfma_f32_16x16x32_bf16 v[110:113], v[132:135], v[196:199], v[110:113]
	v_mfma_f32_16x16x32_bf16 v[94:97], v[132:135], v[208:211], v[94:97]
	v_mfma_f32_16x16x32_bf16 v[78:81], v[132:135], v[216:219], v[78:81]
	v_mfma_f32_16x16x32_bf16 v[74:77], v[160:163], v[216:219], v[74:77]
	v_mfma_f32_16x16x32_bf16 v[90:93], v[160:163], v[208:211], v[90:93]
	v_mfma_f32_16x16x32_bf16 v[106:109], v[160:163], v[196:199], v[106:109]
	v_mfma_f32_16x16x32_bf16 v[122:125], v[160:163], v[188:191], v[122:125]
	v_mfma_f32_16x16x32_bf16 v[122:125], v[164:167], v[192:195], v[122:125]
	v_mfma_f32_16x16x32_bf16 v[106:109], v[164:167], v[204:207], v[106:109]
	v_mfma_f32_16x16x32_bf16 v[90:93], v[164:167], v[212:215], v[90:93]
	v_mfma_f32_16x16x32_bf16 v[74:77], v[164:167], v[220:223], v[74:77]
	v_mfma_f32_16x16x32_bf16 v[78:81], v[136:139], v[220:223], v[78:81]
	v_mfma_f32_16x16x32_bf16 v[94:97], v[136:139], v[212:215], v[94:97]
	v_mfma_f32_16x16x32_bf16 v[110:113], v[136:139], v[204:207], v[110:113]
	v_mfma_f32_16x16x32_bf16 v[126:129], v[136:139], v[192:195], v[126:129]
	v_mfma_f32_16x16x32_bf16 v[118:121], v[168:171], v[188:191], v[118:121]
	v_mfma_f32_16x16x32_bf16 v[102:105], v[168:171], v[196:199], v[102:105]
	v_mfma_f32_16x16x32_bf16 v[86:89], v[168:171], v[208:211], v[86:89]
	v_mfma_f32_16x16x32_bf16 v[70:73], v[168:171], v[216:219], v[70:73]
	v_mfma_f32_16x16x32_bf16 v[66:69], v[180:183], v[216:219], v[66:69]
	v_mfma_f32_16x16x32_bf16 v[82:85], v[180:183], v[208:211], v[82:85]
	v_mfma_f32_16x16x32_bf16 v[98:101], v[180:183], v[196:199], v[98:101]
	v_mfma_f32_16x16x32_bf16 v[114:117], v[180:183], v[188:191], v[114:117]
	v_mfma_f32_16x16x32_bf16 v[114:117], v[184:187], v[192:195], v[114:117]
	v_mfma_f32_16x16x32_bf16 v[98:101], v[184:187], v[204:207], v[98:101]
	v_mfma_f32_16x16x32_bf16 v[82:85], v[184:187], v[212:215], v[82:85]
	v_mfma_f32_16x16x32_bf16 v[66:69], v[184:187], v[220:223], v[66:69]
	v_mfma_f32_16x16x32_bf16 v[70:73], v[172:175], v[220:223], v[70:73]
	v_mfma_f32_16x16x32_bf16 v[86:89], v[172:175], v[212:215], v[86:89]
	v_mfma_f32_16x16x32_bf16 v[102:105], v[172:175], v[204:207], v[102:105]
	v_mfma_f32_16x16x32_bf16 v[118:121], v[172:175], v[192:195], v[118:121]
	s_setprio 0
	s_barrier
	ds_read_b128 v[188:191], v148 offset:16384
	ds_read_b128 v[192:195], v148 offset:17408
	ds_read_b128 v[196:199], v148 offset:18432
	ds_read_b128 v[204:207], v148 offset:19456
	ds_read_b128 v[208:211], v148 offset:20480
	ds_read_b128 v[212:215], v148 offset:21504
	ds_read_b128 v[216:219], v148 offset:22528
	ds_read_b128 v[220:223], v148 offset:23552
	s_mov_b32 m0, s53
	s_nop 0
	global_load_lds_dwordx4 v141, s[12:13]
	s_nop 0
	s_mov_b32 m0, s54
	s_nop 0
	global_load_lds_dwordx4 v143, s[12:13]
	s_add_u32 s4, s12, 0x80000
	s_addc_u32 s5, s13, 0
	s_mov_b32 m0, s55
	s_nop 0
	global_load_lds_dwordx4 v141, s[4:5]
	s_nop 0
	s_mov_b32 m0, s56
	s_nop 0
	global_load_lds_dwordx4 v143, s[4:5]
	s_mov_b32 m0, s52
	s_nop 0
	global_load_lds_dwordx4 v140, s[46:47]
	s_nop 0
	s_mov_b32 m0, s57
	s_nop 0
	global_load_lds_dwordx4 v142, s[46:47]
	s_waitcnt vmcnt(8)
	s_waitcnt lgkmcnt(0)
	s_barrier
	s_setprio 1
	v_mfma_f32_16x16x32_bf16 v[62:65], v[132:135], v[188:191], v[62:65]
	v_mfma_f32_16x16x32_bf16 v[46:49], v[132:135], v[196:199], v[46:49]
	v_mfma_f32_16x16x32_bf16 v[30:33], v[132:135], v[208:211], v[30:33]
	v_mfma_f32_16x16x32_bf16 v[14:17], v[132:135], v[216:219], v[14:17]
	v_mfma_f32_16x16x32_bf16 v[10:13], v[160:163], v[216:219], v[10:13]
	v_mfma_f32_16x16x32_bf16 v[26:29], v[160:163], v[208:211], v[26:29]
	v_mfma_f32_16x16x32_bf16 v[42:45], v[160:163], v[196:199], v[42:45]
	v_mfma_f32_16x16x32_bf16 v[58:61], v[160:163], v[188:191], v[58:61]
	v_mfma_f32_16x16x32_bf16 v[58:61], v[164:167], v[192:195], v[58:61]
	v_mfma_f32_16x16x32_bf16 v[42:45], v[164:167], v[204:207], v[42:45]
	v_mfma_f32_16x16x32_bf16 v[26:29], v[164:167], v[212:215], v[26:29]
	v_mfma_f32_16x16x32_bf16 v[10:13], v[164:167], v[220:223], v[10:13]
	v_mfma_f32_16x16x32_bf16 v[14:17], v[136:139], v[220:223], v[14:17]
	v_mfma_f32_16x16x32_bf16 v[30:33], v[136:139], v[212:215], v[30:33]
	v_mfma_f32_16x16x32_bf16 v[46:49], v[136:139], v[204:207], v[46:49]
	v_mfma_f32_16x16x32_bf16 v[62:65], v[136:139], v[192:195], v[62:65]
	v_mfma_f32_16x16x32_bf16 v[54:57], v[168:171], v[188:191], v[54:57]
	v_mfma_f32_16x16x32_bf16 v[38:41], v[168:171], v[196:199], v[38:41]
	v_mfma_f32_16x16x32_bf16 v[22:25], v[168:171], v[208:211], v[22:25]
	v_mfma_f32_16x16x32_bf16 v[6:9], v[168:171], v[216:219], v[6:9]
	v_mfma_f32_16x16x32_bf16 v[2:5], v[180:183], v[216:219], v[2:5]
	v_mfma_f32_16x16x32_bf16 v[18:21], v[180:183], v[208:211], v[18:21]
	v_mfma_f32_16x16x32_bf16 v[34:37], v[180:183], v[196:199], v[34:37]
	v_mfma_f32_16x16x32_bf16 v[50:53], v[180:183], v[188:191], v[50:53]
	v_mfma_f32_16x16x32_bf16 v[50:53], v[184:187], v[192:195], v[50:53]
	v_mfma_f32_16x16x32_bf16 v[34:37], v[184:187], v[204:207], v[34:37]
	v_mfma_f32_16x16x32_bf16 v[18:21], v[184:187], v[212:215], v[18:21]
	v_mfma_f32_16x16x32_bf16 v[2:5], v[184:187], v[220:223], v[2:5]
	v_mfma_f32_16x16x32_bf16 v[6:9], v[172:175], v[220:223], v[6:9]
	v_mfma_f32_16x16x32_bf16 v[22:25], v[172:175], v[212:215], v[22:25]
	v_mfma_f32_16x16x32_bf16 v[38:41], v[172:175], v[204:207], v[38:41]
	v_mfma_f32_16x16x32_bf16 v[54:57], v[172:175], v[192:195], v[54:57]
	s_setprio 0
	s_barrier
; #define PG8_STAGE(bufoff, gbase, voff) do { _Pragma("unroll") for (int _i = 0; _i < 2; ++_i) { unsigned keep_; \
;         asm volatile("s_mov_b32 %0, m0\n\ts_mov_b32 m0, %3\n\ts_nop 0\n\tglobal_load_lds_dwordx4 %1, %2\n\ts_mov_b32 m0, %0" \
;             : "=&s"(keep_) : "v"((voff)[_i]), "s"((const void*)(gbase)), "s"(ldsb0 + (unsigned)(bufoff) + (unsigned)(_i * 8192)) : "memory"); } } while (0)
; #define PG8_LDA(dst, b, h) do { _Pragma("unroll") for (int m = 0; m < 4; ++m) _Pragma("unroll") for (int k = 0; k < 2; ++k) dst[m][k] = *(const LAS bf16x8*)(lds + PG8_SA(b, h) + aoff + m * 2048 + k * 1024); } while (0)
; #define PG8_LDB(dst, b, h) do { _Pragma("unroll") for (int n = 0; n < 2; ++n) _Pragma("unroll") for (int k = 0; k < 2; ++k) dst[n][k] = *(const LAS bf16x8*)(lds + PG8_SB(b, h) + boff + n * 2048 + k * 1024); } while (0)
; #define PG8_MMA(ai, bj, At, Bt) do { __builtin_amdgcn_s_setprio(1); _Pragma("unroll") for (int m = 0; m < 4; ++m) _Pragma("unroll") for (int n = 0; n < 2; ++n) _Pragma("unroll") for (int k = 0; k < 2; ++k) \
;         acc[ai][bj][m][n] = __builtin_amdgcn_mfma_f32_16x16x32_bf16(Bt[n][k], At[m][k], acc[ai][bj][m][n], 0, 0, 0); __builtin_amdgcn_s_setprio(0); } while (0)
; #define PG8_WAIT_V(n) asm volatile("s_waitcnt vmcnt(" #n ")" ::: "memory")
; #define PG8_WAIT_L(n) asm volatile("s_waitcnt lgkmcnt(" #n ")" ::: "memory")
; #define PG8_BAR __builtin_amdgcn_s_barrier()
; #define PG8_SCHED __builtin_amdgcn_sched_barrier(0)
; template <class Epi, class Sched, bool ALIGN_EPI>
; __device__ __forceinline__ void gemm_phase(LAS unsigned char* lds, const Gemm g, const Sched& S, const Epi& E) {
;     ...
;             PG8_LDB(B0, 1, 0); PG8_LDB(B1, 1, 1); PG8_SCHED; PG8_LDA(At, 1, 0); PG8_STAGE(PG8_SA(0, 1), a2 + hstepA, voffA);
;             PG8_WAIT_V(8); PG8_WAIT_L(0); PG8_BAR; PG8_MMA(0, 0, At, B0); PG8_MMA(0, 1, At, B1); PG8_BAR; PG8_SCHED;
;             PG8_LDA(At, 1, 1); PG8_STAGE(PG8_SB(1, 0), b3, voffB); PG8_STAGE(PG8_SB(1, 1), b3 + hstepB, voffB); PG8_STAGE(PG8_SA(1, 0), a3, voffA);
;             PG8_WAIT_V(8); PG8_WAIT_L(0); PG8_BAR; PG8_MMA(1, 0, At, B0); PG8_MMA(1, 1, At, B1); PG8_BAR; PG8_SCHED;
;         }
;         if constexpr (ALIGN_EPI) { if (wr == 0) PG8_BAR; }
	ds_read_b128 v[132:135], v149
	ds_read_b128 v[136:139], v149 offset:1024
	ds_read_b128 v[160:163], v149 offset:2048
	ds_read_b128 v[164:167], v149 offset:3072
	ds_read_b128 v[168:171], v150
	ds_read_b128 v[172:175], v150 offset:1024
	ds_read_b128 v[180:183], v150 offset:2048
	ds_read_b128 v[184:187], v150 offset:3072
	ds_read_b128 v[188:191], v148 offset:32768
	ds_read_b128 v[192:195], v148 offset:33792
	ds_read_b128 v[196:199], v148 offset:34816
	ds_read_b128 v[204:207], v148 offset:35840
	ds_read_b128 v[208:211], v148 offset:36864
	ds_read_b128 v[212:215], v148 offset:37888
	ds_read_b128 v[216:219], v148 offset:38912
	ds_read_b128 v[220:223], v148 offset:39936
	s_add_u32 s4, s46, 0x80000
	s_addc_u32 s5, s47, 0
	s_mov_b32 m0, s59
	s_nop 0
	global_load_lds_dwordx4 v140, s[4:5]
	s_nop 0
	s_mov_b32 m0, s61
	s_nop 0
	global_load_lds_dwordx4 v142, s[4:5]
	s_waitcnt vmcnt(8)
	s_waitcnt lgkmcnt(0)
	s_barrier
	s_setprio 1
	v_mfma_f32_16x16x32_bf16 v[126:129], v[132:135], v[188:191], v[126:129]
	v_mfma_f32_16x16x32_bf16 v[110:113], v[132:135], v[196:199], v[110:113]
	v_mfma_f32_16x16x32_bf16 v[94:97], v[132:135], v[208:211], v[94:97]
	v_mfma_f32_16x16x32_bf16 v[78:81], v[132:135], v[216:219], v[78:81]
	v_mfma_f32_16x16x32_bf16 v[74:77], v[160:163], v[216:219], v[74:77]
	v_mfma_f32_16x16x32_bf16 v[90:93], v[160:163], v[208:211], v[90:93]
	v_mfma_f32_16x16x32_bf16 v[106:109], v[160:163], v[196:199], v[106:109]
	v_mfma_f32_16x16x32_bf16 v[122:125], v[160:163], v[188:191], v[122:125]
	v_mfma_f32_16x16x32_bf16 v[122:125], v[164:167], v[192:195], v[122:125]
	v_mfma_f32_16x16x32_bf16 v[106:109], v[164:167], v[204:207], v[106:109]
	v_mfma_f32_16x16x32_bf16 v[90:93], v[164:167], v[212:215], v[90:93]
	v_mfma_f32_16x16x32_bf16 v[74:77], v[164:167], v[220:223], v[74:77]
	v_mfma_f32_16x16x32_bf16 v[78:81], v[136:139], v[220:223], v[78:81]
	v_mfma_f32_16x16x32_bf16 v[94:97], v[136:139], v[212:215], v[94:97]
	v_mfma_f32_16x16x32_bf16 v[110:113], v[136:139], v[204:207], v[110:113]
	v_mfma_f32_16x16x32_bf16 v[126:129], v[136:139], v[192:195], v[126:129]
	v_mfma_f32_16x16x32_bf16 v[118:121], v[168:171], v[188:191], v[118:121]
	v_mfma_f32_16x16x32_bf16 v[102:105], v[168:171], v[196:199], v[102:105]
	v_mfma_f32_16x16x32_bf16 v[86:89], v[168:171], v[208:211], v[86:89]
	v_mfma_f32_16x16x32_bf16 v[70:73], v[168:171], v[216:219], v[70:73]
	v_mfma_f32_16x16x32_bf16 v[66:69], v[180:183], v[216:219], v[66:69]
	v_mfma_f32_16x16x32_bf16 v[82:85], v[180:183], v[208:211], v[82:85]
	v_mfma_f32_16x16x32_bf16 v[98:101], v[180:183], v[196:199], v[98:101]
	v_mfma_f32_16x16x32_bf16 v[114:117], v[180:183], v[188:191], v[114:117]
	v_mfma_f32_16x16x32_bf16 v[114:117], v[184:187], v[192:195], v[114:117]
	v_mfma_f32_16x16x32_bf16 v[98:101], v[184:187], v[204:207], v[98:101]
	v_mfma_f32_16x16x32_bf16 v[82:85], v[184:187], v[212:215], v[82:85]
	v_mfma_f32_16x16x32_bf16 v[66:69], v[184:187], v[220:223], v[66:69]
	v_mfma_f32_16x16x32_bf16 v[70:73], v[172:175], v[220:223], v[70:73]
	v_mfma_f32_16x16x32_bf16 v[86:89], v[172:175], v[212:215], v[86:89]
	v_mfma_f32_16x16x32_bf16 v[102:105], v[172:175], v[204:207], v[102:105]
	v_mfma_f32_16x16x32_bf16 v[118:121], v[172:175], v[192:195], v[118:121]
	s_setprio 0
	s_barrier
	ds_read_b128 v[188:191], v148 offset:49152
	ds_read_b128 v[192:195], v148 offset:50176
	ds_read_b128 v[196:199], v148 offset:51200
	ds_read_b128 v[204:207], v148 offset:52224
	ds_read_b128 v[208:211], v148 offset:53248
	ds_read_b128 v[212:215], v148 offset:54272
	ds_read_b128 v[216:219], v148 offset:55296
	ds_read_b128 v[220:223], v148 offset:56320
	s_add_u32 s4, s12, 0x80
	s_addc_u32 s5, s13, 0
	s_mov_b32 m0, s62
	s_nop 0
	global_load_lds_dwordx4 v141, s[4:5]
	s_nop 0
	s_mov_b32 m0, s63
	s_nop 0
	global_load_lds_dwordx4 v143, s[4:5]
	s_add_u32 s4, s12, 0x80080
	s_addc_u32 s5, s13, 0
	s_mov_b32 m0, s66
	s_nop 0
	global_load_lds_dwordx4 v141, s[4:5]
	s_nop 0
	s_mov_b32 m0, s67
	s_nop 0
	global_load_lds_dwordx4 v143, s[4:5]
	s_mov_b32 m0, s64
	s_nop 0
	global_load_lds_dwordx4 v140, s[10:11]
	s_nop 0
	s_mov_b32 m0, s65
	s_nop 0
	global_load_lds_dwordx4 v142, s[10:11]
	s_waitcnt vmcnt(8)
	s_waitcnt lgkmcnt(0)
	s_barrier
	s_setprio 1
	v_mfma_f32_16x16x32_bf16 v[62:65], v[132:135], v[188:191], v[62:65]
	v_mfma_f32_16x16x32_bf16 v[46:49], v[132:135], v[196:199], v[46:49]
	v_mfma_f32_16x16x32_bf16 v[30:33], v[132:135], v[208:211], v[30:33]
	v_mfma_f32_16x16x32_bf16 v[14:17], v[132:135], v[216:219], v[14:17]
	v_mfma_f32_16x16x32_bf16 v[10:13], v[160:163], v[216:219], v[10:13]
	v_mfma_f32_16x16x32_bf16 v[26:29], v[160:163], v[208:211], v[26:29]
	v_mfma_f32_16x16x32_bf16 v[42:45], v[160:163], v[196:199], v[42:45]
	v_mfma_f32_16x16x32_bf16 v[58:61], v[160:163], v[188:191], v[58:61]
	v_mfma_f32_16x16x32_bf16 v[58:61], v[164:167], v[192:195], v[58:61]
	v_mfma_f32_16x16x32_bf16 v[42:45], v[164:167], v[204:207], v[42:45]
	v_mfma_f32_16x16x32_bf16 v[26:29], v[164:167], v[212:215], v[26:29]
	v_mfma_f32_16x16x32_bf16 v[10:13], v[164:167], v[220:223], v[10:13]
	v_mfma_f32_16x16x32_bf16 v[14:17], v[136:139], v[220:223], v[14:17]
	v_mfma_f32_16x16x32_bf16 v[30:33], v[136:139], v[212:215], v[30:33]
	v_mfma_f32_16x16x32_bf16 v[46:49], v[136:139], v[204:207], v[46:49]
	v_mfma_f32_16x16x32_bf16 v[62:65], v[136:139], v[192:195], v[62:65]
	v_mfma_f32_16x16x32_bf16 v[54:57], v[168:171], v[188:191], v[54:57]
	v_mfma_f32_16x16x32_bf16 v[38:41], v[168:171], v[196:199], v[38:41]
	v_mfma_f32_16x16x32_bf16 v[22:25], v[168:171], v[208:211], v[22:25]
	v_mfma_f32_16x16x32_bf16 v[6:9], v[168:171], v[216:219], v[6:9]
	v_mfma_f32_16x16x32_bf16 v[2:5], v[180:183], v[216:219], v[2:5]
	v_mfma_f32_16x16x32_bf16 v[18:21], v[180:183], v[208:211], v[18:21]
	v_mfma_f32_16x16x32_bf16 v[34:37], v[180:183], v[196:199], v[34:37]
	v_mfma_f32_16x16x32_bf16 v[50:53], v[180:183], v[188:191], v[50:53]
	v_mfma_f32_16x16x32_bf16 v[50:53], v[184:187], v[192:195], v[50:53]
	v_mfma_f32_16x16x32_bf16 v[34:37], v[184:187], v[204:207], v[34:37]
	v_mfma_f32_16x16x32_bf16 v[18:21], v[184:187], v[212:215], v[18:21]
	v_mfma_f32_16x16x32_bf16 v[2:5], v[184:187], v[220:223], v[2:5]
	v_mfma_f32_16x16x32_bf16 v[6:9], v[172:175], v[220:223], v[6:9]
	v_mfma_f32_16x16x32_bf16 v[22:25], v[172:175], v[212:215], v[22:25]
	v_mfma_f32_16x16x32_bf16 v[38:41], v[172:175], v[204:207], v[38:41]
	v_mfma_f32_16x16x32_bf16 v[54:57], v[172:175], v[192:195], v[54:57]
	s_setprio 0
	s_barrier
	s_add_i32 s39, s39, 2
	s_add_u32 s23, s23, 0x100
	s_addc_u32 s37, s37, 0
	s_cmp_gt_u32 s39, 29
	s_mov_b64 s[4:5], s[8:9]
	s_cbranch_scc0 .LBB0_1409
	s_and_b64 vcc, exec, s[34:35]
	s_cbranch_vccz .LBB0_1412
	s_barrier

; #define PG8_STAGE(bufoff, gbase, voff) do { _Pragma("unroll") for (int _i = 0; _i < 2; ++_i) { unsigned keep_; \
;         asm volatile("s_mov_b32 %0, m0\n\ts_mov_b32 m0, %3\n\ts_nop 0\n\tglobal_load_lds_dwordx4 %1, %2\n\ts_mov_b32 m0, %0" \
;             : "=&s"(keep_) : "v"((voff)[_i]), "s"((const void*)(gbase)), "s"(ldsb0 + (unsigned)(bufoff) + (unsigned)(_i * 8192)) : "memory"); } } while (0)
; #define PG8_LDA(dst, b, h) do { _Pragma("unroll") for (int m = 0; m < 4; ++m) _Pragma("unroll") for (int k = 0; k < 2; ++k) dst[m][k] = *(const LAS bf16x8*)(lds + PG8_SA(b, h) + aoff + m * 2048 + k * 1024); } while (0)
; #define PG8_LDB(dst, b, h) do { _Pragma("unroll") for (int n = 0; n < 2; ++n) _Pragma("unroll") for (int k = 0; k < 2; ++k) dst[n][k] = *(const LAS bf16x8*)(lds + PG8_SB(b, h) + boff + n * 2048 + k * 1024); } while (0)
; #define PG8_MMA(ai, bj, At, Bt) do { __builtin_amdgcn_s_setprio(1); _Pragma("unroll") for (int m = 0; m < 4; ++m) _Pragma("unroll") for (int n = 0; n < 2; ++n) _Pragma("unroll") for (int k = 0; k < 2; ++k) \
;         acc[ai][bj][m][n] = __builtin_amdgcn_mfma_f32_16x16x32_bf16(Bt[n][k], At[m][k], acc[ai][bj][m][n], 0, 0, 0); __builtin_amdgcn_s_setprio(0); } while (0)
; #define PG8_WAIT_V(n) asm volatile("s_waitcnt vmcnt(" #n ")" ::: "memory")
; #define PG8_BAR __builtin_amdgcn_s_barrier()
; template <class Epi, class Sched, bool ALIGN_EPI>
; __device__ __forceinline__ void gemm_phase(LAS unsigned char* lds, const Gemm g, const Sched& S, const Epi& E) {
;     ...
;         for (int t = 0; t < nt; t += 2) {
;             const bool last = (t == nt - 2);
;             const char* a1 = cA + (size_t)(t + 1) * kstep;
;             const char* a2 = last ? nA : cA + (size_t)(t + 2) * kstep; const char* b2 = last ? nB : cB + (size_t)(t + 2) * kstep;
;             const char* a3 = a2 + kstep; const char* b3 = b2 + kstep;
;             PG8_LDB(B0, 0, 0); PG8_LDB(B1, 0, 1); PG8_SCHED; PG8_LDA(At, 0, 0); PG8_STAGE(PG8_SA(1, 1), a1 + hstepA, voffA);
;             PG8_WAIT_V(8); PG8_WAIT_L(0); PG8_BAR; PG8_MMA(0, 0, At, B0); PG8_MMA(0, 1, At, B1); PG8_BAR; PG8_SCHED;
;             PG8_LDA(At, 0, 1); PG8_STAGE(PG8_SB(0, 0), b2, voffB); PG8_STAGE(PG8_SB(0, 1), b2 + hstepB, voffB); PG8_STAGE(PG8_SA(0, 0), a2, voffA);
;             PG8_WAIT_V(8); PG8_WAIT_L(0); PG8_BAR; PG8_MMA(1, 0, At, B0); PG8_MMA(1, 1, At, B1); PG8_BAR; PG8_SCHED;
.LBB0_1994:
	ds_read_b128 v[110:113], v206
	ds_read_b128 v[126:129], v206 offset:1024
	ds_read_b128 v[130:133], v206 offset:2048
	ds_read_b128 v[142:145], v206 offset:3072
	ds_read_b128 v[146:149], v207
	ds_read_b128 v[150:153], v207 offset:1024
	ds_read_b128 v[154:157], v207 offset:2048
	ds_read_b128 v[158:161], v207 offset:3072
	s_cmp_eq_u32 s59, 28
	s_cselect_b32 s34, s5, s19
	s_cselect_b32 s35, s3, s21
	s_cselect_b32 s30, s7, s57
	s_cselect_b32 s31, s6, s58
	s_add_u32 s28, s34, 0x80
	s_addc_u32 s29, s35, 0
	ds_read_b128 v[162:165], v208
	ds_read_b128 v[166:169], v208 offset:1024
	ds_read_b128 v[170:173], v208 offset:2048
	ds_read_b128 v[174:177], v208 offset:3072
	ds_read_b128 v[188:191], v208 offset:4096
	ds_read_b128 v[192:195], v208 offset:5120
	ds_read_b128 v[196:199], v208 offset:6144
	ds_read_b128 v[212:215], v208 offset:7168
	s_mov_b32 m0, s55
	s_nop 0
	global_load_lds_dwordx4 v179, s[26:27]
	s_nop 0
	s_mov_b32 m0, s56
	s_nop 0
	global_load_lds_dwordx4 v201, s[26:27]
	s_waitcnt vmcnt(8)
	s_waitcnt lgkmcnt(0)
	s_barrier
	s_setprio 1
	v_mfma_f32_16x16x32_bf16 v[138:141], v[110:113], v[162:165], v[138:141]
	v_mfma_f32_16x16x32_bf16 v[114:117], v[110:113], v[170:173], v[114:117]
	v_mfma_f32_16x16x32_bf16 v[94:97], v[110:113], v[188:191], v[94:97]
	v_mfma_f32_16x16x32_bf16 v[78:81], v[110:113], v[196:199], v[78:81]
	v_mfma_f32_16x16x32_bf16 v[74:77], v[130:133], v[196:199], v[74:77]
	v_mfma_f32_16x16x32_bf16 v[90:93], v[130:133], v[188:191], v[90:93]
	v_mfma_f32_16x16x32_bf16 v[106:109], v[130:133], v[170:173], v[106:109]
	v_mfma_f32_16x16x32_bf16 v[134:137], v[130:133], v[162:165], v[134:137]
	v_mfma_f32_16x16x32_bf16 v[134:137], v[142:145], v[166:169], v[134:137]
	v_mfma_f32_16x16x32_bf16 v[106:109], v[142:145], v[174:177], v[106:109]
	v_mfma_f32_16x16x32_bf16 v[90:93], v[142:145], v[192:195], v[90:93]
	v_mfma_f32_16x16x32_bf16 v[74:77], v[142:145], v[212:215], v[74:77]
	v_mfma_f32_16x16x32_bf16 v[78:81], v[126:129], v[212:215], v[78:81]
	v_mfma_f32_16x16x32_bf16 v[94:97], v[126:129], v[192:195], v[94:97]
	v_mfma_f32_16x16x32_bf16 v[114:117], v[126:129], v[174:177], v[114:117]
	v_mfma_f32_16x16x32_bf16 v[138:141], v[126:129], v[166:169], v[138:141]
	v_mfma_f32_16x16x32_bf16 v[122:125], v[146:149], v[162:165], v[122:125]
	v_mfma_f32_16x16x32_bf16 v[102:105], v[146:149], v[170:173], v[102:105]
	v_mfma_f32_16x16x32_bf16 v[86:89], v[146:149], v[188:191], v[86:89]
	v_mfma_f32_16x16x32_bf16 v[70:73], v[146:149], v[196:199], v[70:73]
	v_mfma_f32_16x16x32_bf16 v[66:69], v[154:157], v[196:199], v[66:69]
	v_mfma_f32_16x16x32_bf16 v[82:85], v[154:157], v[188:191], v[82:85]
	v_mfma_f32_16x16x32_bf16 v[98:101], v[154:157], v[170:173], v[98:101]
	v_mfma_f32_16x16x32_bf16 v[118:121], v[154:157], v[162:165], v[118:121]
	v_mfma_f32_16x16x32_bf16 v[118:121], v[158:161], v[166:169], v[118:121]
	v_mfma_f32_16x16x32_bf16 v[98:101], v[158:161], v[174:177], v[98:101]
	v_mfma_f32_16x16x32_bf16 v[82:85], v[158:161], v[192:195], v[82:85]
	v_mfma_f32_16x16x32_bf16 v[66:69], v[158:161], v[212:215], v[66:69]
	v_mfma_f32_16x16x32_bf16 v[70:73], v[150:153], v[212:215], v[70:73]
	v_mfma_f32_16x16x32_bf16 v[86:89], v[150:153], v[192:195], v[86:89]
	v_mfma_f32_16x16x32_bf16 v[102:105], v[150:153], v[174:177], v[102:105]
	v_mfma_f32_16x16x32_bf16 v[122:125], v[150:153], v[166:169], v[122:125]
	s_setprio 0
	s_barrier
	ds_read_b128 v[162:165], v208 offset:16384
	ds_read_b128 v[166:169], v208 offset:17408
	ds_read_b128 v[170:173], v208 offset:18432
	ds_read_b128 v[174:177], v208 offset:19456
	ds_read_b128 v[188:191], v208 offset:20480
	ds_read_b128 v[192:195], v208 offset:21504
	ds_read_b128 v[196:199], v208 offset:22528
	ds_read_b128 v[212:215], v208 offset:23552
	s_mov_b32 m0, s42
	s_nop 0
	global_load_lds_dwordx4 v200, s[30:31]
	s_nop 0
	s_mov_b32 m0, s43
	s_nop 0
	global_load_lds_dwordx4 v203, s[30:31]
	s_add_u32 s60, s30, 0x80000
	s_addc_u32 s61, s31, 0
	s_mov_b32 m0, s44
	s_nop 0
	global_load_lds_dwordx4 v200, s[60:61]
	s_nop 0
	s_mov_b32 m0, s45
	s_nop 0
	global_load_lds_dwordx4 v203, s[60:61]
	s_mov_b32 m0, s41
	s_nop 0
	global_load_lds_dwordx4 v179, s[34:35]
	s_nop 0
	s_mov_b32 m0, s46
	s_nop 0
	global_load_lds_dwordx4 v201, s[34:35]
	s_waitcnt vmcnt(8)
	s_waitcnt lgkmcnt(0)
	s_barrier
	s_setprio 1
	v_mfma_f32_16x16x32_bf16 v[62:65], v[110:113], v[162:165], v[62:65]
	v_mfma_f32_16x16x32_bf16 v[46:49], v[110:113], v[170:173], v[46:49]
	v_mfma_f32_16x16x32_bf16 v[30:33], v[110:113], v[188:191], v[30:33]
	v_mfma_f32_16x16x32_bf16 v[14:17], v[110:113], v[196:199], v[14:17]
	v_mfma_f32_16x16x32_bf16 v[10:13], v[130:133], v[196:199], v[10:13]
	v_mfma_f32_16x16x32_bf16 v[26:29], v[130:133], v[188:191], v[26:29]
	v_mfma_f32_16x16x32_bf16 v[42:45], v[130:133], v[170:173], v[42:45]
	v_mfma_f32_16x16x32_bf16 v[58:61], v[130:133], v[162:165], v[58:61]
	v_mfma_f32_16x16x32_bf16 v[58:61], v[142:145], v[166:169], v[58:61]
	v_mfma_f32_16x16x32_bf16 v[42:45], v[142:145], v[174:177], v[42:45]
	v_mfma_f32_16x16x32_bf16 v[26:29], v[142:145], v[192:195], v[26:29]
	v_mfma_f32_16x16x32_bf16 v[10:13], v[142:145], v[212:215], v[10:13]
	v_mfma_f32_16x16x32_bf16 v[14:17], v[126:129], v[212:215], v[14:17]
	v_mfma_f32_16x16x32_bf16 v[30:33], v[126:129], v[192:195], v[30:33]
	v_mfma_f32_16x16x32_bf16 v[46:49], v[126:129], v[174:177], v[46:49]
	v_mfma_f32_16x16x32_bf16 v[62:65], v[126:129], v[166:169], v[62:65]
	v_mfma_f32_16x16x32_bf16 v[54:57], v[146:149], v[162:165], v[54:57]
	v_mfma_f32_16x16x32_bf16 v[38:41], v[146:149], v[170:173], v[38:41]
	v_mfma_f32_16x16x32_bf16 v[22:25], v[146:149], v[188:191], v[22:25]
	v_mfma_f32_16x16x32_bf16 v[6:9], v[146:149], v[196:199], v[6:9]
	v_mfma_f32_16x16x32_bf16 v[2:5], v[154:157], v[196:199], v[2:5]
	v_mfma_f32_16x16x32_bf16 v[18:21], v[154:157], v[188:191], v[18:21]
	v_mfma_f32_16x16x32_bf16 v[34:37], v[154:157], v[170:173], v[34:37]
	v_mfma_f32_16x16x32_bf16 v[50:53], v[154:157], v[162:165], v[50:53]
	v_mfma_f32_16x16x32_bf16 v[50:53], v[158:161], v[166:169], v[50:53]
	v_mfma_f32_16x16x32_bf16 v[34:37], v[158:161], v[174:177], v[34:37]
	v_mfma_f32_16x16x32_bf16 v[18:21], v[158:161], v[192:195], v[18:21]
	v_mfma_f32_16x16x32_bf16 v[2:5], v[158:161], v[212:215], v[2:5]
	v_mfma_f32_16x16x32_bf16 v[6:9], v[150:153], v[212:215], v[6:9]
	v_mfma_f32_16x16x32_bf16 v[22:25], v[150:153], v[192:195], v[22:25]
	v_mfma_f32_16x16x32_bf16 v[38:41], v[150:153], v[174:177], v[38:41]
	v_mfma_f32_16x16x32_bf16 v[54:57], v[150:153], v[166:169], v[54:57]
	s_setprio 0
	s_barrier
; #define PG8_STAGE(bufoff, gbase, voff) do { _Pragma("unroll") for (int _i = 0; _i < 2; ++_i) { unsigned keep_; \
;         asm volatile("s_mov_b32 %0, m0\n\ts_mov_b32 m0, %3\n\ts_nop 0\n\tglobal_load_lds_dwordx4 %1, %2\n\ts_mov_b32 m0, %0" \
;             : "=&s"(keep_) : "v"((voff)[_i]), "s"((const void*)(gbase)), "s"(ldsb0 + (unsigned)(bufoff) + (unsigned)(_i * 8192)) : "memory"); } } while (0)
; #define PG8_LDA(dst, b, h) do { _Pragma("unroll") for (int m = 0; m < 4; ++m) _Pragma("unroll") for (int k = 0; k < 2; ++k) dst[m][k] = *(const LAS bf16x8*)(lds + PG8_SA(b, h) + aoff + m * 2048 + k * 1024); } while (0)
; #define PG8_LDB(dst, b, h) do { _Pragma("unroll") for (int n = 0; n < 2; ++n) _Pragma("unroll") for (int k = 0; k < 2; ++k) dst[n][k] = *(const LAS bf16x8*)(lds + PG8_SB(b, h) + boff + n * 2048 + k * 1024); } while (0)
; #define PG8_MMA(ai, bj, At, Bt) do { __builtin_amdgcn_s_setprio(1); _Pragma("unroll") for (int m = 0; m < 4; ++m) _Pragma("unroll") for (int n = 0; n < 2; ++n) _Pragma("unroll") for (int k = 0; k < 2; ++k) \
;         acc[ai][bj][m][n] = __builtin_amdgcn_mfma_f32_16x16x32_bf16(Bt[n][k], At[m][k], acc[ai][bj][m][n], 0, 0, 0); __builtin_amdgcn_s_setprio(0); } while (0)
; #define PG8_WAIT_V(n) asm volatile("s_waitcnt vmcnt(" #n ")" ::: "memory")
; #define PG8_WAIT_L(n) asm volatile("s_waitcnt lgkmcnt(" #n ")" ::: "memory")
; #define PG8_BAR __builtin_amdgcn_s_barrier()
; #define PG8_SCHED __builtin_amdgcn_sched_barrier(0)
; template <class Epi, class Sched, bool ALIGN_EPI>
; __device__ __forceinline__ void gemm_phase(LAS unsigned char* lds, const Gemm g, const Sched& S, const Epi& E) {
;     ...
;             PG8_LDB(B0, 1, 0); PG8_LDB(B1, 1, 1); PG8_SCHED; PG8_LDA(At, 1, 0); PG8_STAGE(PG8_SA(0, 1), a2 + hstepA, voffA);
;             PG8_WAIT_V(8); PG8_WAIT_L(0); PG8_BAR; PG8_MMA(0, 0, At, B0); PG8_MMA(0, 1, At, B1); PG8_BAR; PG8_SCHED;
;             PG8_LDA(At, 1, 1); PG8_STAGE(PG8_SB(1, 0), b3, voffB); PG8_STAGE(PG8_SB(1, 1), b3 + hstepB, voffB); PG8_STAGE(PG8_SA(1, 0), a3, voffA);
;             PG8_WAIT_V(8); PG8_WAIT_L(0); PG8_BAR; PG8_MMA(1, 0, At, B0); PG8_MMA(1, 1, At, B1); PG8_BAR; PG8_SCHED;
;         }
;         if constexpr (ALIGN_EPI) { if (wr == 0) PG8_BAR; }
	ds_read_b128 v[110:113], v209
	ds_read_b128 v[126:129], v209 offset:1024
	ds_read_b128 v[130:133], v209 offset:2048
	ds_read_b128 v[142:145], v209 offset:3072
	ds_read_b128 v[146:149], v210
	ds_read_b128 v[150:153], v210 offset:1024
	ds_read_b128 v[154:157], v210 offset:2048
	ds_read_b128 v[158:161], v210 offset:3072
	ds_read_b128 v[162:165], v208 offset:32768
	ds_read_b128 v[166:169], v208 offset:33792
	ds_read_b128 v[170:173], v208 offset:34816
	ds_read_b128 v[174:177], v208 offset:35840
	ds_read_b128 v[188:191], v208 offset:36864
	ds_read_b128 v[192:195], v208 offset:37888
	ds_read_b128 v[196:199], v208 offset:38912
	ds_read_b128 v[212:215], v208 offset:39936
	s_add_u32 s34, s34, 0x80000
	s_addc_u32 s35, s35, 0
	s_mov_b32 m0, s47
	s_nop 0
	global_load_lds_dwordx4 v179, s[34:35]
	s_nop 0
	s_mov_b32 m0, s48
	s_nop 0
	global_load_lds_dwordx4 v201, s[34:35]
	s_waitcnt vmcnt(8)
	s_waitcnt lgkmcnt(0)
	s_barrier
	s_setprio 1
	v_mfma_f32_16x16x32_bf16 v[138:141], v[110:113], v[162:165], v[138:141]
	v_mfma_f32_16x16x32_bf16 v[114:117], v[110:113], v[170:173], v[114:117]
	v_mfma_f32_16x16x32_bf16 v[94:97], v[110:113], v[188:191], v[94:97]
	v_mfma_f32_16x16x32_bf16 v[78:81], v[110:113], v[196:199], v[78:81]
	v_mfma_f32_16x16x32_bf16 v[74:77], v[130:133], v[196:199], v[74:77]
	v_mfma_f32_16x16x32_bf16 v[90:93], v[130:133], v[188:191], v[90:93]
	v_mfma_f32_16x16x32_bf16 v[106:109], v[130:133], v[170:173], v[106:109]
	v_mfma_f32_16x16x32_bf16 v[134:137], v[130:133], v[162:165], v[134:137]
	v_mfma_f32_16x16x32_bf16 v[134:137], v[142:145], v[166:169], v[134:137]
	v_mfma_f32_16x16x32_bf16 v[106:109], v[142:145], v[174:177], v[106:109]
	v_mfma_f32_16x16x32_bf16 v[90:93], v[142:145], v[192:195], v[90:93]
	v_mfma_f32_16x16x32_bf16 v[74:77], v[142:145], v[212:215], v[74:77]
	v_mfma_f32_16x16x32_bf16 v[78:81], v[126:129], v[212:215], v[78:81]
	v_mfma_f32_16x16x32_bf16 v[94:97], v[126:129], v[192:195], v[94:97]
	v_mfma_f32_16x16x32_bf16 v[114:117], v[126:129], v[174:177], v[114:117]
	v_mfma_f32_16x16x32_bf16 v[138:141], v[126:129], v[166:169], v[138:141]
	v_mfma_f32_16x16x32_bf16 v[122:125], v[146:149], v[162:165], v[122:125]
	v_mfma_f32_16x16x32_bf16 v[102:105], v[146:149], v[170:173], v[102:105]
	v_mfma_f32_16x16x32_bf16 v[86:89], v[146:149], v[188:191], v[86:89]
	v_mfma_f32_16x16x32_bf16 v[70:73], v[146:149], v[196:199], v[70:73]
	v_mfma_f32_16x16x32_bf16 v[66:69], v[154:157], v[196:199], v[66:69]
	v_mfma_f32_16x16x32_bf16 v[82:85], v[154:157], v[188:191], v[82:85]
	v_mfma_f32_16x16x32_bf16 v[98:101], v[154:157], v[170:173], v[98:101]
	v_mfma_f32_16x16x32_bf16 v[118:121], v[154:157], v[162:165], v[118:121]
	v_mfma_f32_16x16x32_bf16 v[118:121], v[158:161], v[166:169], v[118:121]
	v_mfma_f32_16x16x32_bf16 v[98:101], v[158:161], v[174:177], v[98:101]
	v_mfma_f32_16x16x32_bf16 v[82:85], v[158:161], v[192:195], v[82:85]
	v_mfma_f32_16x16x32_bf16 v[66:69], v[158:161], v[212:215], v[66:69]
	v_mfma_f32_16x16x32_bf16 v[70:73], v[150:153], v[212:215], v[70:73]
	v_mfma_f32_16x16x32_bf16 v[86:89], v[150:153], v[192:195], v[86:89]
	v_mfma_f32_16x16x32_bf16 v[102:105], v[150:153], v[174:177], v[102:105]
	v_mfma_f32_16x16x32_bf16 v[122:125], v[150:153], v[166:169], v[122:125]
	s_setprio 0
	s_barrier
	ds_read_b128 v[162:165], v208 offset:49152
	ds_read_b128 v[166:169], v208 offset:50176
	ds_read_b128 v[170:173], v208 offset:51200
	ds_read_b128 v[174:177], v208 offset:52224
	ds_read_b128 v[188:191], v208 offset:53248
	ds_read_b128 v[192:195], v208 offset:54272
	ds_read_b128 v[196:199], v208 offset:55296
	ds_read_b128 v[212:215], v208 offset:56320
	s_add_u32 s34, s30, 0x80
	s_addc_u32 s35, s31, 0
	s_mov_b32 m0, s49
	s_nop 0
	global_load_lds_dwordx4 v200, s[34:35]
	s_add_u32 s30, s30, 0x80080
	s_mov_b32 m0, s50
	s_nop 0
	global_load_lds_dwordx4 v203, s[34:35]
	s_addc_u32 s31, s31, 0
	s_mov_b32 m0, s53
	s_nop 0
	global_load_lds_dwordx4 v200, s[30:31]
	s_nop 0
	s_mov_b32 m0, s54
	s_nop 0
	global_load_lds_dwordx4 v203, s[30:31]
	s_mov_b32 m0, s51
	s_nop 0
	global_load_lds_dwordx4 v179, s[28:29]
	s_nop 0
	s_mov_b32 m0, s52
	s_nop 0
	global_load_lds_dwordx4 v201, s[28:29]
	s_waitcnt vmcnt(8)
	s_waitcnt lgkmcnt(0)
	s_barrier
	s_setprio 1
	v_mfma_f32_16x16x32_bf16 v[62:65], v[110:113], v[162:165], v[62:65]
	v_mfma_f32_16x16x32_bf16 v[46:49], v[110:113], v[170:173], v[46:49]
	v_mfma_f32_16x16x32_bf16 v[30:33], v[110:113], v[188:191], v[30:33]
	v_mfma_f32_16x16x32_bf16 v[14:17], v[110:113], v[196:199], v[14:17]
	v_mfma_f32_16x16x32_bf16 v[10:13], v[130:133], v[196:199], v[10:13]
	v_mfma_f32_16x16x32_bf16 v[26:29], v[130:133], v[188:191], v[26:29]
	v_mfma_f32_16x16x32_bf16 v[42:45], v[130:133], v[170:173], v[42:45]
	v_mfma_f32_16x16x32_bf16 v[58:61], v[130:133], v[162:165], v[58:61]
	v_mfma_f32_16x16x32_bf16 v[58:61], v[142:145], v[166:169], v[58:61]
	v_mfma_f32_16x16x32_bf16 v[42:45], v[142:145], v[174:177], v[42:45]
	v_mfma_f32_16x16x32_bf16 v[26:29], v[142:145], v[192:195], v[26:29]
	v_mfma_f32_16x16x32_bf16 v[10:13], v[142:145], v[212:215], v[10:13]
	v_mfma_f32_16x16x32_bf16 v[14:17], v[126:129], v[212:215], v[14:17]
	v_mfma_f32_16x16x32_bf16 v[30:33], v[126:129], v[192:195], v[30:33]
	v_mfma_f32_16x16x32_bf16 v[46:49], v[126:129], v[174:177], v[46:49]
	v_mfma_f32_16x16x32_bf16 v[62:65], v[126:129], v[166:169], v[62:65]
	v_mfma_f32_16x16x32_bf16 v[54:57], v[146:149], v[162:165], v[54:57]
	v_mfma_f32_16x16x32_bf16 v[38:41], v[146:149], v[170:173], v[38:41]
	v_mfma_f32_16x16x32_bf16 v[22:25], v[146:149], v[188:191], v[22:25]
	v_mfma_f32_16x16x32_bf16 v[6:9], v[146:149], v[196:199], v[6:9]
	v_mfma_f32_16x16x32_bf16 v[2:5], v[154:157], v[196:199], v[2:5]
	v_mfma_f32_16x16x32_bf16 v[18:21], v[154:157], v[188:191], v[18:21]
	v_mfma_f32_16x16x32_bf16 v[34:37], v[154:157], v[170:173], v[34:37]
	v_mfma_f32_16x16x32_bf16 v[50:53], v[154:157], v[162:165], v[50:53]
	v_mfma_f32_16x16x32_bf16 v[50:53], v[158:161], v[166:169], v[50:53]
	v_mfma_f32_16x16x32_bf16 v[34:37], v[158:161], v[174:177], v[34:37]
	v_mfma_f32_16x16x32_bf16 v[18:21], v[158:161], v[192:195], v[18:21]
	v_mfma_f32_16x16x32_bf16 v[2:5], v[158:161], v[212:215], v[2:5]
	v_mfma_f32_16x16x32_bf16 v[6:9], v[150:153], v[212:215], v[6:9]
	v_mfma_f32_16x16x32_bf16 v[22:25], v[150:153], v[192:195], v[22:25]
	v_mfma_f32_16x16x32_bf16 v[38:41], v[150:153], v[174:177], v[38:41]
	v_mfma_f32_16x16x32_bf16 v[54:57], v[150:153], v[166:169], v[54:57]
	s_setprio 0
	s_barrier
	s_add_i32 s59, s59, 2
	s_add_u32 s19, s19, 0x100
	s_addc_u32 s21, s21, 0
	s_add_u32 s57, s57, 0x100
	s_addc_u32 s58, s58, 0
	s_add_u32 s26, s26, 0x100
	s_addc_u32 s27, s27, 0
	s_cmp_gt_u32 s59, 29
	s_cbranch_scc0 .LBB0_1994
	s_and_b64 vcc, exec, s[16:17]
	s_cbranch_vccz .LBB0_1997
	s_barrier

; #define PG8_STAGE(bufoff, gbase, voff) do { _Pragma("unroll") for (int _i = 0; _i < 2; ++_i) { unsigned keep_; \
;         asm volatile("s_mov_b32 %0, m0\n\ts_mov_b32 m0, %3\n\ts_nop 0\n\tglobal_load_lds_dwordx4 %1, %2\n\ts_mov_b32 m0, %0" \
;             : "=&s"(keep_) : "v"((voff)[_i]), "s"((const void*)(gbase)), "s"(ldsb0 + (unsigned)(bufoff) + (unsigned)(_i * 8192)) : "memory"); } } while (0)
; #define PG8_LDA(dst, b, h) do { _Pragma("unroll") for (int m = 0; m < 4; ++m) _Pragma("unroll") for (int k = 0; k < 2; ++k) dst[m][k] = *(const LAS bf16x8*)(lds + PG8_SA(b, h) + aoff + m * 2048 + k * 1024); } while (0)
; #define PG8_LDB(dst, b, h) do { _Pragma("unroll") for (int n = 0; n < 2; ++n) _Pragma("unroll") for (int k = 0; k < 2; ++k) dst[n][k] = *(const LAS bf16x8*)(lds + PG8_SB(b, h) + boff + n * 2048 + k * 1024); } while (0)
; #define PG8_MMA(ai, bj, At, Bt) do { __builtin_amdgcn_s_setprio(1); _Pragma("unroll") for (int m = 0; m < 4; ++m) _Pragma("unroll") for (int n = 0; n < 2; ++n) _Pragma("unroll") for (int k = 0; k < 2; ++k) \
;         acc[ai][bj][m][n] = __builtin_amdgcn_mfma_f32_16x16x32_bf16(Bt[n][k], At[m][k], acc[ai][bj][m][n], 0, 0, 0); __builtin_amdgcn_s_setprio(0); } while (0)
; #define PG8_WAIT_V(n) asm volatile("s_waitcnt vmcnt(" #n ")" ::: "memory")
; #define PG8_BAR __builtin_amdgcn_s_barrier()
; template <class Epi, class Sched, bool ALIGN_EPI>
; __device__ __forceinline__ void gemm_phase(LAS unsigned char* lds, const Gemm g, const Sched& S, const Epi& E) {
;     ...
;         for (int t = 0; t < nt; t += 2) {
;             const bool last = (t == nt - 2);
;             const char* a1 = cA + (size_t)(t + 1) * kstep;
;             const char* a2 = last ? nA : cA + (size_t)(t + 2) * kstep; const char* b2 = last ? nB : cB + (size_t)(t + 2) * kstep;
;             const char* a3 = a2 + kstep; const char* b3 = b2 + kstep;
;             PG8_LDB(B0, 0, 0); PG8_LDB(B1, 0, 1); PG8_SCHED; PG8_LDA(At, 0, 0); PG8_STAGE(PG8_SA(1, 1), a1 + hstepA, voffA);
;             PG8_WAIT_V(8); PG8_WAIT_L(0); PG8_BAR; PG8_MMA(0, 0, At, B0); PG8_MMA(0, 1, At, B1); PG8_BAR; PG8_SCHED;
;             PG8_LDA(At, 0, 1); PG8_STAGE(PG8_SB(0, 0), b2, voffB); PG8_STAGE(PG8_SB(0, 1), b2 + hstepB, voffB); PG8_STAGE(PG8_SA(0, 0), a2, voffA);
;             PG8_WAIT_V(8); PG8_WAIT_L(0); PG8_BAR; PG8_MMA(1, 0, At, B0); PG8_MMA(1, 1, At, B1); PG8_BAR; PG8_SCHED;
.LBB0_2075:
	ds_read_b128 v[154:157], v141
	ds_read_b128 v[158:161], v141 offset:1024
	ds_read_b128 v[162:165], v141 offset:2048
	ds_read_b128 v[166:169], v141 offset:3072
	ds_read_b128 v[170:173], v142
	ds_read_b128 v[174:177], v142 offset:1024
	ds_read_b128 v[180:183], v142 offset:2048
	ds_read_b128 v[184:187], v142 offset:3072
	s_add_u32 s28, s26, 0x100
	s_addc_u32 s29, s27, 0
	s_cmp_eq_u32 s60, 28
	s_cselect_b32 s36, s5, s28
	s_cselect_b32 s37, s3, s29
	s_cselect_b32 s34, s7, s19
	s_cselect_b32 s35, s6, s21
	s_add_u32 s30, s36, 0x80
	s_addc_u32 s31, s37, 0
	ds_read_b128 v[188:191], v143
	ds_read_b128 v[192:195], v143 offset:1024
	ds_read_b128 v[196:199], v143 offset:2048
	ds_read_b128 v[204:207], v143 offset:3072
	ds_read_b128 v[208:211], v143 offset:4096
	ds_read_b128 v[212:215], v143 offset:5120
	ds_read_b128 v[216:219], v143 offset:6144
	ds_read_b128 v[220:223], v143 offset:7168
	s_add_u32 s26, s26, 0x80080
	s_addc_u32 s27, s27, 0
	s_mov_b32 m0, s57
	s_nop 0
	global_load_lds_dwordx4 v134, s[26:27]
	s_nop 0
	s_mov_b32 m0, s58
	s_nop 0
	global_load_lds_dwordx4 v136, s[26:27]
	s_waitcnt vmcnt(8)
	s_waitcnt lgkmcnt(0)
	s_barrier
	s_setprio 1
	v_mfma_f32_16x16x32_bf16 v[126:129], v[154:157], v[188:191], v[126:129]
	v_mfma_f32_16x16x32_bf16 v[110:113], v[154:157], v[196:199], v[110:113]
	v_mfma_f32_16x16x32_bf16 v[94:97], v[154:157], v[208:211], v[94:97]
	v_mfma_f32_16x16x32_bf16 v[78:81], v[154:157], v[216:219], v[78:81]
	v_mfma_f32_16x16x32_bf16 v[74:77], v[162:165], v[216:219], v[74:77]
	v_mfma_f32_16x16x32_bf16 v[90:93], v[162:165], v[208:211], v[90:93]
	v_mfma_f32_16x16x32_bf16 v[106:109], v[162:165], v[196:199], v[106:109]
	v_mfma_f32_16x16x32_bf16 v[122:125], v[162:165], v[188:191], v[122:125]
	v_mfma_f32_16x16x32_bf16 v[122:125], v[166:169], v[192:195], v[122:125]
	v_mfma_f32_16x16x32_bf16 v[106:109], v[166:169], v[204:207], v[106:109]
	v_mfma_f32_16x16x32_bf16 v[90:93], v[166:169], v[212:215], v[90:93]
	v_mfma_f32_16x16x32_bf16 v[74:77], v[166:169], v[220:223], v[74:77]
	v_mfma_f32_16x16x32_bf16 v[78:81], v[158:161], v[220:223], v[78:81]
	v_mfma_f32_16x16x32_bf16 v[94:97], v[158:161], v[212:215], v[94:97]
	v_mfma_f32_16x16x32_bf16 v[110:113], v[158:161], v[204:207], v[110:113]
	v_mfma_f32_16x16x32_bf16 v[126:129], v[158:161], v[192:195], v[126:129]
	v_mfma_f32_16x16x32_bf16 v[118:121], v[170:173], v[188:191], v[118:121]
	v_mfma_f32_16x16x32_bf16 v[102:105], v[170:173], v[196:199], v[102:105]
	v_mfma_f32_16x16x32_bf16 v[86:89], v[170:173], v[208:211], v[86:89]
	v_mfma_f32_16x16x32_bf16 v[70:73], v[170:173], v[216:219], v[70:73]
	v_mfma_f32_16x16x32_bf16 v[66:69], v[180:183], v[216:219], v[66:69]
	v_mfma_f32_16x16x32_bf16 v[82:85], v[180:183], v[208:211], v[82:85]
	v_mfma_f32_16x16x32_bf16 v[98:101], v[180:183], v[196:199], v[98:101]
	v_mfma_f32_16x16x32_bf16 v[114:117], v[180:183], v[188:191], v[114:117]
	v_mfma_f32_16x16x32_bf16 v[114:117], v[184:187], v[192:195], v[114:117]
	v_mfma_f32_16x16x32_bf16 v[98:101], v[184:187], v[204:207], v[98:101]
	v_mfma_f32_16x16x32_bf16 v[82:85], v[184:187], v[212:215], v[82:85]
	v_mfma_f32_16x16x32_bf16 v[66:69], v[184:187], v[220:223], v[66:69]
	v_mfma_f32_16x16x32_bf16 v[70:73], v[174:177], v[220:223], v[70:73]
	v_mfma_f32_16x16x32_bf16 v[86:89], v[174:177], v[212:215], v[86:89]
	v_mfma_f32_16x16x32_bf16 v[102:105], v[174:177], v[204:207], v[102:105]
	v_mfma_f32_16x16x32_bf16 v[118:121], v[174:177], v[192:195], v[118:121]
	s_setprio 0
	s_barrier
	ds_read_b128 v[188:191], v143 offset:16384
	ds_read_b128 v[192:195], v143 offset:17408
	ds_read_b128 v[196:199], v143 offset:18432
	ds_read_b128 v[204:207], v143 offset:19456
	ds_read_b128 v[208:211], v143 offset:20480
	ds_read_b128 v[212:215], v143 offset:21504
	ds_read_b128 v[216:219], v143 offset:22528
	ds_read_b128 v[220:223], v143 offset:23552
	s_mov_b32 m0, s44
	s_nop 0
	global_load_lds_dwordx4 v135, s[34:35]
	s_nop 0
	s_mov_b32 m0, s45
	s_nop 0
	global_load_lds_dwordx4 v137, s[34:35]
	s_add_u32 s26, s34, 0x80000
	s_addc_u32 s27, s35, 0
	s_mov_b32 m0, s46
	s_nop 0
	global_load_lds_dwordx4 v135, s[26:27]
	s_nop 0
	s_mov_b32 m0, s47
	s_nop 0
	global_load_lds_dwordx4 v137, s[26:27]
	s_mov_b32 m0, s42
	s_nop 0
	global_load_lds_dwordx4 v134, s[36:37]
	s_nop 0
	s_mov_b32 m0, s48
	s_nop 0
	global_load_lds_dwordx4 v136, s[36:37]
	s_waitcnt vmcnt(8)
	s_waitcnt lgkmcnt(0)
	s_barrier
	s_setprio 1
	v_mfma_f32_16x16x32_bf16 v[62:65], v[154:157], v[188:191], v[62:65]
	v_mfma_f32_16x16x32_bf16 v[46:49], v[154:157], v[196:199], v[46:49]
	v_mfma_f32_16x16x32_bf16 v[30:33], v[154:157], v[208:211], v[30:33]
	v_mfma_f32_16x16x32_bf16 v[14:17], v[154:157], v[216:219], v[14:17]
	v_mfma_f32_16x16x32_bf16 v[10:13], v[162:165], v[216:219], v[10:13]
	v_mfma_f32_16x16x32_bf16 v[26:29], v[162:165], v[208:211], v[26:29]
	v_mfma_f32_16x16x32_bf16 v[42:45], v[162:165], v[196:199], v[42:45]
	v_mfma_f32_16x16x32_bf16 v[58:61], v[162:165], v[188:191], v[58:61]
	v_mfma_f32_16x16x32_bf16 v[58:61], v[166:169], v[192:195], v[58:61]
	v_mfma_f32_16x16x32_bf16 v[42:45], v[166:169], v[204:207], v[42:45]
	v_mfma_f32_16x16x32_bf16 v[26:29], v[166:169], v[212:215], v[26:29]
	v_mfma_f32_16x16x32_bf16 v[10:13], v[166:169], v[220:223], v[10:13]
	v_mfma_f32_16x16x32_bf16 v[14:17], v[158:161], v[220:223], v[14:17]
	v_mfma_f32_16x16x32_bf16 v[30:33], v[158:161], v[212:215], v[30:33]
	v_mfma_f32_16x16x32_bf16 v[46:49], v[158:161], v[204:207], v[46:49]
	v_mfma_f32_16x16x32_bf16 v[62:65], v[158:161], v[192:195], v[62:65]
	v_mfma_f32_16x16x32_bf16 v[54:57], v[170:173], v[188:191], v[54:57]
	v_mfma_f32_16x16x32_bf16 v[38:41], v[170:173], v[196:199], v[38:41]
	v_mfma_f32_16x16x32_bf16 v[22:25], v[170:173], v[208:211], v[22:25]
	v_mfma_f32_16x16x32_bf16 v[6:9], v[170:173], v[216:219], v[6:9]
	v_mfma_f32_16x16x32_bf16 v[2:5], v[180:183], v[216:219], v[2:5]
	v_mfma_f32_16x16x32_bf16 v[18:21], v[180:183], v[208:211], v[18:21]
	v_mfma_f32_16x16x32_bf16 v[34:37], v[180:183], v[196:199], v[34:37]
	v_mfma_f32_16x16x32_bf16 v[50:53], v[180:183], v[188:191], v[50:53]
	v_mfma_f32_16x16x32_bf16 v[50:53], v[184:187], v[192:195], v[50:53]
	v_mfma_f32_16x16x32_bf16 v[34:37], v[184:187], v[204:207], v[34:37]
	v_mfma_f32_16x16x32_bf16 v[18:21], v[184:187], v[212:215], v[18:21]
	v_mfma_f32_16x16x32_bf16 v[2:5], v[184:187], v[220:223], v[2:5]
	v_mfma_f32_16x16x32_bf16 v[6:9], v[174:177], v[220:223], v[6:9]
	v_mfma_f32_16x16x32_bf16 v[22:25], v[174:177], v[212:215], v[22:25]
	v_mfma_f32_16x16x32_bf16 v[38:41], v[174:177], v[204:207], v[38:41]
	v_mfma_f32_16x16x32_bf16 v[54:57], v[174:177], v[192:195], v[54:57]
	s_setprio 0
	s_barrier
; #define PG8_STAGE(bufoff, gbase, voff) do { _Pragma("unroll") for (int _i = 0; _i < 2; ++_i) { unsigned keep_; \
;         asm volatile("s_mov_b32 %0, m0\n\ts_mov_b32 m0, %3\n\ts_nop 0\n\tglobal_load_lds_dwordx4 %1, %2\n\ts_mov_b32 m0, %0" \
;             : "=&s"(keep_) : "v"((voff)[_i]), "s"((const void*)(gbase)), "s"(ldsb0 + (unsigned)(bufoff) + (unsigned)(_i * 8192)) : "memory"); } } while (0)
; #define PG8_LDA(dst, b, h) do { _Pragma("unroll") for (int m = 0; m < 4; ++m) _Pragma("unroll") for (int k = 0; k < 2; ++k) dst[m][k] = *(const LAS bf16x8*)(lds + PG8_SA(b, h) + aoff + m * 2048 + k * 1024); } while (0)
; #define PG8_LDB(dst, b, h) do { _Pragma("unroll") for (int n = 0; n < 2; ++n) _Pragma("unroll") for (int k = 0; k < 2; ++k) dst[n][k] = *(const LAS bf16x8*)(lds + PG8_SB(b, h) + boff + n * 2048 + k * 1024); } while (0)
; template <class Epi, class Sched, bool ALIGN_EPI>
; __device__ __forceinline__ void gemm_phase(LAS unsigned char* lds, const Gemm g, const Sched& S, const Epi& E) {
;     ...
;         for (int t = 0; t < nt; t += 2) {
;             const bool last = (t == nt - 2);
;             const char* a1 = cA + (size_t)(t + 1) * kstep;
;             const char* a2 = last ? nA : cA + (size_t)(t + 2) * kstep; const char* b2 = last ? nB : cB + (size_t)(t + 2) * kstep;
;             const char* a3 = a2 + kstep; const char* b3 = b2 + kstep;
;             PG8_LDB(B0, 0, 0); PG8_LDB(B1, 0, 1); PG8_SCHED; PG8_LDA(At, 0, 0); PG8_STAGE(PG8_SA(1, 1), a1 + hstepA, voffA);
;             PG8_WAIT_V(8); PG8_WAIT_L(0); PG8_BAR; PG8_MMA(0, 0, At, B0); PG8_MMA(0, 1, At, B1); PG8_BAR; PG8_SCHED;
;             PG8_LDA(At, 0, 1); PG8_STAGE(PG8_SB(0, 0), b2, voffB); PG8_STAGE(PG8_SB(0, 1), b2 + hstepB, voffB); PG8_STAGE(PG8_SA(0, 0), a2, voffA);
;             PG8_WAIT_V(8); PG8_WAIT_L(0); PG8_BAR; PG8_MMA(1, 0, At, B0); PG8_MMA(1, 1, At, B1); PG8_BAR; PG8_SCHED;
;             PG8_LDB(B0, 1, 0); PG8_LDB(B1, 1, 1); PG8_SCHED; PG8_LDA(At, 1, 0); PG8_STAGE(PG8_SA(0, 1), a2 + hstepA, voffA);
;             PG8_WAIT_V(8); PG8_WAIT_L(0); PG8_BAR; PG8_MMA(0, 0, At, B0); PG8_MMA(0, 1, At, B1); PG8_BAR; PG8_SCHED;
;             PG8_LDA(At, 1, 1); PG8_STAGE(PG8_SB(1, 0), b3, voffB); PG8_STAGE(PG8_SB(1, 1), b3 + hstepB, voffB); PG8_STAGE(PG8_SA(1, 0), a3, voffA);
;             PG8_WAIT_V(8); PG8_WAIT_L(0); PG8_BAR; PG8_MMA(1, 0, At, B0); PG8_MMA(1, 1, At, B1); PG8_BAR; PG8_SCHED;
	ds_read_b128 v[154:157], v144
	ds_read_b128 v[158:161], v144 offset:1024
	ds_read_b128 v[162:165], v144 offset:2048
	ds_read_b128 v[166:169], v144 offset:3072
	ds_read_b128 v[170:173], v145
	ds_read_b128 v[174:177], v145 offset:1024
	ds_read_b128 v[180:183], v145 offset:2048
	ds_read_b128 v[184:187], v145 offset:3072
	ds_read_b128 v[188:191], v143 offset:32768
	ds_read_b128 v[192:195], v143 offset:33792
	ds_read_b128 v[196:199], v143 offset:34816
	ds_read_b128 v[204:207], v143 offset:35840
	ds_read_b128 v[208:211], v143 offset:36864
	ds_read_b128 v[212:215], v143 offset:37888
	ds_read_b128 v[216:219], v143 offset:38912
	ds_read_b128 v[220:223], v143 offset:39936
	s_add_u32 s26, s36, 0x80000
	s_addc_u32 s27, s37, 0
	s_mov_b32 m0, s49
	s_nop 0
	global_load_lds_dwordx4 v134, s[26:27]
	s_nop 0
	s_mov_b32 m0, s50
	s_nop 0
	global_load_lds_dwordx4 v136, s[26:27]
	s_waitcnt vmcnt(8)
	s_waitcnt lgkmcnt(0)
	s_barrier
	s_setprio 1
	v_mfma_f32_16x16x32_bf16 v[126:129], v[154:157], v[188:191], v[126:129]
	v_mfma_f32_16x16x32_bf16 v[110:113], v[154:157], v[196:199], v[110:113]
	v_mfma_f32_16x16x32_bf16 v[94:97], v[154:157], v[208:211], v[94:97]
	v_mfma_f32_16x16x32_bf16 v[78:81], v[154:157], v[216:219], v[78:81]
	v_mfma_f32_16x16x32_bf16 v[74:77], v[162:165], v[216:219], v[74:77]
	v_mfma_f32_16x16x32_bf16 v[90:93], v[162:165], v[208:211], v[90:93]
	v_mfma_f32_16x16x32_bf16 v[106:109], v[162:165], v[196:199], v[106:109]
	v_mfma_f32_16x16x32_bf16 v[122:125], v[162:165], v[188:191], v[122:125]
	v_mfma_f32_16x16x32_bf16 v[122:125], v[166:169], v[192:195], v[122:125]
	v_mfma_f32_16x16x32_bf16 v[106:109], v[166:169], v[204:207], v[106:109]
	v_mfma_f32_16x16x32_bf16 v[90:93], v[166:169], v[212:215], v[90:93]
	v_mfma_f32_16x16x32_bf16 v[74:77], v[166:169], v[220:223], v[74:77]
	v_mfma_f32_16x16x32_bf16 v[78:81], v[158:161], v[220:223], v[78:81]
	v_mfma_f32_16x16x32_bf16 v[94:97], v[158:161], v[212:215], v[94:97]
	v_mfma_f32_16x16x32_bf16 v[110:113], v[158:161], v[204:207], v[110:113]
	v_mfma_f32_16x16x32_bf16 v[126:129], v[158:161], v[192:195], v[126:129]
	v_mfma_f32_16x16x32_bf16 v[118:121], v[170:173], v[188:191], v[118:121]
	v_mfma_f32_16x16x32_bf16 v[102:105], v[170:173], v[196:199], v[102:105]
	v_mfma_f32_16x16x32_bf16 v[86:89], v[170:173], v[208:211], v[86:89]
	v_mfma_f32_16x16x32_bf16 v[70:73], v[170:173], v[216:219], v[70:73]
	v_mfma_f32_16x16x32_bf16 v[66:69], v[180:183], v[216:219], v[66:69]
	v_mfma_f32_16x16x32_bf16 v[82:85], v[180:183], v[208:211], v[82:85]
	v_mfma_f32_16x16x32_bf16 v[98:101], v[180:183], v[196:199], v[98:101]
	v_mfma_f32_16x16x32_bf16 v[114:117], v[180:183], v[188:191], v[114:117]
	v_mfma_f32_16x16x32_bf16 v[114:117], v[184:187], v[192:195], v[114:117]
	v_mfma_f32_16x16x32_bf16 v[98:101], v[184:187], v[204:207], v[98:101]
	v_mfma_f32_16x16x32_bf16 v[82:85], v[184:187], v[212:215], v[82:85]
	v_mfma_f32_16x16x32_bf16 v[66:69], v[184:187], v[220:223], v[66:69]
	v_mfma_f32_16x16x32_bf16 v[70:73], v[174:177], v[220:223], v[70:73]
	v_mfma_f32_16x16x32_bf16 v[86:89], v[174:177], v[212:215], v[86:89]
	v_mfma_f32_16x16x32_bf16 v[102:105], v[174:177], v[204:207], v[102:105]
	v_mfma_f32_16x16x32_bf16 v[118:121], v[174:177], v[192:195], v[118:121]
	s_setprio 0
	s_barrier
	ds_read_b128 v[188:191], v143 offset:49152
	ds_read_b128 v[192:195], v143 offset:50176
	ds_read_b128 v[196:199], v143 offset:51200
	ds_read_b128 v[204:207], v143 offset:52224
	ds_read_b128 v[208:211], v143 offset:53248
	ds_read_b128 v[212:215], v143 offset:54272
	ds_read_b128 v[216:219], v143 offset:55296
	ds_read_b128 v[220:223], v143 offset:56320
	s_add_u32 s26, s34, 0x80
	s_addc_u32 s27, s35, 0
	s_mov_b32 m0, s51
	s_nop 0
	global_load_lds_dwordx4 v135, s[26:27]
	s_nop 0
	s_mov_b32 m0, s52
	s_nop 0
	global_load_lds_dwordx4 v137, s[26:27]
	s_add_u32 s26, s34, 0x80080
	s_addc_u32 s27, s35, 0
	s_mov_b32 m0, s55
	s_nop 0
	global_load_lds_dwordx4 v135, s[26:27]
	s_nop 0
	s_mov_b32 m0, s56
	s_nop 0
	global_load_lds_dwordx4 v137, s[26:27]
	s_mov_b32 m0, s53
	s_nop 0
	global_load_lds_dwordx4 v134, s[30:31]
	s_nop 0
	s_mov_b32 m0, s54
	s_nop 0
	global_load_lds_dwordx4 v136, s[30:31]
	s_waitcnt vmcnt(8)
	s_waitcnt lgkmcnt(0)
	s_barrier
	s_setprio 1
	v_mfma_f32_16x16x32_bf16 v[62:65], v[154:157], v[188:191], v[62:65]
	v_mfma_f32_16x16x32_bf16 v[46:49], v[154:157], v[196:199], v[46:49]
	v_mfma_f32_16x16x32_bf16 v[30:33], v[154:157], v[208:211], v[30:33]
	v_mfma_f32_16x16x32_bf16 v[14:17], v[154:157], v[216:219], v[14:17]
	v_mfma_f32_16x16x32_bf16 v[10:13], v[162:165], v[216:219], v[10:13]
	v_mfma_f32_16x16x32_bf16 v[26:29], v[162:165], v[208:211], v[26:29]
	v_mfma_f32_16x16x32_bf16 v[42:45], v[162:165], v[196:199], v[42:45]
	v_mfma_f32_16x16x32_bf16 v[58:61], v[162:165], v[188:191], v[58:61]
	v_mfma_f32_16x16x32_bf16 v[58:61], v[166:169], v[192:195], v[58:61]
	v_mfma_f32_16x16x32_bf16 v[42:45], v[166:169], v[204:207], v[42:45]
	v_mfma_f32_16x16x32_bf16 v[26:29], v[166:169], v[212:215], v[26:29]
	v_mfma_f32_16x16x32_bf16 v[10:13], v[166:169], v[220:223], v[10:13]
	v_mfma_f32_16x16x32_bf16 v[14:17], v[158:161], v[220:223], v[14:17]
	v_mfma_f32_16x16x32_bf16 v[30:33], v[158:161], v[212:215], v[30:33]
	v_mfma_f32_16x16x32_bf16 v[46:49], v[158:161], v[204:207], v[46:49]
	v_mfma_f32_16x16x32_bf16 v[62:65], v[158:161], v[192:195], v[62:65]
	v_mfma_f32_16x16x32_bf16 v[54:57], v[170:173], v[188:191], v[54:57]
	v_mfma_f32_16x16x32_bf16 v[38:41], v[170:173], v[196:199], v[38:41]
	v_mfma_f32_16x16x32_bf16 v[22:25], v[170:173], v[208:211], v[22:25]
	v_mfma_f32_16x16x32_bf16 v[6:9], v[170:173], v[216:219], v[6:9]
	v_mfma_f32_16x16x32_bf16 v[2:5], v[180:183], v[216:219], v[2:5]
	v_mfma_f32_16x16x32_bf16 v[18:21], v[180:183], v[208:211], v[18:21]
	v_mfma_f32_16x16x32_bf16 v[34:37], v[180:183], v[196:199], v[34:37]
	v_mfma_f32_16x16x32_bf16 v[50:53], v[180:183], v[188:191], v[50:53]
	v_mfma_f32_16x16x32_bf16 v[50:53], v[184:187], v[192:195], v[50:53]
	v_mfma_f32_16x16x32_bf16 v[34:37], v[184:187], v[204:207], v[34:37]
	v_mfma_f32_16x16x32_bf16 v[18:21], v[184:187], v[212:215], v[18:21]
	v_mfma_f32_16x16x32_bf16 v[2:5], v[184:187], v[220:223], v[2:5]
	v_mfma_f32_16x16x32_bf16 v[6:9], v[174:177], v[220:223], v[6:9]
	v_mfma_f32_16x16x32_bf16 v[22:25], v[174:177], v[212:215], v[22:25]
	v_mfma_f32_16x16x32_bf16 v[38:41], v[174:177], v[204:207], v[38:41]
	v_mfma_f32_16x16x32_bf16 v[54:57], v[174:177], v[192:195], v[54:57]
	s_setprio 0
	s_barrier
	s_add_i32 s60, s60, 2
	s_add_u32 s19, s19, 0x100
	s_addc_u32 s21, s21, 0
	s_cmp_gt_u32 s60, 29
	s_mov_b64 s[26:27], s[28:29]
	s_cbranch_scc0 .LBB0_2075
	s_and_b64 vcc, exec, s[16:17]
	s_cbranch_vccz .LBB0_2078
	s_barrier

; #define PG8_STAGE(bufoff, gbase, voff) do { _Pragma("unroll") for (int _i = 0; _i < 2; ++_i) { unsigned keep_; \
;         asm volatile("s_mov_b32 %0, m0\n\ts_mov_b32 m0, %3\n\ts_nop 0\n\tglobal_load_lds_dwordx4 %1, %2\n\ts_mov_b32 m0, %0" \
;             : "=&s"(keep_) : "v"((voff)[_i]), "s"((const void*)(gbase)), "s"(ldsb0 + (unsigned)(bufoff) + (unsigned)(_i * 8192)) : "memory"); } } while (0)
; #define PG8_LDA(dst, b, h) do { _Pragma("unroll") for (int m = 0; m < 4; ++m) _Pragma("unroll") for (int k = 0; k < 2; ++k) dst[m][k] = *(const LAS bf16x8*)(lds + PG8_SA(b, h) + aoff + m * 2048 + k * 1024); } while (0)
; #define PG8_LDB(dst, b, h) do { _Pragma("unroll") for (int n = 0; n < 2; ++n) _Pragma("unroll") for (int k = 0; k < 2; ++k) dst[n][k] = *(const LAS bf16x8*)(lds + PG8_SB(b, h) + boff + n * 2048 + k * 1024); } while (0)
; template <class Epi, class Sched, bool ALIGN_EPI>
; __device__ __forceinline__ void gemm_phase(LAS unsigned char* lds, const Gemm g, const Sched& S, const Epi& E) {
;     ...
;         for (int t = 0; t < nt; t += 2) {
;             const bool last = (t == nt - 2);
;             const char* a1 = cA + (size_t)(t + 1) * kstep;
;             const char* a2 = last ? nA : cA + (size_t)(t + 2) * kstep; const char* b2 = last ? nB : cB + (size_t)(t + 2) * kstep;
;             const char* a3 = a2 + kstep; const char* b3 = b2 + kstep;
;             PG8_LDB(B0, 0, 0); PG8_LDB(B1, 0, 1); PG8_SCHED; PG8_LDA(At, 0, 0); PG8_STAGE(PG8_SA(1, 1), a1 + hstepA, voffA);
;             PG8_WAIT_V(8); PG8_WAIT_L(0); PG8_BAR; PG8_MMA(0, 0, At, B0); PG8_MMA(0, 1, At, B1); PG8_BAR; PG8_SCHED;
;             PG8_LDA(At, 0, 1); PG8_STAGE(PG8_SB(0, 0), b2, voffB); PG8_STAGE(PG8_SB(0, 1), b2 + hstepB, voffB); PG8_STAGE(PG8_SA(0, 0), a2, voffA);
;             PG8_WAIT_V(8); PG8_WAIT_L(0); PG8_BAR; PG8_MMA(1, 0, At, B0); PG8_MMA(1, 1, At, B1); PG8_BAR; PG8_SCHED;
;             PG8_LDB(B0, 1, 0); PG8_LDB(B1, 1, 1); PG8_SCHED; PG8_LDA(At, 1, 0); PG8_STAGE(PG8_SA(0, 1), a2 + hstepA, voffA);
;             PG8_WAIT_V(8); PG8_WAIT_L(0); PG8_BAR; PG8_MMA(0, 0, At, B0); PG8_MMA(0, 1, At, B1); PG8_BAR; PG8_SCHED;
;             PG8_LDA(At, 1, 1); PG8_STAGE(PG8_SB(1, 0), b3, voffB); PG8_STAGE(PG8_SB(1, 1), b3 + hstepB, voffB); PG8_STAGE(PG8_SA(1, 0), a3, voffA);
;             PG8_WAIT_V(8); PG8_WAIT_L(0); PG8_BAR; PG8_MMA(1, 0, At, B0); PG8_MMA(1, 1, At, B1); PG8_BAR; PG8_SCHED;
.LBB0_2172:
	s_add_u32 s61, s22, s26
	s_addc_u32 s63, s23, s27
	s_add_u32 s28, s61, 0x100
	v_add_u32_e32 v141, 0x10000, v139
	s_addc_u32 s29, s63, 0
	ds_read_b128 v[142:145], v141
	ds_read_b128 v[146:149], v141 offset:1024
	ds_read_b128 v[150:153], v141 offset:2048
	ds_read_b128 v[154:157], v141 offset:3072
	v_add_u32_e32 v141, 0x14000, v139
	s_add_u32 s30, s20, s26
	ds_read_b128 v[158:161], v141
	ds_read_b128 v[162:165], v141 offset:1024
	ds_read_b128 v[166:169], v141 offset:2048
	ds_read_b128 v[170:173], v141 offset:3072
	s_addc_u32 s31, s21, s27
	s_add_u32 s30, s30, 0x100
	s_addc_u32 s31, s31, 0
	s_cmpk_eq_i32 s60, 0x54
	s_cselect_b32 s34, s12, s28
	s_cselect_b32 s35, s13, s29
	s_cselect_b32 s30, s24, s30
	s_cselect_b32 s31, s25, s31
	s_add_u32 s28, s34, 0x80
	s_addc_u32 s29, s35, 0
	ds_read_b128 v[174:177], v140
	ds_read_b128 v[178:181], v140 offset:1024
	ds_read_b128 v[182:185], v140 offset:2048
	ds_read_b128 v[186:189], v140 offset:3072
	ds_read_b128 v[190:193], v140 offset:4096
	ds_read_b128 v[194:197], v140 offset:5120
	ds_read_b128 v[198:201], v140 offset:6144
	ds_read_b128 v[204:207], v140 offset:7168
	s_add_u32 s62, s61, 0x160080
	s_addc_u32 s63, s63, 0
	s_mov_b32 m0, s54
	s_nop 0
	global_load_lds_dwordx4 v131, s[62:63]
	s_nop 0
	s_mov_b32 m0, s55
	s_nop 0
	global_load_lds_dwordx4 v137, s[62:63]
	s_waitcnt vmcnt(8)
	s_waitcnt lgkmcnt(0)
	s_barrier
	s_setprio 1
	v_mfma_f32_16x16x32_bf16 v[126:129], v[142:145], v[174:177], v[126:129]
	v_mfma_f32_16x16x32_bf16 v[110:113], v[142:145], v[182:185], v[110:113]
	v_mfma_f32_16x16x32_bf16 v[94:97], v[142:145], v[190:193], v[94:97]
	v_mfma_f32_16x16x32_bf16 v[78:81], v[142:145], v[198:201], v[78:81]
	v_mfma_f32_16x16x32_bf16 v[74:77], v[150:153], v[198:201], v[74:77]
	v_mfma_f32_16x16x32_bf16 v[90:93], v[150:153], v[190:193], v[90:93]
	v_mfma_f32_16x16x32_bf16 v[106:109], v[150:153], v[182:185], v[106:109]
	v_mfma_f32_16x16x32_bf16 v[122:125], v[150:153], v[174:177], v[122:125]
	v_mfma_f32_16x16x32_bf16 v[122:125], v[154:157], v[178:181], v[122:125]
	v_mfma_f32_16x16x32_bf16 v[106:109], v[154:157], v[186:189], v[106:109]
	v_mfma_f32_16x16x32_bf16 v[90:93], v[154:157], v[194:197], v[90:93]
	v_mfma_f32_16x16x32_bf16 v[74:77], v[154:157], v[204:207], v[74:77]
	v_mfma_f32_16x16x32_bf16 v[78:81], v[146:149], v[204:207], v[78:81]
	v_mfma_f32_16x16x32_bf16 v[94:97], v[146:149], v[194:197], v[94:97]
	v_mfma_f32_16x16x32_bf16 v[110:113], v[146:149], v[186:189], v[110:113]
	v_mfma_f32_16x16x32_bf16 v[126:129], v[146:149], v[178:181], v[126:129]
	v_mfma_f32_16x16x32_bf16 v[118:121], v[158:161], v[174:177], v[118:121]
	v_mfma_f32_16x16x32_bf16 v[102:105], v[158:161], v[182:185], v[102:105]
	v_mfma_f32_16x16x32_bf16 v[86:89], v[158:161], v[190:193], v[86:89]
	v_mfma_f32_16x16x32_bf16 v[70:73], v[158:161], v[198:201], v[70:73]
	v_mfma_f32_16x16x32_bf16 v[66:69], v[166:169], v[198:201], v[66:69]
	v_mfma_f32_16x16x32_bf16 v[82:85], v[166:169], v[190:193], v[82:85]
	v_mfma_f32_16x16x32_bf16 v[98:101], v[166:169], v[182:185], v[98:101]
	v_mfma_f32_16x16x32_bf16 v[114:117], v[166:169], v[174:177], v[114:117]
	v_mfma_f32_16x16x32_bf16 v[114:117], v[170:173], v[178:181], v[114:117]
	v_mfma_f32_16x16x32_bf16 v[98:101], v[170:173], v[186:189], v[98:101]
	v_mfma_f32_16x16x32_bf16 v[82:85], v[170:173], v[194:197], v[82:85]
	v_mfma_f32_16x16x32_bf16 v[66:69], v[170:173], v[204:207], v[66:69]
	v_mfma_f32_16x16x32_bf16 v[70:73], v[162:165], v[204:207], v[70:73]
	v_mfma_f32_16x16x32_bf16 v[86:89], v[162:165], v[194:197], v[86:89]
	v_mfma_f32_16x16x32_bf16 v[102:105], v[162:165], v[186:189], v[102:105]
	v_mfma_f32_16x16x32_bf16 v[118:121], v[162:165], v[178:181], v[118:121]
	s_setprio 0
	s_barrier
	ds_read_b128 v[174:177], v140 offset:16384
	ds_read_b128 v[178:181], v140 offset:17408
	ds_read_b128 v[182:185], v140 offset:18432
	ds_read_b128 v[186:189], v140 offset:19456
	ds_read_b128 v[190:193], v140 offset:20480
	ds_read_b128 v[194:197], v140 offset:21504
	ds_read_b128 v[198:201], v140 offset:22528
	ds_read_b128 v[204:207], v140 offset:23552
	s_mov_b32 m0, s3
	s_nop 0
	global_load_lds_dwordx4 v136, s[30:31]
	s_add_u32 s62, s30, 0x160000
	s_mov_b32 m0, s41
	s_nop 0
	global_load_lds_dwordx4 v138, s[30:31]
	s_addc_u32 s63, s31, 0
	s_mov_b32 m0, s42
	s_nop 0
	global_load_lds_dwordx4 v136, s[62:63]
	s_nop 0
	s_mov_b32 m0, s43
	s_nop 0
	global_load_lds_dwordx4 v138, s[62:63]
	s_nop 0
	s_mov_b32 m0, s2
	s_nop 0
	global_load_lds_dwordx4 v131, s[34:35]
	s_nop 0
	s_mov_b32 m0, s44
	s_nop 0
	global_load_lds_dwordx4 v137, s[34:35]
	s_waitcnt vmcnt(8)
	s_waitcnt lgkmcnt(0)
	s_barrier
; #define PG8_STAGE(bufoff, gbase, voff) do { _Pragma("unroll") for (int _i = 0; _i < 2; ++_i) { unsigned keep_; \
;         asm volatile("s_mov_b32 %0, m0\n\ts_mov_b32 m0, %3\n\ts_nop 0\n\tglobal_load_lds_dwordx4 %1, %2\n\ts_mov_b32 m0, %0" \
;             : "=&s"(keep_) : "v"((voff)[_i]), "s"((const void*)(gbase)), "s"(ldsb0 + (unsigned)(bufoff) + (unsigned)(_i * 8192)) : "memory"); } } while (0)
; #define PG8_LDA(dst, b, h) do { _Pragma("unroll") for (int m = 0; m < 4; ++m) _Pragma("unroll") for (int k = 0; k < 2; ++k) dst[m][k] = *(const LAS bf16x8*)(lds + PG8_SA(b, h) + aoff + m * 2048 + k * 1024); } while (0)
; #define PG8_LDB(dst, b, h) do { _Pragma("unroll") for (int n = 0; n < 2; ++n) _Pragma("unroll") for (int k = 0; k < 2; ++k) dst[n][k] = *(const LAS bf16x8*)(lds + PG8_SB(b, h) + boff + n * 2048 + k * 1024); } while (0)
; template <class Epi, class Sched, bool ALIGN_EPI>
; __device__ __forceinline__ void gemm_phase(LAS unsigned char* lds, const Gemm g, const Sched& S, const Epi& E) {
;     ...
;         for (int t = 0; t < nt; t += 2) {
;             const bool last = (t == nt - 2);
;             const char* a1 = cA + (size_t)(t + 1) * kstep;
;             const char* a2 = last ? nA : cA + (size_t)(t + 2) * kstep; const char* b2 = last ? nB : cB + (size_t)(t + 2) * kstep;
;             const char* a3 = a2 + kstep; const char* b3 = b2 + kstep;
;             PG8_LDB(B0, 0, 0); PG8_LDB(B1, 0, 1); PG8_SCHED; PG8_LDA(At, 0, 0); PG8_STAGE(PG8_SA(1, 1), a1 + hstepA, voffA);
;             PG8_WAIT_V(8); PG8_WAIT_L(0); PG8_BAR; PG8_MMA(0, 0, At, B0); PG8_MMA(0, 1, At, B1); PG8_BAR; PG8_SCHED;
;             PG8_LDA(At, 0, 1); PG8_STAGE(PG8_SB(0, 0), b2, voffB); PG8_STAGE(PG8_SB(0, 1), b2 + hstepB, voffB); PG8_STAGE(PG8_SA(0, 0), a2, voffA);
;             PG8_WAIT_V(8); PG8_WAIT_L(0); PG8_BAR; PG8_MMA(1, 0, At, B0); PG8_MMA(1, 1, At, B1); PG8_BAR; PG8_SCHED;
;             PG8_LDB(B0, 1, 0); PG8_LDB(B1, 1, 1); PG8_SCHED; PG8_LDA(At, 1, 0); PG8_STAGE(PG8_SA(0, 1), a2 + hstepA, voffA);
;             PG8_WAIT_V(8); PG8_WAIT_L(0); PG8_BAR; PG8_MMA(0, 0, At, B0); PG8_MMA(0, 1, At, B1); PG8_BAR; PG8_SCHED;
;             PG8_LDA(At, 1, 1); PG8_STAGE(PG8_SB(1, 0), b3, voffB); PG8_STAGE(PG8_SB(1, 1), b3 + hstepB, voffB); PG8_STAGE(PG8_SA(1, 0), a3, voffA);
;             PG8_WAIT_V(8); PG8_WAIT_L(0); PG8_BAR; PG8_MMA(1, 0, At, B0); PG8_MMA(1, 1, At, B1); PG8_BAR; PG8_SCHED;
	s_setprio 1
	v_mfma_f32_16x16x32_bf16 v[62:65], v[142:145], v[174:177], v[62:65]
	v_mfma_f32_16x16x32_bf16 v[46:49], v[142:145], v[182:185], v[46:49]
	v_mfma_f32_16x16x32_bf16 v[30:33], v[142:145], v[190:193], v[30:33]
	v_mfma_f32_16x16x32_bf16 v[14:17], v[142:145], v[198:201], v[14:17]
	v_mfma_f32_16x16x32_bf16 v[10:13], v[150:153], v[198:201], v[10:13]
	v_mfma_f32_16x16x32_bf16 v[26:29], v[150:153], v[190:193], v[26:29]
	v_mfma_f32_16x16x32_bf16 v[42:45], v[150:153], v[182:185], v[42:45]
	v_mfma_f32_16x16x32_bf16 v[58:61], v[150:153], v[174:177], v[58:61]
	v_mfma_f32_16x16x32_bf16 v[58:61], v[154:157], v[178:181], v[58:61]
	v_mfma_f32_16x16x32_bf16 v[42:45], v[154:157], v[186:189], v[42:45]
	v_mfma_f32_16x16x32_bf16 v[26:29], v[154:157], v[194:197], v[26:29]
	v_mfma_f32_16x16x32_bf16 v[10:13], v[154:157], v[204:207], v[10:13]
	v_mfma_f32_16x16x32_bf16 v[14:17], v[146:149], v[204:207], v[14:17]
	v_mfma_f32_16x16x32_bf16 v[30:33], v[146:149], v[194:197], v[30:33]
	v_mfma_f32_16x16x32_bf16 v[46:49], v[146:149], v[186:189], v[46:49]
	v_mfma_f32_16x16x32_bf16 v[62:65], v[146:149], v[178:181], v[62:65]
	v_mfma_f32_16x16x32_bf16 v[54:57], v[158:161], v[174:177], v[54:57]
	v_mfma_f32_16x16x32_bf16 v[38:41], v[158:161], v[182:185], v[38:41]
	v_mfma_f32_16x16x32_bf16 v[22:25], v[158:161], v[190:193], v[22:25]
	v_mfma_f32_16x16x32_bf16 v[6:9], v[158:161], v[198:201], v[6:9]
	v_mfma_f32_16x16x32_bf16 v[2:5], v[166:169], v[198:201], v[2:5]
	v_mfma_f32_16x16x32_bf16 v[18:21], v[166:169], v[190:193], v[18:21]
	v_mfma_f32_16x16x32_bf16 v[34:37], v[166:169], v[182:185], v[34:37]
	v_mfma_f32_16x16x32_bf16 v[50:53], v[166:169], v[174:177], v[50:53]
	v_mfma_f32_16x16x32_bf16 v[50:53], v[170:173], v[178:181], v[50:53]
	v_mfma_f32_16x16x32_bf16 v[34:37], v[170:173], v[186:189], v[34:37]
	v_mfma_f32_16x16x32_bf16 v[18:21], v[170:173], v[194:197], v[18:21]
	v_mfma_f32_16x16x32_bf16 v[2:5], v[170:173], v[204:207], v[2:5]
	v_mfma_f32_16x16x32_bf16 v[6:9], v[162:165], v[204:207], v[6:9]
	v_mfma_f32_16x16x32_bf16 v[22:25], v[162:165], v[194:197], v[22:25]
	v_mfma_f32_16x16x32_bf16 v[38:41], v[162:165], v[186:189], v[38:41]
	v_mfma_f32_16x16x32_bf16 v[54:57], v[162:165], v[178:181], v[54:57]
	s_setprio 0
	s_barrier
	v_add_u32_e32 v141, 0x18000, v139
	ds_read_b128 v[142:145], v141
	ds_read_b128 v[146:149], v141 offset:1024
	ds_read_b128 v[150:153], v141 offset:2048
	ds_read_b128 v[154:157], v141 offset:3072
	v_add_u32_e32 v141, 0x1c000, v139
	ds_read_b128 v[158:161], v141
	ds_read_b128 v[162:165], v141 offset:1024
	ds_read_b128 v[166:169], v141 offset:2048
	ds_read_b128 v[170:173], v141 offset:3072
	ds_read_b128 v[174:177], v140 offset:32768
	ds_read_b128 v[178:181], v140 offset:33792
	ds_read_b128 v[182:185], v140 offset:34816
	ds_read_b128 v[186:189], v140 offset:35840
	ds_read_b128 v[190:193], v140 offset:36864
	ds_read_b128 v[194:197], v140 offset:37888
	ds_read_b128 v[198:201], v140 offset:38912
	ds_read_b128 v[204:207], v140 offset:39936
	s_add_u32 s34, s34, 0x160000
	s_addc_u32 s35, s35, 0
	s_mov_b32 m0, s46
	s_nop 0
	global_load_lds_dwordx4 v131, s[34:35]
	s_nop 0
	s_mov_b32 m0, s47
	s_nop 0
	global_load_lds_dwordx4 v137, s[34:35]
	s_waitcnt vmcnt(8)
	s_waitcnt lgkmcnt(0)
	s_barrier
	s_setprio 1
	v_mfma_f32_16x16x32_bf16 v[126:129], v[142:145], v[174:177], v[126:129]
	v_mfma_f32_16x16x32_bf16 v[110:113], v[142:145], v[182:185], v[110:113]
	v_mfma_f32_16x16x32_bf16 v[94:97], v[142:145], v[190:193], v[94:97]
	v_mfma_f32_16x16x32_bf16 v[78:81], v[142:145], v[198:201], v[78:81]
	v_mfma_f32_16x16x32_bf16 v[74:77], v[150:153], v[198:201], v[74:77]
	v_mfma_f32_16x16x32_bf16 v[90:93], v[150:153], v[190:193], v[90:93]
	v_mfma_f32_16x16x32_bf16 v[106:109], v[150:153], v[182:185], v[106:109]
	v_mfma_f32_16x16x32_bf16 v[122:125], v[150:153], v[174:177], v[122:125]
	v_mfma_f32_16x16x32_bf16 v[122:125], v[154:157], v[178:181], v[122:125]
	v_mfma_f32_16x16x32_bf16 v[106:109], v[154:157], v[186:189], v[106:109]
	v_mfma_f32_16x16x32_bf16 v[90:93], v[154:157], v[194:197], v[90:93]
	v_mfma_f32_16x16x32_bf16 v[74:77], v[154:157], v[204:207], v[74:77]
	v_mfma_f32_16x16x32_bf16 v[78:81], v[146:149], v[204:207], v[78:81]
	v_mfma_f32_16x16x32_bf16 v[94:97], v[146:149], v[194:197], v[94:97]
	v_mfma_f32_16x16x32_bf16 v[110:113], v[146:149], v[186:189], v[110:113]
	v_mfma_f32_16x16x32_bf16 v[126:129], v[146:149], v[178:181], v[126:129]
	v_mfma_f32_16x16x32_bf16 v[118:121], v[158:161], v[174:177], v[118:121]
	v_mfma_f32_16x16x32_bf16 v[102:105], v[158:161], v[182:185], v[102:105]
	v_mfma_f32_16x16x32_bf16 v[86:89], v[158:161], v[190:193], v[86:89]
	v_mfma_f32_16x16x32_bf16 v[70:73], v[158:161], v[198:201], v[70:73]
	v_mfma_f32_16x16x32_bf16 v[66:69], v[166:169], v[198:201], v[66:69]
	v_mfma_f32_16x16x32_bf16 v[82:85], v[166:169], v[190:193], v[82:85]
	v_mfma_f32_16x16x32_bf16 v[98:101], v[166:169], v[182:185], v[98:101]
	v_mfma_f32_16x16x32_bf16 v[114:117], v[166:169], v[174:177], v[114:117]
	v_mfma_f32_16x16x32_bf16 v[114:117], v[170:173], v[178:181], v[114:117]
	v_mfma_f32_16x16x32_bf16 v[98:101], v[170:173], v[186:189], v[98:101]
	v_mfma_f32_16x16x32_bf16 v[82:85], v[170:173], v[194:197], v[82:85]
	v_mfma_f32_16x16x32_bf16 v[66:69], v[170:173], v[204:207], v[66:69]
	v_mfma_f32_16x16x32_bf16 v[70:73], v[162:165], v[204:207], v[70:73]
	v_mfma_f32_16x16x32_bf16 v[86:89], v[162:165], v[194:197], v[86:89]
	v_mfma_f32_16x16x32_bf16 v[102:105], v[162:165], v[186:189], v[102:105]
	v_mfma_f32_16x16x32_bf16 v[118:121], v[162:165], v[178:181], v[118:121]
	s_setprio 0
	s_barrier
; #define PG8_LDA(dst, b, h) do { _Pragma("unroll") for (int m = 0; m < 4; ++m) _Pragma("unroll") for (int k = 0; k < 2; ++k) dst[m][k] = *(const LAS bf16x8*)(lds + PG8_SA(b, h) + aoff + m * 2048 + k * 1024); } while (0)
; template <class Epi, class Sched, bool ALIGN_EPI>
; __device__ __forceinline__ void gemm_phase(LAS unsigned char* lds, const Gemm g, const Sched& S, const Epi& E) {
;     ...
;         for (int t = 0; t < nt; t += 2) {
;             const bool last = (t == nt - 2);
;             const char* a1 = cA + (size_t)(t + 1) * kstep;
;             const char* a2 = last ? nA : cA + (size_t)(t + 2) * kstep; const char* b2 = last ? nB : cB + (size_t)(t + 2) * kstep;
;             const char* a3 = a2 + kstep; const char* b3 = b2 + kstep;
;             PG8_LDB(B0, 0, 0); PG8_LDB(B1, 0, 1); PG8_SCHED; PG8_LDA(At, 0, 0); PG8_STAGE(PG8_SA(1, 1), a1 + hstepA, voffA);
;             PG8_WAIT_V(8); PG8_WAIT_L(0); PG8_BAR; PG8_MMA(0, 0, At, B0); PG8_MMA(0, 1, At, B1); PG8_BAR; PG8_SCHED;
;             PG8_LDA(At, 0, 1); PG8_STAGE(PG8_SB(0, 0), b2, voffB); PG8_STAGE(PG8_SB(0, 1), b2 + hstepB, voffB); PG8_STAGE(PG8_SA(0, 0), a2, voffA);
;             PG8_WAIT_V(8); PG8_WAIT_L(0); PG8_BAR; PG8_MMA(1, 0, At, B0); PG8_MMA(1, 1, At, B1); PG8_BAR; PG8_SCHED;
;             PG8_LDB(B0, 1, 0); PG8_LDB(B1, 1, 1); PG8_SCHED; PG8_LDA(At, 1, 0); PG8_STAGE(PG8_SA(0, 1), a2 + hstepA, voffA);
;             PG8_WAIT_V(8); PG8_WAIT_L(0); PG8_BAR; PG8_MMA(0, 0, At, B0); PG8_MMA(0, 1, At, B1); PG8_BAR; PG8_SCHED;
;             PG8_LDA(At, 1, 1); PG8_STAGE(PG8_SB(1, 0), b3, voffB); PG8_STAGE(PG8_SB(1, 1), b3 + hstepB, voffB); PG8_STAGE(PG8_SA(1, 0), a3, voffA);
;             PG8_WAIT_V(8); PG8_WAIT_L(0); PG8_BAR; PG8_MMA(1, 0, At, B0); PG8_MMA(1, 1, At, B1); PG8_BAR; PG8_SCHED;
;         }
;         if constexpr (ALIGN_EPI) { if (wr == 0) PG8_BAR; }
;         if constexpr (Epi::NPRE > 0) E(acc, cur, wr, wc, fr, fq, pre); else
;         if constexpr (!Epi::AFTER_DRAIN) E(acc, cur, wr, wc, fr, fq);
;         if (!has_next) break;
; #pragma unroll
;         for (int a = 0; a < 2; ++a)
; #pragma unroll
;             for (int b = 0; b < 2; ++b)
; #pragma unroll
;                 for (int m = 0; m < 4; ++m)
; #pragma unroll
;                     for (int n = 0; n < 2; ++n) acc[a][b][m][n] = (f32x4){0.f, 0.f, 0.f, 0.f};
;         cur = nxt; cA = nA; cB = nB; ++ui;
	ds_read_b128 v[174:177], v140 offset:49152
	ds_read_b128 v[178:181], v140 offset:50176
	ds_read_b128 v[182:185], v140 offset:51200
	ds_read_b128 v[186:189], v140 offset:52224
	ds_read_b128 v[190:193], v140 offset:53248
	ds_read_b128 v[194:197], v140 offset:54272
	ds_read_b128 v[198:201], v140 offset:55296
	ds_read_b128 v[204:207], v140 offset:56320
	s_add_u32 s34, s30, 0x80
	s_addc_u32 s35, s31, 0
	s_mov_b32 m0, s48
	s_nop 0
	global_load_lds_dwordx4 v136, s[34:35]
	s_add_u32 s30, s30, 0x160080
	s_mov_b32 m0, s49
	s_nop 0
	global_load_lds_dwordx4 v138, s[34:35]
	s_addc_u32 s31, s31, 0
	s_mov_b32 m0, s52
	s_nop 0
	global_load_lds_dwordx4 v136, s[30:31]
	s_nop 0
	s_mov_b32 m0, s53
	s_nop 0
	global_load_lds_dwordx4 v138, s[30:31]
	s_mov_b32 m0, s50
	s_nop 0
	global_load_lds_dwordx4 v131, s[28:29]
	s_nop 0
	s_mov_b32 m0, s51
	s_nop 0
	global_load_lds_dwordx4 v137, s[28:29]
	s_waitcnt vmcnt(8)
	s_waitcnt lgkmcnt(0)
	s_barrier
	s_setprio 1
	v_mfma_f32_16x16x32_bf16 v[62:65], v[142:145], v[174:177], v[62:65]
	v_mfma_f32_16x16x32_bf16 v[46:49], v[142:145], v[182:185], v[46:49]
	v_mfma_f32_16x16x32_bf16 v[30:33], v[142:145], v[190:193], v[30:33]
	v_mfma_f32_16x16x32_bf16 v[14:17], v[142:145], v[198:201], v[14:17]
	v_mfma_f32_16x16x32_bf16 v[10:13], v[150:153], v[198:201], v[10:13]
	v_mfma_f32_16x16x32_bf16 v[26:29], v[150:153], v[190:193], v[26:29]
	v_mfma_f32_16x16x32_bf16 v[42:45], v[150:153], v[182:185], v[42:45]
	v_mfma_f32_16x16x32_bf16 v[58:61], v[150:153], v[174:177], v[58:61]
	v_mfma_f32_16x16x32_bf16 v[58:61], v[154:157], v[178:181], v[58:61]
	v_mfma_f32_16x16x32_bf16 v[42:45], v[154:157], v[186:189], v[42:45]
	v_mfma_f32_16x16x32_bf16 v[26:29], v[154:157], v[194:197], v[26:29]
	v_mfma_f32_16x16x32_bf16 v[10:13], v[154:157], v[204:207], v[10:13]
	v_mfma_f32_16x16x32_bf16 v[14:17], v[146:149], v[204:207], v[14:17]
	v_mfma_f32_16x16x32_bf16 v[30:33], v[146:149], v[194:197], v[30:33]
	v_mfma_f32_16x16x32_bf16 v[46:49], v[146:149], v[186:189], v[46:49]
	v_mfma_f32_16x16x32_bf16 v[62:65], v[146:149], v[178:181], v[62:65]
	v_mfma_f32_16x16x32_bf16 v[54:57], v[158:161], v[174:177], v[54:57]
	v_mfma_f32_16x16x32_bf16 v[38:41], v[158:161], v[182:185], v[38:41]
	v_mfma_f32_16x16x32_bf16 v[22:25], v[158:161], v[190:193], v[22:25]
	v_mfma_f32_16x16x32_bf16 v[6:9], v[158:161], v[198:201], v[6:9]
	v_mfma_f32_16x16x32_bf16 v[2:5], v[166:169], v[198:201], v[2:5]
	v_mfma_f32_16x16x32_bf16 v[18:21], v[166:169], v[190:193], v[18:21]
	v_mfma_f32_16x16x32_bf16 v[34:37], v[166:169], v[182:185], v[34:37]
	v_mfma_f32_16x16x32_bf16 v[50:53], v[166:169], v[174:177], v[50:53]
	v_mfma_f32_16x16x32_bf16 v[50:53], v[170:173], v[178:181], v[50:53]
	v_mfma_f32_16x16x32_bf16 v[34:37], v[170:173], v[186:189], v[34:37]
	v_mfma_f32_16x16x32_bf16 v[18:21], v[170:173], v[194:197], v[18:21]
	v_mfma_f32_16x16x32_bf16 v[2:5], v[170:173], v[204:207], v[2:5]
	v_mfma_f32_16x16x32_bf16 v[6:9], v[162:165], v[204:207], v[6:9]
	v_mfma_f32_16x16x32_bf16 v[22:25], v[162:165], v[194:197], v[22:25]
	v_mfma_f32_16x16x32_bf16 v[38:41], v[162:165], v[186:189], v[38:41]
	v_mfma_f32_16x16x32_bf16 v[54:57], v[162:165], v[178:181], v[54:57]
	s_setprio 0
	s_barrier
	s_add_i32 s60, s60, 2
	s_add_u32 s26, s26, 0x100
	s_addc_u32 s27, s27, 0
	s_cmpk_gt_u32 s60, 0x55
	s_cbranch_scc0 .LBB0_2172
	s_and_b64 vcc, exec, s[10:11]
	s_cbranch_vccnz .LBB0_2160
	v_mov_b32_e32 v2, 0
	s_mov_b32 s45, s57
	s_mov_b32 s17, s58
	s_mov_b64 s[20:21], s[24:25]
	s_mov_b64 s[22:23], s[12:13]
	s_mov_b32 s56, s59
	v_mov_b32_e32 v3, v2
	v_mov_b32_e32 v4, v2
	v_mov_b32_e32 v5, v2
	v_mov_b32_e32 v6, v2
	v_mov_b32_e32 v7, v2
	v_mov_b32_e32 v8, v2
	v_mov_b32_e32 v9, v2
	v_mov_b32_e32 v18, v2
	v_mov_b32_e32 v19, v2
	v_mov_b32_e32 v20, v2
	v_mov_b32_e32 v21, v2
	v_mov_b32_e32 v22, v2
	v_mov_b32_e32 v23, v2
	v_mov_b32_e32 v24, v2
	v_mov_b32_e32 v25, v2
	v_mov_b32_e32 v34, v2
	v_mov_b32_e32 v35, v2
	v_mov_b32_e32 v36, v2
	v_mov_b32_e32 v37, v2
	v_mov_b32_e32 v38, v2
	v_mov_b32_e32 v39, v2
	v_mov_b32_e32 v40, v2
	v_mov_b32_e32 v41, v2
	v_mov_b32_e32 v50, v2
	v_mov_b32_e32 v51, v2
	v_mov_b32_e32 v52, v2
	v_mov_b32_e32 v53, v2
	v_mov_b32_e32 v54, v2
	v_mov_b32_e32 v55, v2
	v_mov_b32_e32 v56, v2
	v_mov_b32_e32 v57, v2
	v_mov_b32_e32 v10, v2
	v_mov_b32_e32 v11, v2
	v_mov_b32_e32 v12, v2
	v_mov_b32_e32 v13, v2
	v_mov_b32_e32 v14, v2
	v_mov_b32_e32 v15, v2
	v_mov_b32_e32 v16, v2
	v_mov_b32_e32 v17, v2
	v_mov_b32_e32 v26, v2
	v_mov_b32_e32 v27, v2
	v_mov_b32_e32 v28, v2
	v_mov_b32_e32 v29, v2
	v_mov_b32_e32 v30, v2
	v_mov_b32_e32 v31, v2
	v_mov_b32_e32 v32, v2
	v_mov_b32_e32 v33, v2
	v_mov_b32_e32 v42, v2
	v_mov_b32_e32 v43, v2
	v_mov_b32_e32 v44, v2
	v_mov_b32_e32 v45, v2
	v_mov_b32_e32 v46, v2
	v_mov_b32_e32 v47, v2
	v_mov_b32_e32 v48, v2
	v_mov_b32_e32 v49, v2
	v_mov_b32_e32 v58, v2
	v_mov_b32_e32 v59, v2
	v_mov_b32_e32 v60, v2
	v_mov_b32_e32 v61, v2
	v_mov_b32_e32 v62, v2
	v_mov_b32_e32 v63, v2
	v_mov_b32_e32 v64, v2
	v_mov_b32_e32 v65, v2
	v_mov_b32_e32 v66, v2
	v_mov_b32_e32 v67, v2
	v_mov_b32_e32 v68, v2
	v_mov_b32_e32 v69, v2
	v_mov_b32_e32 v70, v2
	v_mov_b32_e32 v71, v2
	v_mov_b32_e32 v72, v2
	v_mov_b32_e32 v73, v2
	v_mov_b32_e32 v82, v2
	v_mov_b32_e32 v83, v2
	v_mov_b32_e32 v84, v2
	v_mov_b32_e32 v85, v2
	v_mov_b32_e32 v86, v2
	v_mov_b32_e32 v87, v2
	v_mov_b32_e32 v88, v2
	v_mov_b32_e32 v89, v2
	v_mov_b32_e32 v98, v2
	v_mov_b32_e32 v99, v2
	v_mov_b32_e32 v100, v2
	v_mov_b32_e32 v101, v2
	v_mov_b32_e32 v102, v2
	v_mov_b32_e32 v103, v2
	v_mov_b32_e32 v104, v2
	v_mov_b32_e32 v105, v2
	v_mov_b32_e32 v114, v2
	v_mov_b32_e32 v115, v2
	v_mov_b32_e32 v116, v2
	v_mov_b32_e32 v117, v2
	v_mov_b32_e32 v118, v2
	v_mov_b32_e32 v119, v2
	v_mov_b32_e32 v120, v2
	v_mov_b32_e32 v121, v2
	v_mov_b32_e32 v74, v2
	v_mov_b32_e32 v75, v2
	v_mov_b32_e32 v76, v2
	v_mov_b32_e32 v77, v2
	v_mov_b32_e32 v78, v2
	v_mov_b32_e32 v79, v2
	v_mov_b32_e32 v80, v2
	v_mov_b32_e32 v81, v2
	v_mov_b32_e32 v90, v2
	v_mov_b32_e32 v91, v2
	v_mov_b32_e32 v92, v2
	v_mov_b32_e32 v93, v2
	v_mov_b32_e32 v94, v2
	v_mov_b32_e32 v95, v2
	v_mov_b32_e32 v96, v2
	v_mov_b32_e32 v97, v2
	v_mov_b32_e32 v106, v2
	v_mov_b32_e32 v107, v2
	v_mov_b32_e32 v108, v2
	v_mov_b32_e32 v109, v2
	v_mov_b32_e32 v110, v2
	v_mov_b32_e32 v111, v2
	v_mov_b32_e32 v112, v2
	v_mov_b32_e32 v113, v2
	v_mov_b32_e32 v122, v2
	v_mov_b32_e32 v123, v2
	v_mov_b32_e32 v124, v2
	v_mov_b32_e32 v125, v2
	v_mov_b32_e32 v126, v2
	v_mov_b32_e32 v127, v2
	v_mov_b32_e32 v128, v2
	v_mov_b32_e32 v129, v2
	s_branch .LBB0_2160
